# GEMM k-loop software-pipelined frag reads; tile-order swizzle (3 GEMMs); transposed MFMA output + dwordx4 epilogue for MLP1; scan waitcnt counted + LDS read batching
# speedup vs baseline: 1.0238x; 1.0238x over previous
.LBB0_223:
	s_waitcnt lgkmcnt(0)
	s_barrier
	ds_read_b128 v[112:115], v206
	ds_read_b128 v[116:119], v206 offset:2048
	ds_read_b128 v[120:123], v206 offset:4096
	ds_read_b128 v[124:127], v206 offset:6144
	ds_read_b128 v[128:131], v207
	ds_read_b128 v[132:135], v207 offset:2048
	ds_read_b128 v[136:139], v207 offset:4096
	ds_read_b128 v[140:143], v207 offset:6144
	s_waitcnt vmcnt(6)
	ds_write_b128 v204, v[0:3] offset:32768
	ds_write_b128 v204, v[4:7] offset:40960
	ds_write_b128 v204, v[8:11] offset:49152
	ds_write_b128 v204, v[12:15] offset:57344
	ds_write_b128 v210, v[32:35]
	ds_write_b128 v210, v[44:47] offset:8192
	s_cmp_gt_u32 s27, 12
	s_mov_b64 s[10:11], -1
	s_cbranch_scc0 .Lmyafe__227
	s_andn2_b64 vcc, exec, s[8:9]
	s_cbranch_vccnz .Lmyafe__226
	global_load_dwordx4 v[4:7], v[182:183], off
	global_load_dwordx4 v[8:11], v[184:185], off
	global_load_dwordx4 v[0:3], v[178:179], off offset:128
	global_load_dwordx4 v[32:35], v[180:181], off offset:128
	global_load_dwordx4 v[12:15], v[186:187], off
	global_load_dwordx4 v[44:47], v[188:189], off

.Lmyafe__227:
	s_andn2_b64 vcc, exec, s[10:11]
	s_cbranch_vccnz .Lmyafe__229
	v_lshl_add_u64 v[8:9], v[200:201], 0, v[176:177]
	v_add_co_u32_e32 v0, vcc, 0x2800000, v8
	v_lshl_add_u64 v[32:33], v[198:199], 0, v[176:177]
	v_addc_co_u32_e32 v1, vcc, 0, v9, vcc
	v_add_co_u32_e32 v4, vcc, 0x2820000, v8
	s_nop 1
	v_addc_co_u32_e32 v5, vcc, 0, v9, vcc
	v_add_co_u32_e32 v10, vcc, 0x2840000, v8
	global_load_dwordx4 v[0:3], v[0:1], off offset:384
	s_nop 0
	global_load_dwordx4 v[4:7], v[4:5], off offset:384
	v_addc_co_u32_e32 v11, vcc, 0, v9, vcc
	v_add_co_u32_e32 v12, vcc, 0x2860000, v8
	s_nop 1
	v_addc_co_u32_e32 v13, vcc, 0, v9, vcc
	v_add_co_u32_e32 v34, vcc, 0x400000, v32
	global_load_dwordx4 v[8:11], v[10:11], off offset:384
	s_nop 0
	global_load_dwordx4 v[12:15], v[12:13], off offset:384
	v_addc_co_u32_e32 v35, vcc, 0, v33, vcc
	v_add_co_u32_e32 v44, vcc, 0x420000, v32
	s_nop 1
	v_addc_co_u32_e32 v45, vcc, 0, v33, vcc
	global_load_dwordx4 v[32:35], v[34:35], off offset:384
	s_nop 0
	global_load_dwordx4 v[44:47], v[44:45], off offset:384
.Lmyafe__229:
	s_waitcnt lgkmcnt(0)
	v_mfma_f32_16x16x32_bf16 v[108:111], v[112:115], v[128:131], v[108:111]
	ds_read_b128 v[144:147], v208
	v_mfma_f32_16x16x32_bf16 v[104:107], v[112:115], v[132:135], v[104:107]
	ds_read_b128 v[148:151], v208 offset:2048
	v_mfma_f32_16x16x32_bf16 v[100:103], v[112:115], v[136:139], v[100:103]
	ds_read_b128 v[152:155], v208 offset:4096
	v_mfma_f32_16x16x32_bf16 v[96:99], v[112:115], v[140:143], v[96:99]
	ds_read_b128 v[156:159], v208 offset:6144
	v_mfma_f32_16x16x32_bf16 v[92:95], v[116:119], v[128:131], v[92:95]
	ds_read_b128 v[160:163], v209
	v_mfma_f32_16x16x32_bf16 v[88:91], v[116:119], v[132:135], v[88:91]
	ds_read_b128 v[164:167], v209 offset:2048
	v_mfma_f32_16x16x32_bf16 v[84:87], v[116:119], v[136:139], v[84:87]
	ds_read_b128 v[228:231], v209 offset:4096
	v_mfma_f32_16x16x32_bf16 v[80:83], v[116:119], v[140:143], v[80:83]
	ds_read_b128 v[232:235], v209 offset:6144
	v_mfma_f32_16x16x32_bf16 v[76:79], v[120:123], v[128:131], v[76:79]
	v_mfma_f32_16x16x32_bf16 v[72:75], v[120:123], v[132:135], v[72:75]
	v_mfma_f32_16x16x32_bf16 v[68:71], v[120:123], v[136:139], v[68:71]
	v_mfma_f32_16x16x32_bf16 v[64:67], v[120:123], v[140:143], v[64:67]
	v_mfma_f32_16x16x32_bf16 v[60:63], v[124:127], v[128:131], v[60:63]
	v_mfma_f32_16x16x32_bf16 v[56:59], v[124:127], v[132:135], v[56:59]
	v_mfma_f32_16x16x32_bf16 v[52:55], v[124:127], v[136:139], v[52:55]
	v_mfma_f32_16x16x32_bf16 v[48:51], v[124:127], v[140:143], v[48:51]
	s_branch .Lmya_odd
.Lmya_even:
	s_waitcnt lgkmcnt(0)
	s_barrier
	ds_read_b128 v[112:115], v206
	ds_read_b128 v[116:119], v206 offset:2048
	ds_read_b128 v[120:123], v206 offset:4096
	ds_read_b128 v[124:127], v206 offset:6144
	ds_read_b128 v[128:131], v207
	ds_read_b128 v[132:135], v207 offset:2048
	ds_read_b128 v[136:139], v207 offset:4096
	ds_read_b128 v[140:143], v207 offset:6144
	s_cmp_gt_u32 s27, 12
	s_cbranch_scc0 .Lmya_ew6
	s_and_b64 vcc, exec, s[8:9]
	s_cbranch_vccnz .Lmya_ew6
	s_waitcnt vmcnt(0)
.Lmya_ew6:
	s_waitcnt vmcnt(6)
	v_mfma_f32_16x16x32_bf16 v[108:111], v[144:147], v[160:163], v[108:111]
	ds_write_b128 v204, v[0:3] offset:32768
	v_mfma_f32_16x16x32_bf16 v[104:107], v[144:147], v[164:167], v[104:107]
	ds_write_b128 v204, v[4:7] offset:40960
	v_mfma_f32_16x16x32_bf16 v[100:103], v[144:147], v[228:231], v[100:103]
	ds_write_b128 v204, v[8:11] offset:49152
	v_mfma_f32_16x16x32_bf16 v[96:99], v[144:147], v[232:235], v[96:99]
	ds_write_b128 v204, v[12:15] offset:57344
	v_mfma_f32_16x16x32_bf16 v[92:95], v[148:151], v[160:163], v[92:95]
	ds_write_b128 v210, v[32:35]
	v_mfma_f32_16x16x32_bf16 v[88:91], v[148:151], v[164:167], v[88:91]
	ds_write_b128 v210, v[44:47] offset:8192
	v_mfma_f32_16x16x32_bf16 v[84:87], v[148:151], v[228:231], v[84:87]
	v_mfma_f32_16x16x32_bf16 v[80:83], v[148:151], v[232:235], v[80:83]
	s_cmp_gt_u32 s27, 12
	s_mov_b64 s[10:11], -1
	s_cbranch_scc0 .Lmyase__227
	s_andn2_b64 vcc, exec, s[8:9]
	s_cbranch_vccnz .Lmyase__226
	global_load_dwordx4 v[4:7], v[182:183], off
	global_load_dwordx4 v[8:11], v[184:185], off
	global_load_dwordx4 v[0:3], v[178:179], off offset:128
	global_load_dwordx4 v[32:35], v[180:181], off offset:128
	global_load_dwordx4 v[12:15], v[186:187], off
	global_load_dwordx4 v[44:47], v[188:189], off

.Lmyase__229:
	v_mfma_f32_16x16x32_bf16 v[76:79], v[152:155], v[160:163], v[76:79]
	v_mfma_f32_16x16x32_bf16 v[72:75], v[152:155], v[164:167], v[72:75]
	v_mfma_f32_16x16x32_bf16 v[68:71], v[152:155], v[228:231], v[68:71]
	v_mfma_f32_16x16x32_bf16 v[64:67], v[152:155], v[232:235], v[64:67]
	v_mfma_f32_16x16x32_bf16 v[60:63], v[156:159], v[160:163], v[60:63]
	v_mfma_f32_16x16x32_bf16 v[56:59], v[156:159], v[164:167], v[56:59]
	v_mfma_f32_16x16x32_bf16 v[52:55], v[156:159], v[228:231], v[52:55]
	v_mfma_f32_16x16x32_bf16 v[48:51], v[156:159], v[232:235], v[48:51]
	s_waitcnt lgkmcnt(0)
	v_mfma_f32_16x16x32_bf16 v[108:111], v[112:115], v[128:131], v[108:111]
	ds_read_b128 v[144:147], v208
	v_mfma_f32_16x16x32_bf16 v[104:107], v[112:115], v[132:135], v[104:107]
	ds_read_b128 v[148:151], v208 offset:2048
	v_mfma_f32_16x16x32_bf16 v[100:103], v[112:115], v[136:139], v[100:103]
	ds_read_b128 v[152:155], v208 offset:4096
	v_mfma_f32_16x16x32_bf16 v[96:99], v[112:115], v[140:143], v[96:99]
	ds_read_b128 v[156:159], v208 offset:6144
	v_mfma_f32_16x16x32_bf16 v[92:95], v[116:119], v[128:131], v[92:95]
	ds_read_b128 v[160:163], v209
	v_mfma_f32_16x16x32_bf16 v[88:91], v[116:119], v[132:135], v[88:91]
	ds_read_b128 v[164:167], v209 offset:2048
	v_mfma_f32_16x16x32_bf16 v[84:87], v[116:119], v[136:139], v[84:87]
	ds_read_b128 v[228:231], v209 offset:4096
	v_mfma_f32_16x16x32_bf16 v[80:83], v[116:119], v[140:143], v[80:83]
	ds_read_b128 v[232:235], v209 offset:6144
	v_mfma_f32_16x16x32_bf16 v[76:79], v[120:123], v[128:131], v[76:79]
	v_mfma_f32_16x16x32_bf16 v[72:75], v[120:123], v[132:135], v[72:75]
	v_mfma_f32_16x16x32_bf16 v[68:71], v[120:123], v[136:139], v[68:71]
	v_mfma_f32_16x16x32_bf16 v[64:67], v[120:123], v[140:143], v[64:67]
	v_mfma_f32_16x16x32_bf16 v[60:63], v[124:127], v[128:131], v[60:63]
	v_mfma_f32_16x16x32_bf16 v[56:59], v[124:127], v[132:135], v[56:59]
	v_mfma_f32_16x16x32_bf16 v[52:55], v[124:127], v[136:139], v[52:55]
	v_mfma_f32_16x16x32_bf16 v[48:51], v[124:127], v[140:143], v[48:51]
.Lmya_odd:
	s_waitcnt lgkmcnt(0)
	s_barrier
	ds_read_b128 v[112:115], v206 offset:32768
	ds_read_b128 v[116:119], v206 offset:34816
	ds_read_b128 v[120:123], v206 offset:36864
	ds_read_b128 v[124:127], v206 offset:38912
	ds_read_b128 v[128:131], v211
	ds_read_b128 v[132:135], v211 offset:2048
	ds_read_b128 v[136:139], v211 offset:4096
	ds_read_b128 v[140:143], v211 offset:6144
	s_cmp_gt_u32 s27, 13
	s_cselect_b64 s[10:11], -1, 0
	s_and_b64 vcc, exec, s[10:11]
	s_cbranch_vccnz .Lmya_oddlast
	s_waitcnt vmcnt(6)
	v_mfma_f32_16x16x32_bf16 v[108:111], v[144:147], v[160:163], v[108:111]
	ds_write_b128 v204, v[16:19]
	v_mfma_f32_16x16x32_bf16 v[104:107], v[144:147], v[164:167], v[104:107]
	ds_write_b128 v204, v[20:23] offset:8192
	v_mfma_f32_16x16x32_bf16 v[100:103], v[144:147], v[228:231], v[100:103]
	ds_write_b128 v204, v[24:27] offset:16384
	v_mfma_f32_16x16x32_bf16 v[96:99], v[144:147], v[232:235], v[96:99]
	ds_write_b128 v204, v[36:39] offset:24576
	v_mfma_f32_16x16x32_bf16 v[92:95], v[148:151], v[160:163], v[92:95]
	ds_write_b128 v205, v[28:31]
	v_mfma_f32_16x16x32_bf16 v[88:91], v[148:151], v[164:167], v[88:91]
	ds_write_b128 v205, v[40:43] offset:8192
	v_mfma_f32_16x16x32_bf16 v[84:87], v[148:151], v[228:231], v[84:87]
	v_mfma_f32_16x16x32_bf16 v[80:83], v[148:151], v[232:235], v[80:83]
	s_cmp_gt_u32 s27, 11
	s_mov_b64 s[12:13], -1
	s_cbranch_scc0 .Lmyaso__234
	s_andn2_b64 vcc, exec, s[8:9]
	s_cbranch_vccnz .Lmyaso__233
	global_load_dwordx4 v[20:23], v[190:191], off
	global_load_dwordx4 v[24:27], v[192:193], off
	global_load_dwordx4 v[16:19], v[178:179], off
	global_load_dwordx4 v[28:31], v[180:181], off
	global_load_dwordx4 v[36:39], v[194:195], off
	global_load_dwordx4 v[40:43], v[196:197], off

.Lmyaso__234:
	s_andn2_b64 vcc, exec, s[12:13]
	s_cbranch_vccnz .Lmya_ocont
	v_lshl_add_u64 v[24:25], v[200:201], 0, v[176:177]
	v_add_co_u32_e32 v16, vcc, 0x2800000, v24
	v_lshl_add_u64 v[28:29], v[198:199], 0, v[176:177]
	v_addc_co_u32_e32 v17, vcc, 0, v25, vcc
	v_add_co_u32_e32 v20, vcc, 0x2820000, v24
	s_nop 1
	v_addc_co_u32_e32 v21, vcc, 0, v25, vcc
	v_add_co_u32_e32 v26, vcc, 0x2840000, v24
	global_load_dwordx4 v[16:19], v[16:17], off offset:512
	s_nop 0
	global_load_dwordx4 v[20:23], v[20:21], off offset:512
	v_addc_co_u32_e32 v27, vcc, 0, v25, vcc
	v_add_co_u32_e32 v30, vcc, 0x2860000, v24
	s_nop 1
	v_addc_co_u32_e32 v31, vcc, 0, v25, vcc
	global_load_dwordx4 v[24:27], v[26:27], off offset:512
	s_nop 0
	global_load_dwordx4 v[36:39], v[30:31], off offset:512
	v_add_co_u32_e32 v30, vcc, 0x400000, v28
	s_nop 1
	v_addc_co_u32_e32 v31, vcc, 0, v29, vcc
	v_add_co_u32_e32 v40, vcc, 0x420000, v28
	s_nop 1
	v_addc_co_u32_e32 v41, vcc, 0, v29, vcc
	global_load_dwordx4 v[28:31], v[30:31], off offset:512
	s_nop 0
	global_load_dwordx4 v[40:43], v[40:41], off offset:512
.Lmya_ocont:
	v_mfma_f32_16x16x32_bf16 v[76:79], v[152:155], v[160:163], v[76:79]
	v_mfma_f32_16x16x32_bf16 v[72:75], v[152:155], v[164:167], v[72:75]
	v_mfma_f32_16x16x32_bf16 v[68:71], v[152:155], v[228:231], v[68:71]
	v_mfma_f32_16x16x32_bf16 v[64:67], v[152:155], v[232:235], v[64:67]
	v_mfma_f32_16x16x32_bf16 v[60:63], v[156:159], v[160:163], v[60:63]
	v_mfma_f32_16x16x32_bf16 v[56:59], v[156:159], v[164:167], v[56:59]
	v_mfma_f32_16x16x32_bf16 v[52:55], v[156:159], v[228:231], v[52:55]
	v_mfma_f32_16x16x32_bf16 v[48:51], v[156:159], v[232:235], v[48:51]
	s_waitcnt lgkmcnt(0)
	v_mfma_f32_16x16x32_bf16 v[108:111], v[112:115], v[128:131], v[108:111]
	ds_read_b128 v[144:147], v208 offset:32768
	v_mfma_f32_16x16x32_bf16 v[104:107], v[112:115], v[132:135], v[104:107]
	ds_read_b128 v[148:151], v208 offset:34816
	v_mfma_f32_16x16x32_bf16 v[100:103], v[112:115], v[136:139], v[100:103]
	ds_read_b128 v[152:155], v208 offset:36864
	v_mfma_f32_16x16x32_bf16 v[96:99], v[112:115], v[140:143], v[96:99]
	ds_read_b128 v[156:159], v208 offset:38912
	v_mfma_f32_16x16x32_bf16 v[92:95], v[116:119], v[128:131], v[92:95]
	ds_read_b128 v[160:163], v212
	v_mfma_f32_16x16x32_bf16 v[88:91], v[116:119], v[132:135], v[88:91]
	ds_read_b128 v[164:167], v212 offset:2048
	v_mfma_f32_16x16x32_bf16 v[84:87], v[116:119], v[136:139], v[84:87]
	ds_read_b128 v[228:231], v212 offset:4096
	v_mfma_f32_16x16x32_bf16 v[80:83], v[116:119], v[140:143], v[80:83]
	ds_read_b128 v[232:235], v212 offset:6144
	v_mfma_f32_16x16x32_bf16 v[76:79], v[120:123], v[128:131], v[76:79]
	v_mfma_f32_16x16x32_bf16 v[72:75], v[120:123], v[132:135], v[72:75]
	v_mfma_f32_16x16x32_bf16 v[68:71], v[120:123], v[136:139], v[68:71]
	v_mfma_f32_16x16x32_bf16 v[64:67], v[120:123], v[140:143], v[64:67]
	v_mfma_f32_16x16x32_bf16 v[60:63], v[124:127], v[128:131], v[60:63]
	v_mfma_f32_16x16x32_bf16 v[56:59], v[124:127], v[132:135], v[56:59]
	v_mfma_f32_16x16x32_bf16 v[52:55], v[124:127], v[136:139], v[52:55]
	v_mfma_f32_16x16x32_bf16 v[48:51], v[124:127], v[140:143], v[48:51]
	s_add_i32 s27, s27, 2
	v_lshl_add_u64 v[198:199], v[198:199], 0, s[4:5]
	v_lshl_add_u64 v[200:201], v[200:201], 0, s[4:5]
	s_branch .Lmya_even
.Lmya_oddlast:
	v_mfma_f32_16x16x32_bf16 v[108:111], v[144:147], v[160:163], v[108:111]
	v_mfma_f32_16x16x32_bf16 v[104:107], v[144:147], v[164:167], v[104:107]
	v_mfma_f32_16x16x32_bf16 v[100:103], v[144:147], v[228:231], v[100:103]
	v_mfma_f32_16x16x32_bf16 v[96:99], v[144:147], v[232:235], v[96:99]
	v_mfma_f32_16x16x32_bf16 v[92:95], v[148:151], v[160:163], v[92:95]
	v_mfma_f32_16x16x32_bf16 v[88:91], v[148:151], v[164:167], v[88:91]
	v_mfma_f32_16x16x32_bf16 v[84:87], v[148:151], v[228:231], v[84:87]
	v_mfma_f32_16x16x32_bf16 v[80:83], v[148:151], v[232:235], v[80:83]
	v_mfma_f32_16x16x32_bf16 v[76:79], v[152:155], v[160:163], v[76:79]
	v_mfma_f32_16x16x32_bf16 v[72:75], v[152:155], v[164:167], v[72:75]
	v_mfma_f32_16x16x32_bf16 v[68:71], v[152:155], v[228:231], v[68:71]
	v_mfma_f32_16x16x32_bf16 v[64:67], v[152:155], v[232:235], v[64:67]
	v_mfma_f32_16x16x32_bf16 v[60:63], v[156:159], v[160:163], v[60:63]
	v_mfma_f32_16x16x32_bf16 v[56:59], v[156:159], v[164:167], v[56:59]
	v_mfma_f32_16x16x32_bf16 v[52:55], v[156:159], v[228:231], v[52:55]
	v_mfma_f32_16x16x32_bf16 v[48:51], v[156:159], v[232:235], v[48:51]
	s_waitcnt lgkmcnt(0)
	v_mfma_f32_16x16x32_bf16 v[108:111], v[112:115], v[128:131], v[108:111]
	ds_read_b128 v[144:147], v208 offset:32768
	v_mfma_f32_16x16x32_bf16 v[104:107], v[112:115], v[132:135], v[104:107]
	ds_read_b128 v[148:151], v208 offset:34816
	v_mfma_f32_16x16x32_bf16 v[100:103], v[112:115], v[136:139], v[100:103]
	ds_read_b128 v[152:155], v208 offset:36864
	v_mfma_f32_16x16x32_bf16 v[96:99], v[112:115], v[140:143], v[96:99]
	ds_read_b128 v[156:159], v208 offset:38912
	v_mfma_f32_16x16x32_bf16 v[92:95], v[116:119], v[128:131], v[92:95]
	ds_read_b128 v[160:163], v212
	v_mfma_f32_16x16x32_bf16 v[88:91], v[116:119], v[132:135], v[88:91]
	ds_read_b128 v[164:167], v212 offset:2048
	v_mfma_f32_16x16x32_bf16 v[84:87], v[116:119], v[136:139], v[84:87]
	ds_read_b128 v[228:231], v212 offset:4096
	v_mfma_f32_16x16x32_bf16 v[80:83], v[116:119], v[140:143], v[80:83]
	ds_read_b128 v[232:235], v212 offset:6144
	v_mfma_f32_16x16x32_bf16 v[76:79], v[120:123], v[128:131], v[76:79]
	v_mfma_f32_16x16x32_bf16 v[72:75], v[120:123], v[132:135], v[72:75]
	v_mfma_f32_16x16x32_bf16 v[68:71], v[120:123], v[136:139], v[68:71]
	v_mfma_f32_16x16x32_bf16 v[64:67], v[120:123], v[140:143], v[64:67]
	v_mfma_f32_16x16x32_bf16 v[60:63], v[124:127], v[128:131], v[60:63]
	v_mfma_f32_16x16x32_bf16 v[56:59], v[124:127], v[132:135], v[56:59]
	v_mfma_f32_16x16x32_bf16 v[52:55], v[124:127], v[136:139], v[52:55]
	v_mfma_f32_16x16x32_bf16 v[48:51], v[124:127], v[140:143], v[48:51]
	s_add_i32 s27, s27, 2
	v_lshl_add_u64 v[198:199], v[198:199], 0, s[4:5]
	v_lshl_add_u64 v[200:201], v[200:201], 0, s[4:5]
	s_waitcnt lgkmcnt(0)
	v_mfma_f32_16x16x32_bf16 v[108:111], v[144:147], v[160:163], v[108:111]
	v_mfma_f32_16x16x32_bf16 v[104:107], v[144:147], v[164:167], v[104:107]
	v_mfma_f32_16x16x32_bf16 v[100:103], v[144:147], v[228:231], v[100:103]
	v_mfma_f32_16x16x32_bf16 v[96:99], v[144:147], v[232:235], v[96:99]
	v_mfma_f32_16x16x32_bf16 v[92:95], v[148:151], v[160:163], v[92:95]
	v_mfma_f32_16x16x32_bf16 v[88:91], v[148:151], v[164:167], v[88:91]
	v_mfma_f32_16x16x32_bf16 v[84:87], v[148:151], v[228:231], v[84:87]
	v_mfma_f32_16x16x32_bf16 v[80:83], v[148:151], v[232:235], v[80:83]
	v_mfma_f32_16x16x32_bf16 v[76:79], v[152:155], v[160:163], v[76:79]
	v_mfma_f32_16x16x32_bf16 v[72:75], v[152:155], v[164:167], v[72:75]
	v_mfma_f32_16x16x32_bf16 v[68:71], v[152:155], v[228:231], v[68:71]
	v_mfma_f32_16x16x32_bf16 v[64:67], v[152:155], v[232:235], v[64:67]
	v_mfma_f32_16x16x32_bf16 v[60:63], v[156:159], v[160:163], v[60:63]
	v_mfma_f32_16x16x32_bf16 v[56:59], v[156:159], v[164:167], v[56:59]
	v_mfma_f32_16x16x32_bf16 v[52:55], v[156:159], v[228:231], v[52:55]
	v_mfma_f32_16x16x32_bf16 v[48:51], v[156:159], v[232:235], v[48:51]
	s_and_b64 vcc, exec, s[10:11]
	s_nop 7
	s_branch .LBB0_236

.LBB0_633:
	s_waitcnt lgkmcnt(0)
	s_barrier
	ds_read_b128 v[112:115], v206
	ds_read_b128 v[116:119], v206 offset:2048
	ds_read_b128 v[120:123], v206 offset:4096
	ds_read_b128 v[124:127], v206 offset:6144
	ds_read_b128 v[128:131], v207
	ds_read_b128 v[132:135], v207 offset:2048
	ds_read_b128 v[136:139], v207 offset:4096
	ds_read_b128 v[140:143], v207 offset:6144
	s_waitcnt vmcnt(6)
	ds_write_b128 v204, v[0:3] offset:32768
	ds_write_b128 v204, v[4:7] offset:40960
	ds_write_b128 v204, v[8:11] offset:49152
	ds_write_b128 v204, v[12:15] offset:57344
	ds_write_b128 v210, v[16:19]
	ds_write_b128 v210, v[24:27] offset:8192
	s_cmp_gt_u32 s47, 12
	s_mov_b64 s[14:15], -1
	s_cbranch_scc0 .Lmybfe__637
	s_andn2_b64 vcc, exec, s[12:13]
	s_cbranch_vccnz .Lmybfe__636
	global_load_dwordx4 v[4:7], v[186:187], off
	global_load_dwordx4 v[8:11], v[188:189], off
	global_load_dwordx4 v[0:3], v[182:183], off offset:128
	global_load_dwordx4 v[16:19], v[184:185], off offset:128
	global_load_dwordx4 v[12:15], v[190:191], off
	global_load_dwordx4 v[24:27], v[192:193], off

.Lmybfe__637:
	s_andn2_b64 vcc, exec, s[14:15]
	s_cbranch_vccnz .Lmybfe__639
	v_lshl_add_u64 v[8:9], v[180:181], 0, v[176:177]
	v_add_co_u32_e32 v0, vcc, 0xac00000, v8
	v_lshl_add_u64 v[16:17], v[178:179], 0, v[176:177]
	v_addc_co_u32_e32 v1, vcc, 0, v9, vcc
	v_add_co_u32_e32 v4, vcc, 0xac20000, v8
	s_nop 1
	v_addc_co_u32_e32 v5, vcc, 0, v9, vcc
	v_add_co_u32_e32 v10, vcc, 0xac40000, v8
	global_load_dwordx4 v[0:3], v[0:1], off offset:384
	s_nop 0
	global_load_dwordx4 v[4:7], v[4:5], off offset:384
	v_addc_co_u32_e32 v11, vcc, 0, v9, vcc
	v_add_co_u32_e32 v12, vcc, 0xac60000, v8
	s_nop 1
	v_addc_co_u32_e32 v13, vcc, 0, v9, vcc
	v_add_co_u32_e32 v18, vcc, 0x880000, v16
	global_load_dwordx4 v[8:11], v[10:11], off offset:384
	s_nop 0
	global_load_dwordx4 v[12:15], v[12:13], off offset:384
	v_addc_co_u32_e32 v19, vcc, 0, v17, vcc
	v_add_co_u32_e32 v24, vcc, 0x8a0000, v16
	s_nop 1
	v_addc_co_u32_e32 v25, vcc, 0, v17, vcc
	global_load_dwordx4 v[16:19], v[18:19], off offset:384
	s_nop 0
	global_load_dwordx4 v[24:27], v[24:25], off offset:384
.Lmybfe__639:
	s_waitcnt lgkmcnt(0)
	v_mfma_f32_16x16x32_bf16 v[108:111], v[112:115], v[128:131], v[108:111]
	ds_read_b128 v[144:147], v208
	v_mfma_f32_16x16x32_bf16 v[104:107], v[112:115], v[132:135], v[104:107]
	ds_read_b128 v[148:151], v208 offset:2048
	v_mfma_f32_16x16x32_bf16 v[100:103], v[112:115], v[136:139], v[100:103]
	ds_read_b128 v[152:155], v208 offset:4096
	v_mfma_f32_16x16x32_bf16 v[96:99], v[112:115], v[140:143], v[96:99]
	ds_read_b128 v[156:159], v208 offset:6144
	v_mfma_f32_16x16x32_bf16 v[92:95], v[116:119], v[128:131], v[92:95]
	ds_read_b128 v[160:163], v209
	v_mfma_f32_16x16x32_bf16 v[88:91], v[116:119], v[132:135], v[88:91]
	ds_read_b128 v[164:167], v209 offset:2048
	v_mfma_f32_16x16x32_bf16 v[84:87], v[116:119], v[136:139], v[84:87]
	ds_read_b128 v[216:219], v209 offset:4096
	v_mfma_f32_16x16x32_bf16 v[80:83], v[116:119], v[140:143], v[80:83]
	ds_read_b128 v[228:231], v209 offset:6144
	v_mfma_f32_16x16x32_bf16 v[76:79], v[120:123], v[128:131], v[76:79]
	v_mfma_f32_16x16x32_bf16 v[72:75], v[120:123], v[132:135], v[72:75]
	v_mfma_f32_16x16x32_bf16 v[68:71], v[120:123], v[136:139], v[68:71]
	v_mfma_f32_16x16x32_bf16 v[64:67], v[120:123], v[140:143], v[64:67]
	v_mfma_f32_16x16x32_bf16 v[60:63], v[124:127], v[128:131], v[60:63]
	v_mfma_f32_16x16x32_bf16 v[56:59], v[124:127], v[132:135], v[56:59]
	v_mfma_f32_16x16x32_bf16 v[52:55], v[124:127], v[136:139], v[52:55]
	v_mfma_f32_16x16x32_bf16 v[48:51], v[124:127], v[140:143], v[48:51]
	s_branch .Lmyb_odd
.Lmyb_even:
	s_waitcnt lgkmcnt(0)
	s_barrier
	ds_read_b128 v[112:115], v206
	ds_read_b128 v[116:119], v206 offset:2048
	ds_read_b128 v[120:123], v206 offset:4096
	ds_read_b128 v[124:127], v206 offset:6144
	ds_read_b128 v[128:131], v207
	ds_read_b128 v[132:135], v207 offset:2048
	ds_read_b128 v[136:139], v207 offset:4096
	ds_read_b128 v[140:143], v207 offset:6144
	s_cmp_gt_u32 s47, 12
	s_cbranch_scc0 .Lmyb_ew6
	s_and_b64 vcc, exec, s[12:13]
	s_cbranch_vccnz .Lmyb_ew6
	s_waitcnt vmcnt(0)
.Lmyb_ew6:
	s_waitcnt vmcnt(6)
	v_mfma_f32_16x16x32_bf16 v[108:111], v[144:147], v[160:163], v[108:111]
	ds_write_b128 v204, v[0:3] offset:32768
	v_mfma_f32_16x16x32_bf16 v[104:107], v[144:147], v[164:167], v[104:107]
	ds_write_b128 v204, v[4:7] offset:40960
	v_mfma_f32_16x16x32_bf16 v[100:103], v[144:147], v[216:219], v[100:103]
	ds_write_b128 v204, v[8:11] offset:49152
	v_mfma_f32_16x16x32_bf16 v[96:99], v[144:147], v[228:231], v[96:99]
	ds_write_b128 v204, v[12:15] offset:57344
	v_mfma_f32_16x16x32_bf16 v[92:95], v[148:151], v[160:163], v[92:95]
	ds_write_b128 v210, v[16:19]
	v_mfma_f32_16x16x32_bf16 v[88:91], v[148:151], v[164:167], v[88:91]
	ds_write_b128 v210, v[24:27] offset:8192
	v_mfma_f32_16x16x32_bf16 v[84:87], v[148:151], v[216:219], v[84:87]
	v_mfma_f32_16x16x32_bf16 v[80:83], v[148:151], v[228:231], v[80:83]
	s_cmp_gt_u32 s47, 12
	s_mov_b64 s[14:15], -1
	s_cbranch_scc0 .Lmybse__637
	s_andn2_b64 vcc, exec, s[12:13]
	s_cbranch_vccnz .Lmybse__636
	global_load_dwordx4 v[4:7], v[186:187], off
	global_load_dwordx4 v[8:11], v[188:189], off
	global_load_dwordx4 v[0:3], v[182:183], off offset:128
	global_load_dwordx4 v[16:19], v[184:185], off offset:128
	global_load_dwordx4 v[12:15], v[190:191], off
	global_load_dwordx4 v[24:27], v[192:193], off

.Lmybse__639:
	v_mfma_f32_16x16x32_bf16 v[76:79], v[152:155], v[160:163], v[76:79]
	v_mfma_f32_16x16x32_bf16 v[72:75], v[152:155], v[164:167], v[72:75]
	v_mfma_f32_16x16x32_bf16 v[68:71], v[152:155], v[216:219], v[68:71]
	v_mfma_f32_16x16x32_bf16 v[64:67], v[152:155], v[228:231], v[64:67]
	v_mfma_f32_16x16x32_bf16 v[60:63], v[156:159], v[160:163], v[60:63]
	v_mfma_f32_16x16x32_bf16 v[56:59], v[156:159], v[164:167], v[56:59]
	v_mfma_f32_16x16x32_bf16 v[52:55], v[156:159], v[216:219], v[52:55]
	v_mfma_f32_16x16x32_bf16 v[48:51], v[156:159], v[228:231], v[48:51]
	s_waitcnt lgkmcnt(0)
	v_mfma_f32_16x16x32_bf16 v[108:111], v[112:115], v[128:131], v[108:111]
	ds_read_b128 v[144:147], v208
	v_mfma_f32_16x16x32_bf16 v[104:107], v[112:115], v[132:135], v[104:107]
	ds_read_b128 v[148:151], v208 offset:2048
	v_mfma_f32_16x16x32_bf16 v[100:103], v[112:115], v[136:139], v[100:103]
	ds_read_b128 v[152:155], v208 offset:4096
	v_mfma_f32_16x16x32_bf16 v[96:99], v[112:115], v[140:143], v[96:99]
	ds_read_b128 v[156:159], v208 offset:6144
	v_mfma_f32_16x16x32_bf16 v[92:95], v[116:119], v[128:131], v[92:95]
	ds_read_b128 v[160:163], v209
	v_mfma_f32_16x16x32_bf16 v[88:91], v[116:119], v[132:135], v[88:91]
	ds_read_b128 v[164:167], v209 offset:2048
	v_mfma_f32_16x16x32_bf16 v[84:87], v[116:119], v[136:139], v[84:87]
	ds_read_b128 v[216:219], v209 offset:4096
	v_mfma_f32_16x16x32_bf16 v[80:83], v[116:119], v[140:143], v[80:83]
	ds_read_b128 v[228:231], v209 offset:6144
	v_mfma_f32_16x16x32_bf16 v[76:79], v[120:123], v[128:131], v[76:79]
	v_mfma_f32_16x16x32_bf16 v[72:75], v[120:123], v[132:135], v[72:75]
	v_mfma_f32_16x16x32_bf16 v[68:71], v[120:123], v[136:139], v[68:71]
	v_mfma_f32_16x16x32_bf16 v[64:67], v[120:123], v[140:143], v[64:67]
	v_mfma_f32_16x16x32_bf16 v[60:63], v[124:127], v[128:131], v[60:63]
	v_mfma_f32_16x16x32_bf16 v[56:59], v[124:127], v[132:135], v[56:59]
	v_mfma_f32_16x16x32_bf16 v[52:55], v[124:127], v[136:139], v[52:55]
	v_mfma_f32_16x16x32_bf16 v[48:51], v[124:127], v[140:143], v[48:51]
.Lmyb_odd:
	s_waitcnt lgkmcnt(0)
	s_barrier
	ds_read_b128 v[112:115], v206 offset:32768
	ds_read_b128 v[116:119], v206 offset:34816
	ds_read_b128 v[120:123], v206 offset:36864
	ds_read_b128 v[124:127], v206 offset:38912
	ds_read_b128 v[128:131], v211
	ds_read_b128 v[132:135], v211 offset:2048
	ds_read_b128 v[136:139], v211 offset:4096
	ds_read_b128 v[140:143], v211 offset:6144
	s_cmp_gt_u32 s47, 13
	s_cselect_b64 s[14:15], -1, 0
	s_and_b64 vcc, exec, s[14:15]
	s_cbranch_vccnz .Lmyb_oddlast
	s_waitcnt vmcnt(6)
	v_mfma_f32_16x16x32_bf16 v[108:111], v[144:147], v[160:163], v[108:111]
	ds_write_b128 v204, v[36:39]
	v_mfma_f32_16x16x32_bf16 v[104:107], v[144:147], v[164:167], v[104:107]
	ds_write_b128 v204, v[44:47] offset:8192
	v_mfma_f32_16x16x32_bf16 v[100:103], v[144:147], v[216:219], v[100:103]
	ds_write_b128 v204, v[32:35] offset:16384
	v_mfma_f32_16x16x32_bf16 v[96:99], v[144:147], v[228:231], v[96:99]
	ds_write_b128 v204, v[40:43] offset:24576
	v_mfma_f32_16x16x32_bf16 v[92:95], v[148:151], v[160:163], v[92:95]
	ds_write_b128 v205, v[20:23]
	v_mfma_f32_16x16x32_bf16 v[88:91], v[148:151], v[164:167], v[88:91]
	ds_write_b128 v205, v[28:31] offset:8192
	v_mfma_f32_16x16x32_bf16 v[84:87], v[148:151], v[216:219], v[84:87]
	v_mfma_f32_16x16x32_bf16 v[80:83], v[148:151], v[228:231], v[80:83]
	s_cmp_gt_u32 s47, 11
	s_mov_b64 s[16:17], -1
	s_cbranch_scc0 .Lmybso__644
	s_andn2_b64 vcc, exec, s[12:13]
	s_cbranch_vccnz .Lmybso__643
	global_load_dwordx4 v[44:47], v[194:195], off
	global_load_dwordx4 v[32:35], v[196:197], off
	global_load_dwordx4 v[36:39], v[182:183], off
	global_load_dwordx4 v[20:23], v[184:185], off
	global_load_dwordx4 v[40:43], v[198:199], off
	global_load_dwordx4 v[28:31], v[200:201], off

.Lmybso__644:
	s_andn2_b64 vcc, exec, s[16:17]
	s_cbranch_vccnz .Lmyb_ocont
	v_lshl_add_u64 v[20:21], v[180:181], 0, v[176:177]
	v_add_co_u32_e32 v28, vcc, 0xac00000, v20
	v_lshl_add_u64 v[22:23], v[178:179], 0, v[176:177]
	s_nop 0
	v_addc_co_u32_e32 v29, vcc, 0, v21, vcc
	v_add_co_u32_e32 v30, vcc, 0xac20000, v20
	s_nop 1
	v_addc_co_u32_e32 v31, vcc, 0, v21, vcc
	global_load_dwordx4 v[36:39], v[28:29], off offset:512
	global_load_dwordx4 v[44:47], v[30:31], off offset:512
	v_add_co_u32_e32 v28, vcc, 0xac40000, v20
	s_nop 1
	v_addc_co_u32_e32 v29, vcc, 0, v21, vcc
	v_add_co_u32_e32 v20, vcc, 0xac60000, v20
	s_nop 1
	v_addc_co_u32_e32 v21, vcc, 0, v21, vcc
	global_load_dwordx4 v[32:35], v[28:29], off offset:512
	global_load_dwordx4 v[40:43], v[20:21], off offset:512
	v_add_co_u32_e32 v20, vcc, 0x880000, v22
	s_nop 1
	v_addc_co_u32_e32 v21, vcc, 0, v23, vcc
	v_add_co_u32_e32 v28, vcc, 0x8a0000, v22
	s_nop 1
	v_addc_co_u32_e32 v29, vcc, 0, v23, vcc
	global_load_dwordx4 v[20:23], v[20:21], off offset:512
	s_nop 0
	global_load_dwordx4 v[28:31], v[28:29], off offset:512
.Lmyb_ocont:
	v_mfma_f32_16x16x32_bf16 v[76:79], v[152:155], v[160:163], v[76:79]
	v_mfma_f32_16x16x32_bf16 v[72:75], v[152:155], v[164:167], v[72:75]
	v_mfma_f32_16x16x32_bf16 v[68:71], v[152:155], v[216:219], v[68:71]
	v_mfma_f32_16x16x32_bf16 v[64:67], v[152:155], v[228:231], v[64:67]
	v_mfma_f32_16x16x32_bf16 v[60:63], v[156:159], v[160:163], v[60:63]
	v_mfma_f32_16x16x32_bf16 v[56:59], v[156:159], v[164:167], v[56:59]
	v_mfma_f32_16x16x32_bf16 v[52:55], v[156:159], v[216:219], v[52:55]
	v_mfma_f32_16x16x32_bf16 v[48:51], v[156:159], v[228:231], v[48:51]
	s_waitcnt lgkmcnt(0)
	v_mfma_f32_16x16x32_bf16 v[108:111], v[112:115], v[128:131], v[108:111]
	ds_read_b128 v[144:147], v208 offset:32768
	v_mfma_f32_16x16x32_bf16 v[104:107], v[112:115], v[132:135], v[104:107]
	ds_read_b128 v[148:151], v208 offset:34816
	v_mfma_f32_16x16x32_bf16 v[100:103], v[112:115], v[136:139], v[100:103]
	ds_read_b128 v[152:155], v208 offset:36864
	v_mfma_f32_16x16x32_bf16 v[96:99], v[112:115], v[140:143], v[96:99]
	ds_read_b128 v[156:159], v208 offset:38912
	v_mfma_f32_16x16x32_bf16 v[92:95], v[116:119], v[128:131], v[92:95]
	ds_read_b128 v[160:163], v212
	v_mfma_f32_16x16x32_bf16 v[88:91], v[116:119], v[132:135], v[88:91]
	ds_read_b128 v[164:167], v212 offset:2048
	v_mfma_f32_16x16x32_bf16 v[84:87], v[116:119], v[136:139], v[84:87]
	ds_read_b128 v[216:219], v212 offset:4096
	v_mfma_f32_16x16x32_bf16 v[80:83], v[116:119], v[140:143], v[80:83]
	ds_read_b128 v[228:231], v212 offset:6144
	v_mfma_f32_16x16x32_bf16 v[76:79], v[120:123], v[128:131], v[76:79]
	v_mfma_f32_16x16x32_bf16 v[72:75], v[120:123], v[132:135], v[72:75]
	v_mfma_f32_16x16x32_bf16 v[68:71], v[120:123], v[136:139], v[68:71]
	v_mfma_f32_16x16x32_bf16 v[64:67], v[120:123], v[140:143], v[64:67]
	v_mfma_f32_16x16x32_bf16 v[60:63], v[124:127], v[128:131], v[60:63]
	v_mfma_f32_16x16x32_bf16 v[56:59], v[124:127], v[132:135], v[56:59]
	v_mfma_f32_16x16x32_bf16 v[52:55], v[124:127], v[136:139], v[52:55]
	v_mfma_f32_16x16x32_bf16 v[48:51], v[124:127], v[140:143], v[48:51]
	s_add_i32 s47, s47, 2
	v_lshl_add_u64 v[178:179], v[178:179], 0, s[8:9]
	v_lshl_add_u64 v[180:181], v[180:181], 0, s[8:9]
	s_branch .Lmyb_even
.Lmyb_oddlast:
	v_mfma_f32_16x16x32_bf16 v[108:111], v[144:147], v[160:163], v[108:111]
	v_mfma_f32_16x16x32_bf16 v[104:107], v[144:147], v[164:167], v[104:107]
	v_mfma_f32_16x16x32_bf16 v[100:103], v[144:147], v[216:219], v[100:103]
	v_mfma_f32_16x16x32_bf16 v[96:99], v[144:147], v[228:231], v[96:99]
	v_mfma_f32_16x16x32_bf16 v[92:95], v[148:151], v[160:163], v[92:95]
	v_mfma_f32_16x16x32_bf16 v[88:91], v[148:151], v[164:167], v[88:91]
	v_mfma_f32_16x16x32_bf16 v[84:87], v[148:151], v[216:219], v[84:87]
	v_mfma_f32_16x16x32_bf16 v[80:83], v[148:151], v[228:231], v[80:83]
	v_mfma_f32_16x16x32_bf16 v[76:79], v[152:155], v[160:163], v[76:79]
	v_mfma_f32_16x16x32_bf16 v[72:75], v[152:155], v[164:167], v[72:75]
	v_mfma_f32_16x16x32_bf16 v[68:71], v[152:155], v[216:219], v[68:71]
	v_mfma_f32_16x16x32_bf16 v[64:67], v[152:155], v[228:231], v[64:67]
	v_mfma_f32_16x16x32_bf16 v[60:63], v[156:159], v[160:163], v[60:63]
	v_mfma_f32_16x16x32_bf16 v[56:59], v[156:159], v[164:167], v[56:59]
	v_mfma_f32_16x16x32_bf16 v[52:55], v[156:159], v[216:219], v[52:55]
	v_mfma_f32_16x16x32_bf16 v[48:51], v[156:159], v[228:231], v[48:51]
	s_waitcnt lgkmcnt(0)
	v_mfma_f32_16x16x32_bf16 v[108:111], v[112:115], v[128:131], v[108:111]
	ds_read_b128 v[144:147], v208 offset:32768
	v_mfma_f32_16x16x32_bf16 v[104:107], v[112:115], v[132:135], v[104:107]
	ds_read_b128 v[148:151], v208 offset:34816
	v_mfma_f32_16x16x32_bf16 v[100:103], v[112:115], v[136:139], v[100:103]
	ds_read_b128 v[152:155], v208 offset:36864
	v_mfma_f32_16x16x32_bf16 v[96:99], v[112:115], v[140:143], v[96:99]
	ds_read_b128 v[156:159], v208 offset:38912
	v_mfma_f32_16x16x32_bf16 v[92:95], v[116:119], v[128:131], v[92:95]
	ds_read_b128 v[160:163], v212
	v_mfma_f32_16x16x32_bf16 v[88:91], v[116:119], v[132:135], v[88:91]
	ds_read_b128 v[164:167], v212 offset:2048
	v_mfma_f32_16x16x32_bf16 v[84:87], v[116:119], v[136:139], v[84:87]
	ds_read_b128 v[216:219], v212 offset:4096
	v_mfma_f32_16x16x32_bf16 v[80:83], v[116:119], v[140:143], v[80:83]
	ds_read_b128 v[228:231], v212 offset:6144
	v_mfma_f32_16x16x32_bf16 v[76:79], v[120:123], v[128:131], v[76:79]
	v_mfma_f32_16x16x32_bf16 v[72:75], v[120:123], v[132:135], v[72:75]
	v_mfma_f32_16x16x32_bf16 v[68:71], v[120:123], v[136:139], v[68:71]
	v_mfma_f32_16x16x32_bf16 v[64:67], v[120:123], v[140:143], v[64:67]
	v_mfma_f32_16x16x32_bf16 v[60:63], v[124:127], v[128:131], v[60:63]
	v_mfma_f32_16x16x32_bf16 v[56:59], v[124:127], v[132:135], v[56:59]
	v_mfma_f32_16x16x32_bf16 v[52:55], v[124:127], v[136:139], v[52:55]
	v_mfma_f32_16x16x32_bf16 v[48:51], v[124:127], v[140:143], v[48:51]
	s_add_i32 s47, s47, 2
	v_lshl_add_u64 v[178:179], v[178:179], 0, s[8:9]
	v_lshl_add_u64 v[180:181], v[180:181], 0, s[8:9]
	s_waitcnt lgkmcnt(0)
	v_mfma_f32_16x16x32_bf16 v[108:111], v[144:147], v[160:163], v[108:111]
	v_mfma_f32_16x16x32_bf16 v[104:107], v[144:147], v[164:167], v[104:107]
	v_mfma_f32_16x16x32_bf16 v[100:103], v[144:147], v[216:219], v[100:103]
	v_mfma_f32_16x16x32_bf16 v[96:99], v[144:147], v[228:231], v[96:99]
	v_mfma_f32_16x16x32_bf16 v[92:95], v[148:151], v[160:163], v[92:95]
	v_mfma_f32_16x16x32_bf16 v[88:91], v[148:151], v[164:167], v[88:91]
	v_mfma_f32_16x16x32_bf16 v[84:87], v[148:151], v[216:219], v[84:87]
	v_mfma_f32_16x16x32_bf16 v[80:83], v[148:151], v[228:231], v[80:83]
	v_mfma_f32_16x16x32_bf16 v[76:79], v[152:155], v[160:163], v[76:79]
	v_mfma_f32_16x16x32_bf16 v[72:75], v[152:155], v[164:167], v[72:75]
	v_mfma_f32_16x16x32_bf16 v[68:71], v[152:155], v[216:219], v[68:71]
	v_mfma_f32_16x16x32_bf16 v[64:67], v[152:155], v[228:231], v[64:67]
	v_mfma_f32_16x16x32_bf16 v[60:63], v[156:159], v[160:163], v[60:63]
	v_mfma_f32_16x16x32_bf16 v[56:59], v[156:159], v[164:167], v[56:59]
	v_mfma_f32_16x16x32_bf16 v[52:55], v[156:159], v[216:219], v[52:55]
	v_mfma_f32_16x16x32_bf16 v[48:51], v[156:159], v[228:231], v[48:51]
	s_and_b64 vcc, exec, s[14:15]
	s_nop 7
	s_branch .LBB0_646

.LBB0_767:
	s_or_b64 exec, exec, s[0:1]
	s_lshr_b32 s22, s28, 3
	s_mul_i32 s0, s56, 0x108
	s_sub_i32 s23, s0, s22
	s_addk_i32 s23, 0x108
	v_mov_b32_e32 v0, v170
	v_writelane_b32 v252, s0, 28
	s_cmp_ge_i32 s62, s23
	s_mul_i32 s36, s56, 0x8400
	s_waitcnt lgkmcnt(0)
	s_barrier
	s_cbranch_scc1 .LBB0_787
	v_lshlrev_b32_e32 v2, 4, v0
	v_readlane_b32 s0, v252, 13
	v_and_b32_e32 v168, 0x70, v2
	v_mov_b32_e32 v169, 0
	v_readlane_b32 s1, v252, 14
	v_lshl_add_u64 v[2:3], s[76:77], 0, v[168:169]
	v_and_b32_e32 v4, 15, v0
	v_lshl_add_u64 v[172:173], s[0:1], 0, v[168:169]
	s_mov_b64 s[0:1], 0xa80000
	v_lshl_add_u64 v[174:175], v[2:3], 0, s[0:1]
	v_lshrrev_b32_e32 v2, 4, v0
	v_xor_b32_e32 v2, v2, v0
	v_ashrrev_i32_e32 v203, 3, v0
	v_bfe_u32 v5, v0, 6, 1
	v_ashrrev_i32_e32 v6, 7, v0
	v_lshlrev_b32_e32 v2, 4, v2
	v_lshlrev_b32_e32 v4, 7, v4
	v_lshlrev_b32_e32 v3, 7, v203
	v_and_b32_e32 v2, 0x70, v2
	s_add_i32 s0, 16, 0x10000
	v_lshl_or_b32 v7, v6, 13, v4
	v_lshl_or_b32 v4, v5, 13, v4
	v_bfe_u32 v1, v0, 4, 2
	v_and_b32_e32 v40, 3, v203
	v_lshlrev_b32_e32 v40, 4, v40
	v_lshrrev_b32_e32 v41, 2, v203
	v_add_u32_e32 v40, v40, v41
	v_lshrrev_b32_e32 v41, 1, v40
	v_xor_b32_e32 v41, v41, v0
	v_and_b32_e32 v41, 7, v41
	v_lshlrev_b32_e32 v41, 4, v41
	v_lshl_add_u32 v40, v40, 7, v41
	v_add_u32_e32 v205, s0, v40
	v_add_u32_e32 v8, s0, v4
	v_bfe_u32 v9, v0, 1, 3
	s_add_i32 s0, 16, 0x14000
	v_add3_u32 v204, 16, v3, v2
	v_xor_b32_e32 v10, v1, v9
	v_bitop3_b32 v1, v1, v9, 4 bitop3:0x36
	v_and_b32_e32 v40, 3, v203
	v_lshlrev_b32_e32 v40, 4, v40
	v_lshrrev_b32_e32 v41, 2, v203
	v_add_u32_e32 v40, v40, v41
	v_lshrrev_b32_e32 v41, 1, v40
	v_xor_b32_e32 v41, v41, v0
	v_and_b32_e32 v41, 7, v41
	v_lshlrev_b32_e32 v41, 4, v41
	v_lshl_add_u32 v40, v40, 7, v41
	v_add_u32_e32 v210, s0, v40
	v_add_u32_e32 v2, s0, v4
	s_lshl_b32 s0, s62, 7
	v_and_b32_e32 v202, 63, v0
	v_add_u32_e32 v7, 16, v7
	v_lshlrev_b32_e32 v9, 4, v10
	v_lshlrev_b32_e32 v1, 4, v1
	v_and_b32_e32 v0, 7, v0
	s_add_i32 s24, s36, s0
	s_lshl_b32 s0, s62, 3
	v_add_u32_e32 v206, v7, v9
	v_add_u32_e32 v207, v8, v9
	v_add_u32_e32 v208, v7, v1
	v_add_u32_e32 v209, v8, v1
	v_add_u32_e32 v211, v2, v9
	v_add_u32_e32 v212, v2, v1
	v_lshlrev_b32_e32 v213, 6, v6
	v_lshlrev_b32_e32 v214, 6, v5
	v_lshlrev_b32_e32 v176, 4, v0
	v_mov_b32_e32 v177, v169
	s_lshl_b32 s25, s51, 7
	s_add_i32 s26, s28, s0
	s_lshl_b32 s27, s51, 3
	s_mov_b64 s[16:17], 0
	s_mov_b32 s30, 0x20000
	s_mov_b64 s[0:1], 0x20080
	s_mov_b64 s[2:3], 0x40080
	s_mov_b64 s[4:5], 0x60080
	s_mov_b64 s[6:7], 0x20000
	s_mov_b64 s[8:9], 0x40000
	s_mov_b64 s[10:11], 0x60000
	s_mov_b64 s[12:13], 0x100
	s_movk_i32 s31, 0x7fff
	s_mov_b32 s34, s62
	s_branch .LBB0_770
.LBB0_769:
	v_and_b32_e32 v112, 15, v202
	v_lshrrev_b32_e32 v113, 4, v202
	v_add3_u32 v114, s35, v213, v112
	v_or_b32_e32 v115, s37, v214
	v_lshl_add_u32 v115, v113, 4, v115
	v_lshlrev_b32_e32 v114, 13, v114
	v_lshl_add_u32 v114, v115, 1, v114
	v_readlane_b32 s16, v251, 56
	v_readlane_b32 s17, v251, 57
	v_max_f32_e32 v108, 0, v108
	v_max_f32_e32 v104, 0, v104
	v_max_f32_e32 v100, 0, v100
	v_max_f32_e32 v96, 0, v96
	v_mul_f32_e32 v108, v108, v108
	v_mul_f32_e32 v104, v104, v104
	v_mul_f32_e32 v100, v100, v100
	v_mul_f32_e32 v96, v96, v96
	v_cvt_pk_bf16_f32 v120, v108, v104
	v_cvt_pk_bf16_f32 v121, v100, v96
	v_max_f32_e32 v109, 0, v109
	v_max_f32_e32 v105, 0, v105
	v_max_f32_e32 v101, 0, v101
	v_max_f32_e32 v97, 0, v97
	v_mul_f32_e32 v109, v109, v109
	v_mul_f32_e32 v105, v105, v105
	v_mul_f32_e32 v101, v101, v101
	v_mul_f32_e32 v97, v97, v97
	v_cvt_pk_bf16_f32 v122, v109, v105
	v_cvt_pk_bf16_f32 v123, v101, v97
	v_max_f32_e32 v110, 0, v110
	v_max_f32_e32 v106, 0, v106
	v_max_f32_e32 v102, 0, v102
	v_max_f32_e32 v98, 0, v98
	v_mul_f32_e32 v110, v110, v110
	v_mul_f32_e32 v106, v106, v106
	v_mul_f32_e32 v102, v102, v102
	v_mul_f32_e32 v98, v98, v98
	v_cvt_pk_bf16_f32 v124, v110, v106
	v_cvt_pk_bf16_f32 v125, v102, v98
	v_max_f32_e32 v111, 0, v111
	v_max_f32_e32 v107, 0, v107
	v_max_f32_e32 v103, 0, v103
	v_max_f32_e32 v99, 0, v99
	v_mul_f32_e32 v111, v111, v111
	v_mul_f32_e32 v107, v107, v107
	v_mul_f32_e32 v103, v103, v103
	v_mul_f32_e32 v99, v99, v99
	v_cvt_pk_bf16_f32 v126, v111, v107
	v_cvt_pk_bf16_f32 v127, v103, v99
	global_store_dwordx4 v114, v[120:123], s[16:17]
	global_store_dwordx4 v114, v[124:127], s[16:17] offset:16
	v_add_u32_e32 v114, 0x20000, v114
	v_max_f32_e32 v92, 0, v92
	v_max_f32_e32 v88, 0, v88
	v_max_f32_e32 v84, 0, v84
	v_max_f32_e32 v80, 0, v80
	v_mul_f32_e32 v92, v92, v92
	v_mul_f32_e32 v88, v88, v88
	v_mul_f32_e32 v84, v84, v84
	v_mul_f32_e32 v80, v80, v80
	v_cvt_pk_bf16_f32 v120, v92, v88
	v_cvt_pk_bf16_f32 v121, v84, v80
	v_max_f32_e32 v93, 0, v93
	v_max_f32_e32 v89, 0, v89
	v_max_f32_e32 v85, 0, v85
	v_max_f32_e32 v81, 0, v81
	v_mul_f32_e32 v93, v93, v93
	v_mul_f32_e32 v89, v89, v89
	v_mul_f32_e32 v85, v85, v85
	v_mul_f32_e32 v81, v81, v81
	v_cvt_pk_bf16_f32 v122, v93, v89
	v_cvt_pk_bf16_f32 v123, v85, v81
	v_max_f32_e32 v94, 0, v94
	v_max_f32_e32 v90, 0, v90
	v_max_f32_e32 v86, 0, v86
	v_max_f32_e32 v82, 0, v82
	v_mul_f32_e32 v94, v94, v94
	v_mul_f32_e32 v90, v90, v90
	v_mul_f32_e32 v86, v86, v86
	v_mul_f32_e32 v82, v82, v82
	v_cvt_pk_bf16_f32 v124, v94, v90
	v_cvt_pk_bf16_f32 v125, v86, v82
	v_max_f32_e32 v95, 0, v95
	v_max_f32_e32 v91, 0, v91
	v_max_f32_e32 v87, 0, v87
	v_max_f32_e32 v83, 0, v83
	v_mul_f32_e32 v95, v95, v95
	v_mul_f32_e32 v91, v91, v91
	v_mul_f32_e32 v87, v87, v87
	v_mul_f32_e32 v83, v83, v83
	v_cvt_pk_bf16_f32 v126, v95, v91
	v_cvt_pk_bf16_f32 v127, v87, v83
	global_store_dwordx4 v114, v[120:123], s[16:17]
	global_store_dwordx4 v114, v[124:127], s[16:17] offset:16
	v_add_u32_e32 v114, 0x20000, v114
	v_max_f32_e32 v76, 0, v76
	v_max_f32_e32 v72, 0, v72
	v_max_f32_e32 v68, 0, v68
	v_max_f32_e32 v64, 0, v64
	v_mul_f32_e32 v76, v76, v76
	v_mul_f32_e32 v72, v72, v72
	v_mul_f32_e32 v68, v68, v68
	v_mul_f32_e32 v64, v64, v64
	v_cvt_pk_bf16_f32 v120, v76, v72
	v_cvt_pk_bf16_f32 v121, v68, v64
	v_max_f32_e32 v77, 0, v77
	v_max_f32_e32 v73, 0, v73
	v_max_f32_e32 v69, 0, v69
	v_max_f32_e32 v65, 0, v65
	v_mul_f32_e32 v77, v77, v77
	v_mul_f32_e32 v73, v73, v73
	v_mul_f32_e32 v69, v69, v69
	v_mul_f32_e32 v65, v65, v65
	v_cvt_pk_bf16_f32 v122, v77, v73
	v_cvt_pk_bf16_f32 v123, v69, v65
	v_max_f32_e32 v78, 0, v78
	v_max_f32_e32 v74, 0, v74
	v_max_f32_e32 v70, 0, v70
	v_max_f32_e32 v66, 0, v66
	v_mul_f32_e32 v78, v78, v78
	v_mul_f32_e32 v74, v74, v74
	v_mul_f32_e32 v70, v70, v70
	v_mul_f32_e32 v66, v66, v66
	v_cvt_pk_bf16_f32 v124, v78, v74
	v_cvt_pk_bf16_f32 v125, v70, v66
	v_max_f32_e32 v79, 0, v79
	v_max_f32_e32 v75, 0, v75
	v_max_f32_e32 v71, 0, v71
	v_max_f32_e32 v67, 0, v67
	v_mul_f32_e32 v79, v79, v79
	v_mul_f32_e32 v75, v75, v75
	v_mul_f32_e32 v71, v71, v71
	v_mul_f32_e32 v67, v67, v67
	v_cvt_pk_bf16_f32 v126, v79, v75
	v_cvt_pk_bf16_f32 v127, v71, v67
	global_store_dwordx4 v114, v[120:123], s[16:17]
	global_store_dwordx4 v114, v[124:127], s[16:17] offset:16
	v_add_u32_e32 v114, 0x20000, v114
	v_max_f32_e32 v60, 0, v60
	v_max_f32_e32 v56, 0, v56
	v_max_f32_e32 v52, 0, v52
	v_max_f32_e32 v48, 0, v48
	v_mul_f32_e32 v60, v60, v60
	v_mul_f32_e32 v56, v56, v56
	v_mul_f32_e32 v52, v52, v52
	v_mul_f32_e32 v48, v48, v48
	v_cvt_pk_bf16_f32 v120, v60, v56
	v_cvt_pk_bf16_f32 v121, v52, v48
	v_max_f32_e32 v61, 0, v61
	v_max_f32_e32 v57, 0, v57
	v_max_f32_e32 v53, 0, v53
	v_max_f32_e32 v49, 0, v49
	v_mul_f32_e32 v61, v61, v61
	v_mul_f32_e32 v57, v57, v57
	v_mul_f32_e32 v53, v53, v53
	v_mul_f32_e32 v49, v49, v49
	v_cvt_pk_bf16_f32 v122, v61, v57
	v_cvt_pk_bf16_f32 v123, v53, v49
	v_max_f32_e32 v62, 0, v62
	v_max_f32_e32 v58, 0, v58
	v_max_f32_e32 v54, 0, v54
	v_max_f32_e32 v50, 0, v50
	v_mul_f32_e32 v62, v62, v62
	v_mul_f32_e32 v58, v58, v58
	v_mul_f32_e32 v54, v54, v54
	v_mul_f32_e32 v50, v50, v50
	v_cvt_pk_bf16_f32 v124, v62, v58
	v_cvt_pk_bf16_f32 v125, v54, v50
	v_max_f32_e32 v63, 0, v63
	v_max_f32_e32 v59, 0, v59
	v_max_f32_e32 v55, 0, v55
	v_max_f32_e32 v51, 0, v51
	v_mul_f32_e32 v63, v63, v63
	v_mul_f32_e32 v59, v59, v59
	v_mul_f32_e32 v55, v55, v55
	v_mul_f32_e32 v51, v51, v51
	v_cvt_pk_bf16_f32 v126, v63, v59
	v_cvt_pk_bf16_f32 v127, v55, v51
	global_store_dwordx4 v114, v[120:123], s[16:17]
	global_store_dwordx4 v114, v[124:127], s[16:17] offset:16
	s_add_i32 s24, s24, s25
	s_add_i32 s26, s26, s27
	s_mov_b64 s[16:17], -1
	s_and_b64 vcc, exec, s[14:15]
	s_cbranch_vccnz .LBB0_787
.LBB0_770:
	s_add_i32 s14, s34, s22
	s_mov_b32 s100, s14
	s_lshr_b32 s98, s100, 7
	s_lshl_b32 s98, s98, 10
	s_and_b32 s99, s100, 3
	s_lshl_b32 s99, s99, 8
	s_or_b32 s35, s98, s99
	s_lshl_b32 s98, s100, 5
	s_and_b32 s37, s98, 0xf80
	s_cmp_lt_u32 s100, 0x800
	s_cbranch_scc1 .Lswz_c1
	s_and_b32 s98, s100, 1
	s_lshl_b32 s98, s98, 8
	s_or_b32 s35, s98, 0x4000
	s_lshl_b32 s98, s100, 6
	s_and_b32 s37, s98, 0xf80
.Lswz_c1:
	v_add_u32_e32 v48, s35, v203
	v_add_u32_e32 v50, s37, v203
	v_ashrrev_i32_e32 v49, 31, v48
	v_ashrrev_i32_e32 v51, 31, v50
	v_lshlrev_b64 v[48:49], 11, v[48:49]
	v_lshlrev_b64 v[50:51], 11, v[50:51]
	v_lshl_add_u64 v[48:49], v[172:173], 0, v[48:49]
	v_lshl_add_u64 v[50:51], v[174:175], 0, v[50:51]
	s_and_b64 vcc, exec, s[16:17]
	s_cbranch_vccnz .LBB0_772
	s_waitcnt vmcnt(62)
	v_add_co_u32_e32 v4, vcc, 0x20000, v48
	s_nop 1
	v_addc_co_u32_e32 v5, vcc, 0, v49, vcc
	v_add_co_u32_e32 v8, vcc, 0x40000, v48
	s_nop 1
	v_addc_co_u32_e32 v9, vcc, 0, v49, vcc
	v_add_co_u32_e32 v16, vcc, 0x60000, v48
	s_nop 1
	v_addc_co_u32_e32 v17, vcc, 0, v49, vcc
	v_add_co_u32_e32 v36, vcc, 0x20000, v50
	s_nop 1
	v_addc_co_u32_e32 v37, vcc, 0, v51, vcc
	global_load_dwordx4 v[12:15], v[48:49], off
	global_load_dwordx4 v[0:3], v[48:49], off offset:128
	global_load_dwordx4 v[20:23], v[4:5], off
	s_nop 0
	global_load_dwordx4 v[4:7], v[4:5], off offset:128
	s_nop 0
	global_load_dwordx4 v[32:35], v[8:9], off
	s_nop 0
	global_load_dwordx4 v[8:11], v[8:9], off offset:128
	s_nop 0
	global_load_dwordx4 v[24:27], v[16:17], off
	s_nop 0
	global_load_dwordx4 v[16:19], v[16:17], off offset:128
	s_nop 0
	global_load_dwordx4 v[44:47], v[50:51], off
	global_load_dwordx4 v[28:31], v[50:51], off offset:128
	global_load_dwordx4 v[40:43], v[36:37], off
	s_nop 0
	global_load_dwordx4 v[36:39], v[36:37], off offset:128
.LBB0_772:
	s_barrier
	s_waitcnt vmcnt(11)
	ds_write_b128 v204, v[12:15]
	s_waitcnt vmcnt(9)
	ds_write_b128 v204, v[20:23] offset:8192
	s_waitcnt vmcnt(7)
	ds_write_b128 v204, v[32:35] offset:16384
	s_waitcnt vmcnt(5)
	ds_write_b128 v204, v[24:27] offset:24576
	s_waitcnt vmcnt(3)
	ds_write_b128 v205, v[44:47]
	s_waitcnt vmcnt(1)
	ds_write_b128 v205, v[40:43] offset:8192
	v_add_co_u32_e32 v12, vcc, s30, v50
	s_mov_b32 s14, s37
	s_nop 0
	v_addc_co_u32_e32 v13, vcc, 0, v51, vcc
	v_add_co_u32_e32 v14, vcc, 0x60000, v48
	v_add_u32_e32 v52, s14, v203
	s_nop 0
	v_addc_co_u32_e32 v15, vcc, 0, v49, vcc
	global_load_dwordx4 v[40:43], v[12:13], off offset:256
	global_load_dwordx4 v[24:27], v[14:15], off offset:256
	v_add_co_u32_e32 v12, vcc, 0x40000, v48
	v_ashrrev_i32_e32 v53, 31, v52
	s_nop 0
	v_addc_co_u32_e32 v13, vcc, 0, v49, vcc
	v_add_co_u32_e32 v14, vcc, 0x20000, v48
	s_mov_b32 s14, s35
	s_nop 0
	v_addc_co_u32_e32 v15, vcc, 0, v49, vcc
	global_load_dwordx4 v[32:35], v[12:13], off offset:256
	global_load_dwordx4 v[20:23], v[14:15], off offset:256
	global_load_dwordx4 v[44:47], v[50:51], off offset:256
	s_nop 0
	global_load_dwordx4 v[12:15], v[48:49], off offset:256
	s_add_i32 s34, s34, s51
	v_lshlrev_b64 v[52:53], 11, v[52:53]
	s_cmp_ge_i32 s34, s23
	v_lshl_add_u64 v[178:179], s[76:77], 0, v[52:53]
	v_add_u32_e32 v52, s14, v203
	s_cselect_b64 s[14:15], -1, 0
	s_add_i32 s20, s34, s22
	s_cmp_lt_i32 s34, s23
	s_cselect_b64 s[16:17], -1, 0
	s_and_b64 s[18:19], s[16:17], exec
	s_cselect_b32 s18, s20, 0
	v_ashrrev_i32_e32 v53, 31, v52
	v_lshlrev_b64 v[52:53], 11, v[52:53]
	s_mov_b32 s100, s18
	s_lshr_b32 s98, s100, 7
	s_lshl_b32 s98, s98, 10
	s_and_b32 s99, s100, 3
	s_lshl_b32 s99, s99, 8
	s_or_b32 s19, s98, s99
	s_lshl_b32 s98, s100, 5
	s_and_b32 s18, s98, 0xf80
	s_cmp_lt_u32 s100, 0x800
	s_cbranch_scc1 .Lswz_c3
	s_and_b32 s98, s100, 1
	s_lshl_b32 s98, s98, 8
	s_or_b32 s19, s98, 0x4000
	s_lshl_b32 s98, s100, 6
	s_and_b32 s18, s98, 0xf80
.Lswz_c3:
	v_lshl_add_u64 v[180:181], s[76:77], 0, v[52:53]
	v_add_u32_e32 v52, s19, v203
	v_add_u32_e32 v48, s18, v203
	v_ashrrev_i32_e32 v53, 31, v52
	v_ashrrev_i32_e32 v49, 31, v48
	v_lshlrev_b64 v[52:53], 11, v[52:53]
	v_lshlrev_b64 v[48:49], 11, v[48:49]
	v_lshl_add_u64 v[182:183], v[172:173], 0, v[52:53]
	v_lshl_add_u64 v[184:185], v[174:175], 0, v[48:49]
	v_mov_b32_e32 v48, 0
	s_mov_b32 s38, 0
	v_lshl_add_u64 v[186:187], v[182:183], 0, s[0:1]
	v_lshl_add_u64 v[188:189], v[182:183], 0, s[2:3]
	v_lshl_add_u64 v[190:191], v[182:183], 0, s[4:5]
	v_lshl_add_u64 v[192:193], v[184:185], 0, s[0:1]
	v_lshl_add_u64 v[194:195], v[182:183], 0, s[6:7]
	v_lshl_add_u64 v[196:197], v[182:183], 0, s[8:9]
	v_lshl_add_u64 v[198:199], v[182:183], 0, s[10:11]
	v_lshl_add_u64 v[200:201], v[184:185], 0, s[6:7]
	v_mov_b32_e32 v49, v48
	v_mov_b32_e32 v50, v48
	v_mov_b32_e32 v51, v48
	v_mov_b32_e32 v52, v48
	v_mov_b32_e32 v53, v48
	v_mov_b32_e32 v54, v48
	v_mov_b32_e32 v55, v48
	v_mov_b32_e32 v56, v48
	v_mov_b32_e32 v57, v48
	v_mov_b32_e32 v58, v48
	v_mov_b32_e32 v59, v48
	v_mov_b32_e32 v60, v48
	v_mov_b32_e32 v61, v48
	v_mov_b32_e32 v62, v48
	v_mov_b32_e32 v63, v48
	v_mov_b32_e32 v64, v48
	v_mov_b32_e32 v65, v48
	v_mov_b32_e32 v66, v48
	v_mov_b32_e32 v67, v48
	v_mov_b32_e32 v68, v48
	v_mov_b32_e32 v69, v48
	v_mov_b32_e32 v70, v48
	v_mov_b32_e32 v71, v48
	v_mov_b32_e32 v72, v48
	v_mov_b32_e32 v73, v48
	v_mov_b32_e32 v74, v48
	v_mov_b32_e32 v75, v48
	v_mov_b32_e32 v76, v48
	v_mov_b32_e32 v77, v48
	v_mov_b32_e32 v78, v48
	v_mov_b32_e32 v79, v48
	v_mov_b32_e32 v80, v48
	v_mov_b32_e32 v81, v48
	v_mov_b32_e32 v82, v48
	v_mov_b32_e32 v83, v48
	v_mov_b32_e32 v84, v48
	v_mov_b32_e32 v85, v48
	v_mov_b32_e32 v86, v48
	v_mov_b32_e32 v87, v48
	v_mov_b32_e32 v88, v48
	v_mov_b32_e32 v89, v48
	v_mov_b32_e32 v90, v48
	v_mov_b32_e32 v91, v48
	v_mov_b32_e32 v92, v48
	v_mov_b32_e32 v93, v48
	v_mov_b32_e32 v94, v48
	v_mov_b32_e32 v95, v48
	v_mov_b32_e32 v96, v48
	v_mov_b32_e32 v97, v48
	v_mov_b32_e32 v98, v48
	v_mov_b32_e32 v99, v48
	v_mov_b32_e32 v100, v48
	v_mov_b32_e32 v101, v48
	v_mov_b32_e32 v102, v48
	v_mov_b32_e32 v103, v48
	v_mov_b32_e32 v104, v48
	v_mov_b32_e32 v105, v48
	v_mov_b32_e32 v106, v48
	v_mov_b32_e32 v107, v48
	v_mov_b32_e32 v108, v48
	v_mov_b32_e32 v109, v48
	v_mov_b32_e32 v110, v48
	v_mov_b32_e32 v111, v48
	s_branch .LBB0_774
.LBB0_774:
	s_waitcnt lgkmcnt(0)
	s_barrier
	ds_read_b128 v[112:115], v206
	ds_read_b128 v[116:119], v206 offset:2048
	ds_read_b128 v[120:123], v206 offset:4096
	ds_read_b128 v[124:127], v206 offset:6144
	ds_read_b128 v[128:131], v207
	ds_read_b128 v[132:135], v207 offset:2048
	ds_read_b128 v[136:139], v207 offset:4096
	ds_read_b128 v[140:143], v207 offset:6144
	s_waitcnt vmcnt(6)
	ds_write_b128 v204, v[0:3] offset:32768
	ds_write_b128 v204, v[4:7] offset:40960
	ds_write_b128 v204, v[8:11] offset:49152
	ds_write_b128 v204, v[16:19] offset:57344
	ds_write_b128 v210, v[28:31]
	ds_write_b128 v210, v[36:39] offset:8192
	s_cmp_gt_u32 s38, 12
	s_mov_b64 s[18:19], -1
	s_cbranch_scc0 .Lmycfe__778
	s_andn2_b64 vcc, exec, s[16:17]
	s_cbranch_vccnz .Lmycfe__777
	global_load_dwordx4 v[4:7], v[186:187], off
	global_load_dwordx4 v[8:11], v[188:189], off
	global_load_dwordx4 v[0:3], v[182:183], off offset:128
	global_load_dwordx4 v[28:31], v[184:185], off offset:128
	global_load_dwordx4 v[16:19], v[190:191], off
	global_load_dwordx4 v[36:39], v[192:193], off

.Lmycfe__778:
	s_andn2_b64 vcc, exec, s[18:19]
	s_cbranch_vccnz .Lmycfe__780
	v_lshl_add_u64 v[8:9], v[180:181], 0, v[176:177]
	v_add_co_u32_e32 v0, vcc, 0x2800000, v8
	v_lshl_add_u64 v[28:29], v[178:179], 0, v[176:177]
	v_addc_co_u32_e32 v1, vcc, 0, v9, vcc
	v_add_co_u32_e32 v4, vcc, 0x2820000, v8
	s_nop 1
	v_addc_co_u32_e32 v5, vcc, 0, v9, vcc
	v_add_co_u32_e32 v10, vcc, 0x2840000, v8
	global_load_dwordx4 v[0:3], v[0:1], off offset:384
	s_nop 0
	global_load_dwordx4 v[4:7], v[4:5], off offset:384
	v_addc_co_u32_e32 v11, vcc, 0, v9, vcc
	v_add_co_u32_e32 v16, vcc, 0x2860000, v8
	s_nop 1
	v_addc_co_u32_e32 v17, vcc, 0, v9, vcc
	v_add_co_u32_e32 v30, vcc, 0xa80000, v28
	global_load_dwordx4 v[8:11], v[10:11], off offset:384
	s_nop 0
	global_load_dwordx4 v[16:19], v[16:17], off offset:384
	v_addc_co_u32_e32 v31, vcc, 0, v29, vcc
	v_add_co_u32_e32 v36, vcc, 0xaa0000, v28
	s_nop 1
	v_addc_co_u32_e32 v37, vcc, 0, v29, vcc
	global_load_dwordx4 v[28:31], v[30:31], off offset:384
	s_nop 0
	global_load_dwordx4 v[36:39], v[36:37], off offset:384
.Lmycfe__780:
	s_waitcnt lgkmcnt(0)
	v_mfma_f32_16x16x32_bf16 v[108:111], v[128:131], v[112:115], v[108:111]
	ds_read_b128 v[144:147], v208
	v_mfma_f32_16x16x32_bf16 v[104:107], v[132:135], v[112:115], v[104:107]
	ds_read_b128 v[148:151], v208 offset:2048
	v_mfma_f32_16x16x32_bf16 v[100:103], v[136:139], v[112:115], v[100:103]
	ds_read_b128 v[152:155], v208 offset:4096
	v_mfma_f32_16x16x32_bf16 v[96:99], v[140:143], v[112:115], v[96:99]
	ds_read_b128 v[156:159], v208 offset:6144
	v_mfma_f32_16x16x32_bf16 v[92:95], v[128:131], v[116:119], v[92:95]
	ds_read_b128 v[160:163], v209
	v_mfma_f32_16x16x32_bf16 v[88:91], v[132:135], v[116:119], v[88:91]
	ds_read_b128 v[164:167], v209 offset:2048
	v_mfma_f32_16x16x32_bf16 v[84:87], v[136:139], v[116:119], v[84:87]
	ds_read_b128 v[216:219], v209 offset:4096
	v_mfma_f32_16x16x32_bf16 v[80:83], v[140:143], v[116:119], v[80:83]
	ds_read_b128 v[228:231], v209 offset:6144
	v_mfma_f32_16x16x32_bf16 v[76:79], v[128:131], v[120:123], v[76:79]
	v_mfma_f32_16x16x32_bf16 v[72:75], v[132:135], v[120:123], v[72:75]
	v_mfma_f32_16x16x32_bf16 v[68:71], v[136:139], v[120:123], v[68:71]
	v_mfma_f32_16x16x32_bf16 v[64:67], v[140:143], v[120:123], v[64:67]
	v_mfma_f32_16x16x32_bf16 v[60:63], v[128:131], v[124:127], v[60:63]
	v_mfma_f32_16x16x32_bf16 v[56:59], v[132:135], v[124:127], v[56:59]
	v_mfma_f32_16x16x32_bf16 v[52:55], v[136:139], v[124:127], v[52:55]
	v_mfma_f32_16x16x32_bf16 v[48:51], v[140:143], v[124:127], v[48:51]
	s_branch .Lmyc_odd
.Lmyc_even:
	s_waitcnt lgkmcnt(0)
	s_barrier
	ds_read_b128 v[112:115], v206
	ds_read_b128 v[116:119], v206 offset:2048
	ds_read_b128 v[120:123], v206 offset:4096
	ds_read_b128 v[124:127], v206 offset:6144
	ds_read_b128 v[128:131], v207
	ds_read_b128 v[132:135], v207 offset:2048
	ds_read_b128 v[136:139], v207 offset:4096
	ds_read_b128 v[140:143], v207 offset:6144
	s_cmp_gt_u32 s38, 12
	s_cbranch_scc0 .Lmyc_ew6
	s_and_b64 vcc, exec, s[16:17]
	s_cbranch_vccnz .Lmyc_ew6
	s_waitcnt vmcnt(0)
.Lmyc_ew6:
	s_waitcnt vmcnt(6)
	v_mfma_f32_16x16x32_bf16 v[108:111], v[160:163], v[144:147], v[108:111]
	ds_write_b128 v204, v[0:3] offset:32768
	v_mfma_f32_16x16x32_bf16 v[104:107], v[164:167], v[144:147], v[104:107]
	ds_write_b128 v204, v[4:7] offset:40960
	v_mfma_f32_16x16x32_bf16 v[100:103], v[216:219], v[144:147], v[100:103]
	ds_write_b128 v204, v[8:11] offset:49152
	v_mfma_f32_16x16x32_bf16 v[96:99], v[228:231], v[144:147], v[96:99]
	ds_write_b128 v204, v[16:19] offset:57344
	v_mfma_f32_16x16x32_bf16 v[92:95], v[160:163], v[148:151], v[92:95]
	ds_write_b128 v210, v[28:31]
	v_mfma_f32_16x16x32_bf16 v[88:91], v[164:167], v[148:151], v[88:91]
	ds_write_b128 v210, v[36:39] offset:8192
	v_mfma_f32_16x16x32_bf16 v[84:87], v[216:219], v[148:151], v[84:87]
	v_mfma_f32_16x16x32_bf16 v[80:83], v[228:231], v[148:151], v[80:83]
	s_cmp_gt_u32 s38, 12
	s_mov_b64 s[18:19], -1
	s_cbranch_scc0 .Lmycse__778
	s_andn2_b64 vcc, exec, s[16:17]
	s_cbranch_vccnz .Lmycse__777
	global_load_dwordx4 v[4:7], v[186:187], off
	global_load_dwordx4 v[8:11], v[188:189], off
	global_load_dwordx4 v[0:3], v[182:183], off offset:128
	global_load_dwordx4 v[28:31], v[184:185], off offset:128
	global_load_dwordx4 v[16:19], v[190:191], off
	global_load_dwordx4 v[36:39], v[192:193], off

.Lmycse__780:
	v_mfma_f32_16x16x32_bf16 v[76:79], v[160:163], v[152:155], v[76:79]
	v_mfma_f32_16x16x32_bf16 v[72:75], v[164:167], v[152:155], v[72:75]
	v_mfma_f32_16x16x32_bf16 v[68:71], v[216:219], v[152:155], v[68:71]
	v_mfma_f32_16x16x32_bf16 v[64:67], v[228:231], v[152:155], v[64:67]
	v_mfma_f32_16x16x32_bf16 v[60:63], v[160:163], v[156:159], v[60:63]
	v_mfma_f32_16x16x32_bf16 v[56:59], v[164:167], v[156:159], v[56:59]
	v_mfma_f32_16x16x32_bf16 v[52:55], v[216:219], v[156:159], v[52:55]
	v_mfma_f32_16x16x32_bf16 v[48:51], v[228:231], v[156:159], v[48:51]
	s_waitcnt lgkmcnt(0)
	v_mfma_f32_16x16x32_bf16 v[108:111], v[128:131], v[112:115], v[108:111]
	ds_read_b128 v[144:147], v208
	v_mfma_f32_16x16x32_bf16 v[104:107], v[132:135], v[112:115], v[104:107]
	ds_read_b128 v[148:151], v208 offset:2048
	v_mfma_f32_16x16x32_bf16 v[100:103], v[136:139], v[112:115], v[100:103]
	ds_read_b128 v[152:155], v208 offset:4096
	v_mfma_f32_16x16x32_bf16 v[96:99], v[140:143], v[112:115], v[96:99]
	ds_read_b128 v[156:159], v208 offset:6144
	v_mfma_f32_16x16x32_bf16 v[92:95], v[128:131], v[116:119], v[92:95]
	ds_read_b128 v[160:163], v209
	v_mfma_f32_16x16x32_bf16 v[88:91], v[132:135], v[116:119], v[88:91]
	ds_read_b128 v[164:167], v209 offset:2048
	v_mfma_f32_16x16x32_bf16 v[84:87], v[136:139], v[116:119], v[84:87]
	ds_read_b128 v[216:219], v209 offset:4096
	v_mfma_f32_16x16x32_bf16 v[80:83], v[140:143], v[116:119], v[80:83]
	ds_read_b128 v[228:231], v209 offset:6144
	v_mfma_f32_16x16x32_bf16 v[76:79], v[128:131], v[120:123], v[76:79]
	v_mfma_f32_16x16x32_bf16 v[72:75], v[132:135], v[120:123], v[72:75]
	v_mfma_f32_16x16x32_bf16 v[68:71], v[136:139], v[120:123], v[68:71]
	v_mfma_f32_16x16x32_bf16 v[64:67], v[140:143], v[120:123], v[64:67]
	v_mfma_f32_16x16x32_bf16 v[60:63], v[128:131], v[124:127], v[60:63]
	v_mfma_f32_16x16x32_bf16 v[56:59], v[132:135], v[124:127], v[56:59]
	v_mfma_f32_16x16x32_bf16 v[52:55], v[136:139], v[124:127], v[52:55]
	v_mfma_f32_16x16x32_bf16 v[48:51], v[140:143], v[124:127], v[48:51]
.Lmyc_odd:
	s_waitcnt lgkmcnt(0)
	s_barrier
	ds_read_b128 v[112:115], v206 offset:32768
	ds_read_b128 v[116:119], v206 offset:34816
	ds_read_b128 v[120:123], v206 offset:36864
	ds_read_b128 v[124:127], v206 offset:38912
	ds_read_b128 v[128:131], v211
	ds_read_b128 v[132:135], v211 offset:2048
	ds_read_b128 v[136:139], v211 offset:4096
	ds_read_b128 v[140:143], v211 offset:6144
	s_cmp_gt_u32 s38, 13
	s_cselect_b64 s[18:19], -1, 0
	s_and_b64 vcc, exec, s[18:19]
	s_cbranch_vccnz .Lmyc_oddlast
	s_waitcnt vmcnt(6)
	v_mfma_f32_16x16x32_bf16 v[108:111], v[160:163], v[144:147], v[108:111]
	ds_write_b128 v204, v[12:15]
	v_mfma_f32_16x16x32_bf16 v[104:107], v[164:167], v[144:147], v[104:107]
	ds_write_b128 v204, v[20:23] offset:8192
	v_mfma_f32_16x16x32_bf16 v[100:103], v[216:219], v[144:147], v[100:103]
	ds_write_b128 v204, v[32:35] offset:16384
	v_mfma_f32_16x16x32_bf16 v[96:99], v[228:231], v[144:147], v[96:99]
	ds_write_b128 v204, v[24:27] offset:24576
	v_mfma_f32_16x16x32_bf16 v[92:95], v[160:163], v[148:151], v[92:95]
	ds_write_b128 v205, v[44:47]
	v_mfma_f32_16x16x32_bf16 v[88:91], v[164:167], v[148:151], v[88:91]
	ds_write_b128 v205, v[40:43] offset:8192
	v_mfma_f32_16x16x32_bf16 v[84:87], v[216:219], v[148:151], v[84:87]
	v_mfma_f32_16x16x32_bf16 v[80:83], v[228:231], v[148:151], v[80:83]
	s_cmp_gt_u32 s38, 11
	s_mov_b64 s[20:21], -1
	s_cbranch_scc0 .Lmycso__785
	s_andn2_b64 vcc, exec, s[16:17]
	s_cbranch_vccnz .Lmycso__784
	global_load_dwordx4 v[20:23], v[194:195], off
	global_load_dwordx4 v[32:35], v[196:197], off
	global_load_dwordx4 v[12:15], v[182:183], off
	global_load_dwordx4 v[44:47], v[184:185], off
	global_load_dwordx4 v[24:27], v[198:199], off
	global_load_dwordx4 v[40:43], v[200:201], off

.Lmycso__785:
	s_andn2_b64 vcc, exec, s[20:21]
	s_cbranch_vccnz .Lmyc_ocont
	v_lshl_add_u64 v[24:25], v[180:181], 0, v[176:177]
	v_add_co_u32_e32 v12, vcc, 0x2800000, v24
	v_lshl_add_u64 v[40:41], v[178:179], 0, v[176:177]
	v_addc_co_u32_e32 v13, vcc, 0, v25, vcc
	v_add_co_u32_e32 v20, vcc, 0x2820000, v24
	s_nop 1
	v_addc_co_u32_e32 v21, vcc, 0, v25, vcc
	v_add_co_u32_e32 v26, vcc, 0x2840000, v24
	global_load_dwordx4 v[12:15], v[12:13], off offset:512
	s_nop 0
	global_load_dwordx4 v[20:23], v[20:21], off offset:512
	v_addc_co_u32_e32 v27, vcc, 0, v25, vcc
	v_add_co_u32_e32 v24, vcc, 0x2860000, v24
	s_nop 1
	v_addc_co_u32_e32 v25, vcc, 0, v25, vcc
	v_add_co_u32_e32 v42, vcc, 0xa80000, v40
	global_load_dwordx4 v[32:35], v[26:27], off offset:512
	s_nop 0
	global_load_dwordx4 v[24:27], v[24:25], off offset:512
	v_addc_co_u32_e32 v43, vcc, 0, v41, vcc
	v_add_co_u32_e32 v40, vcc, 0xaa0000, v40
	s_nop 1
	v_addc_co_u32_e32 v41, vcc, 0, v41, vcc
	global_load_dwordx4 v[44:47], v[42:43], off offset:512
	s_nop 0
	global_load_dwordx4 v[40:43], v[40:41], off offset:512
.Lmyc_ocont:
	v_mfma_f32_16x16x32_bf16 v[76:79], v[160:163], v[152:155], v[76:79]
	v_mfma_f32_16x16x32_bf16 v[72:75], v[164:167], v[152:155], v[72:75]
	v_mfma_f32_16x16x32_bf16 v[68:71], v[216:219], v[152:155], v[68:71]
	v_mfma_f32_16x16x32_bf16 v[64:67], v[228:231], v[152:155], v[64:67]
	v_mfma_f32_16x16x32_bf16 v[60:63], v[160:163], v[156:159], v[60:63]
	v_mfma_f32_16x16x32_bf16 v[56:59], v[164:167], v[156:159], v[56:59]
	v_mfma_f32_16x16x32_bf16 v[52:55], v[216:219], v[156:159], v[52:55]
	v_mfma_f32_16x16x32_bf16 v[48:51], v[228:231], v[156:159], v[48:51]
	s_waitcnt lgkmcnt(0)
	v_mfma_f32_16x16x32_bf16 v[108:111], v[128:131], v[112:115], v[108:111]
	ds_read_b128 v[144:147], v208 offset:32768
	v_mfma_f32_16x16x32_bf16 v[104:107], v[132:135], v[112:115], v[104:107]
	ds_read_b128 v[148:151], v208 offset:34816
	v_mfma_f32_16x16x32_bf16 v[100:103], v[136:139], v[112:115], v[100:103]
	ds_read_b128 v[152:155], v208 offset:36864
	v_mfma_f32_16x16x32_bf16 v[96:99], v[140:143], v[112:115], v[96:99]
	ds_read_b128 v[156:159], v208 offset:38912
	v_mfma_f32_16x16x32_bf16 v[92:95], v[128:131], v[116:119], v[92:95]
	ds_read_b128 v[160:163], v212
	v_mfma_f32_16x16x32_bf16 v[88:91], v[132:135], v[116:119], v[88:91]
	ds_read_b128 v[164:167], v212 offset:2048
	v_mfma_f32_16x16x32_bf16 v[84:87], v[136:139], v[116:119], v[84:87]
	ds_read_b128 v[216:219], v212 offset:4096
	v_mfma_f32_16x16x32_bf16 v[80:83], v[140:143], v[116:119], v[80:83]
	ds_read_b128 v[228:231], v212 offset:6144
	v_mfma_f32_16x16x32_bf16 v[76:79], v[128:131], v[120:123], v[76:79]
	v_mfma_f32_16x16x32_bf16 v[72:75], v[132:135], v[120:123], v[72:75]
	v_mfma_f32_16x16x32_bf16 v[68:71], v[136:139], v[120:123], v[68:71]
	v_mfma_f32_16x16x32_bf16 v[64:67], v[140:143], v[120:123], v[64:67]
	v_mfma_f32_16x16x32_bf16 v[60:63], v[128:131], v[124:127], v[60:63]
	v_mfma_f32_16x16x32_bf16 v[56:59], v[132:135], v[124:127], v[56:59]
	v_mfma_f32_16x16x32_bf16 v[52:55], v[136:139], v[124:127], v[52:55]
	v_mfma_f32_16x16x32_bf16 v[48:51], v[140:143], v[124:127], v[48:51]
	s_add_i32 s38, s38, 2
	v_lshl_add_u64 v[178:179], v[178:179], 0, s[12:13]
	v_lshl_add_u64 v[180:181], v[180:181], 0, s[12:13]
	s_branch .Lmyc_even
.Lmyc_oddlast:
	v_mfma_f32_16x16x32_bf16 v[108:111], v[160:163], v[144:147], v[108:111]
	v_mfma_f32_16x16x32_bf16 v[104:107], v[164:167], v[144:147], v[104:107]
	v_mfma_f32_16x16x32_bf16 v[100:103], v[216:219], v[144:147], v[100:103]
	v_mfma_f32_16x16x32_bf16 v[96:99], v[228:231], v[144:147], v[96:99]
	v_mfma_f32_16x16x32_bf16 v[92:95], v[160:163], v[148:151], v[92:95]
	v_mfma_f32_16x16x32_bf16 v[88:91], v[164:167], v[148:151], v[88:91]
	v_mfma_f32_16x16x32_bf16 v[84:87], v[216:219], v[148:151], v[84:87]
	v_mfma_f32_16x16x32_bf16 v[80:83], v[228:231], v[148:151], v[80:83]
	v_mfma_f32_16x16x32_bf16 v[76:79], v[160:163], v[152:155], v[76:79]
	v_mfma_f32_16x16x32_bf16 v[72:75], v[164:167], v[152:155], v[72:75]
	v_mfma_f32_16x16x32_bf16 v[68:71], v[216:219], v[152:155], v[68:71]
	v_mfma_f32_16x16x32_bf16 v[64:67], v[228:231], v[152:155], v[64:67]
	v_mfma_f32_16x16x32_bf16 v[60:63], v[160:163], v[156:159], v[60:63]
	v_mfma_f32_16x16x32_bf16 v[56:59], v[164:167], v[156:159], v[56:59]
	v_mfma_f32_16x16x32_bf16 v[52:55], v[216:219], v[156:159], v[52:55]
	v_mfma_f32_16x16x32_bf16 v[48:51], v[228:231], v[156:159], v[48:51]
	s_waitcnt lgkmcnt(0)
	v_mfma_f32_16x16x32_bf16 v[108:111], v[128:131], v[112:115], v[108:111]
	ds_read_b128 v[144:147], v208 offset:32768
	v_mfma_f32_16x16x32_bf16 v[104:107], v[132:135], v[112:115], v[104:107]
	ds_read_b128 v[148:151], v208 offset:34816
	v_mfma_f32_16x16x32_bf16 v[100:103], v[136:139], v[112:115], v[100:103]
	ds_read_b128 v[152:155], v208 offset:36864
	v_mfma_f32_16x16x32_bf16 v[96:99], v[140:143], v[112:115], v[96:99]
	ds_read_b128 v[156:159], v208 offset:38912
	v_mfma_f32_16x16x32_bf16 v[92:95], v[128:131], v[116:119], v[92:95]
	ds_read_b128 v[160:163], v212
	v_mfma_f32_16x16x32_bf16 v[88:91], v[132:135], v[116:119], v[88:91]
	ds_read_b128 v[164:167], v212 offset:2048
	v_mfma_f32_16x16x32_bf16 v[84:87], v[136:139], v[116:119], v[84:87]
	ds_read_b128 v[216:219], v212 offset:4096
	v_mfma_f32_16x16x32_bf16 v[80:83], v[140:143], v[116:119], v[80:83]
	ds_read_b128 v[228:231], v212 offset:6144
	v_mfma_f32_16x16x32_bf16 v[76:79], v[128:131], v[120:123], v[76:79]
	v_mfma_f32_16x16x32_bf16 v[72:75], v[132:135], v[120:123], v[72:75]
	v_mfma_f32_16x16x32_bf16 v[68:71], v[136:139], v[120:123], v[68:71]
	v_mfma_f32_16x16x32_bf16 v[64:67], v[140:143], v[120:123], v[64:67]
	v_mfma_f32_16x16x32_bf16 v[60:63], v[128:131], v[124:127], v[60:63]
	v_mfma_f32_16x16x32_bf16 v[56:59], v[132:135], v[124:127], v[56:59]
	v_mfma_f32_16x16x32_bf16 v[52:55], v[136:139], v[124:127], v[52:55]
	v_mfma_f32_16x16x32_bf16 v[48:51], v[140:143], v[124:127], v[48:51]
	s_add_i32 s38, s38, 2
	v_lshl_add_u64 v[178:179], v[178:179], 0, s[12:13]
	v_lshl_add_u64 v[180:181], v[180:181], 0, s[12:13]
	s_waitcnt lgkmcnt(0)
	v_mfma_f32_16x16x32_bf16 v[108:111], v[160:163], v[144:147], v[108:111]
	v_mfma_f32_16x16x32_bf16 v[104:107], v[164:167], v[144:147], v[104:107]
	v_mfma_f32_16x16x32_bf16 v[100:103], v[216:219], v[144:147], v[100:103]
	v_mfma_f32_16x16x32_bf16 v[96:99], v[228:231], v[144:147], v[96:99]
	v_mfma_f32_16x16x32_bf16 v[92:95], v[160:163], v[148:151], v[92:95]
	v_mfma_f32_16x16x32_bf16 v[88:91], v[164:167], v[148:151], v[88:91]
	v_mfma_f32_16x16x32_bf16 v[84:87], v[216:219], v[148:151], v[84:87]
	v_mfma_f32_16x16x32_bf16 v[80:83], v[228:231], v[148:151], v[80:83]
	v_mfma_f32_16x16x32_bf16 v[76:79], v[160:163], v[152:155], v[76:79]
	v_mfma_f32_16x16x32_bf16 v[72:75], v[164:167], v[152:155], v[72:75]
	v_mfma_f32_16x16x32_bf16 v[68:71], v[216:219], v[152:155], v[68:71]
	v_mfma_f32_16x16x32_bf16 v[64:67], v[228:231], v[152:155], v[64:67]
	v_mfma_f32_16x16x32_bf16 v[60:63], v[160:163], v[156:159], v[60:63]
	v_mfma_f32_16x16x32_bf16 v[56:59], v[164:167], v[156:159], v[56:59]
	v_mfma_f32_16x16x32_bf16 v[52:55], v[216:219], v[156:159], v[52:55]
	v_mfma_f32_16x16x32_bf16 v[48:51], v[228:231], v[156:159], v[48:51]
	s_and_b64 vcc, exec, s[18:19]
	s_nop 7
	s_branch .LBB0_769

.LBB0_1036:
	s_add_i32 s2, s12, s14
	s_mov_b32 s100, s2
	s_lshr_b32 s98, s100, 8
	s_lshl_b32 s98, s98, 10
	s_and_b32 s99, s100, 3
	s_lshl_b32 s99, s99, 8
	s_or_b32 s9, s98, s99
	s_lshl_b32 s98, s100, 5
	s_and_b32 s8, s98, 0x1f80
	s_cmp_lt_u32 s100, 0x800
	s_cbranch_scc1 .Lswz_d1
	s_mov_b32 s9, 0x2000
	s_lshl_b32 s98, s100, 7
	s_and_b32 s8, s98, 0x1f80
.Lswz_d1:
	v_add_u32_e32 v50, s9, v221
	v_add_u32_e32 v52, s8, v221
	v_ashrrev_i32_e32 v51, 31, v50
	v_ashrrev_i32_e32 v53, 31, v52
	v_lshlrev_b64 v[50:51], 11, v[50:51]
	v_lshlrev_b64 v[52:53], 11, v[52:53]
	v_lshl_add_u64 v[50:51], v[168:169], 0, v[50:51]
	v_lshl_add_u64 v[52:53], v[172:173], 0, v[52:53]
	s_and_b64 vcc, exec, s[0:1]
	s_cbranch_vccnz .LBB0_1038
	s_waitcnt vmcnt(4)
	v_add_co_u32_e32 v6, vcc, 0x20000, v50
	s_nop 1
	v_addc_co_u32_e32 v7, vcc, 0, v51, vcc
	s_waitcnt vmcnt(3)
	v_add_co_u32_e32 v10, vcc, 0x40000, v50
	s_nop 1
	v_addc_co_u32_e32 v11, vcc, 0, v51, vcc
	s_waitcnt vmcnt(1)
	v_add_co_u32_e32 v14, vcc, 0x60000, v50
	s_nop 1
	v_addc_co_u32_e32 v15, vcc, 0, v51, vcc
	s_waitcnt vmcnt(0)
	v_add_co_u32_e32 v26, vcc, 0x20000, v52
	s_nop 1
	v_addc_co_u32_e32 v27, vcc, 0, v53, vcc
	global_load_dwordx4 v[38:41], v[50:51], off
	global_load_dwordx4 v[2:5], v[50:51], off offset:128
	global_load_dwordx4 v[46:49], v[6:7], off
	s_nop 0
	global_load_dwordx4 v[6:9], v[6:7], off offset:128
	s_nop 0
	global_load_dwordx4 v[34:37], v[10:11], off
	s_nop 0
	global_load_dwordx4 v[10:13], v[10:11], off offset:128
	s_nop 0
	global_load_dwordx4 v[42:45], v[14:15], off
	s_nop 0
	global_load_dwordx4 v[14:17], v[14:15], off offset:128
	s_nop 0
	global_load_dwordx4 v[22:25], v[52:53], off
	global_load_dwordx4 v[18:21], v[52:53], off offset:128
	global_load_dwordx4 v[30:33], v[26:27], off
	s_nop 0
	global_load_dwordx4 v[26:29], v[26:27], off offset:128
.LBB0_1038:
	s_barrier
	s_waitcnt vmcnt(0)
	ds_write_b128 v222, v[38:41]
	s_waitcnt vmcnt(0)
	ds_write_b128 v222, v[46:49] offset:8192
	ds_write_b128 v222, v[34:37] offset:16384
	ds_write_b128 v222, v[42:45] offset:24576
	ds_write_b128 v223, v[22:25]
	ds_write_b128 v223, v[30:33] offset:8192
	v_add_co_u32_e32 v22, vcc, s79, v52
	s_mov_b32 s0, s8
	s_nop 0
	v_addc_co_u32_e32 v23, vcc, 0, v53, vcc
	v_add_co_u32_e32 v34, vcc, 0x60000, v50
	global_load_dwordx4 v[30:33], v[22:23], off offset:256
	s_nop 0
	global_load_dwordx4 v[22:25], v[52:53], off offset:256
	v_addc_co_u32_e32 v35, vcc, 0, v51, vcc
	global_load_dwordx4 v[42:45], v[34:35], off offset:256
	v_add_co_u32_e32 v34, vcc, 0x40000, v50
	v_add_u32_e32 v54, s0, v221
	s_nop 0
	v_addc_co_u32_e32 v35, vcc, 0, v51, vcc
	v_add_co_u32_e32 v38, vcc, 0x20000, v50
	global_load_dwordx4 v[34:37], v[34:35], off offset:256
	s_nop 0
	v_addc_co_u32_e32 v39, vcc, 0, v51, vcc
	global_load_dwordx4 v[46:49], v[38:39], off offset:256
	s_nop 0
	global_load_dwordx4 v[38:41], v[50:51], off offset:256
	s_mov_b32 s0, s9
	s_add_i32 s12, s12, s51
	s_cmp_ge_i32 s12, s15
	v_ashrrev_i32_e32 v55, 31, v54
	s_cselect_b64 s[6:7], -1, 0
	s_add_i32 s4, s12, s14
	v_lshlrev_b64 v[54:55], 11, v[54:55]
	s_cmp_lt_i32 s12, s15
	v_lshl_add_u64 v[176:177], s[76:77], 0, v[54:55]
	v_add_u32_e32 v54, s0, v221
	s_cselect_b64 s[0:1], -1, 0
	s_and_b64 s[2:3], s[0:1], exec
	s_cselect_b32 s2, s4, 0
	v_ashrrev_i32_e32 v55, 31, v54
	s_mov_b32 s100, s2
	s_lshr_b32 s98, s100, 8
	s_lshl_b32 s98, s98, 10
	s_and_b32 s99, s100, 3
	s_lshl_b32 s99, s99, 8
	s_or_b32 s3, s98, s99
	s_lshl_b32 s98, s100, 5
	s_and_b32 s2, s98, 0x1f80
	s_cmp_lt_u32 s100, 0x800
	s_cbranch_scc1 .Lswz_d3
	s_mov_b32 s3, 0x2000
	s_lshl_b32 s98, s100, 7
	s_and_b32 s2, s98, 0x1f80
.Lswz_d3:
	v_lshlrev_b64 v[54:55], 11, v[54:55]
	v_lshl_add_u64 v[178:179], s[76:77], 0, v[54:55]
	v_add_u32_e32 v54, s3, v221
	v_ashrrev_i32_e32 v55, 31, v54
	v_lshlrev_b64 v[54:55], 11, v[54:55]
	v_add_u32_e32 v56, s2, v221
	v_lshl_add_u64 v[180:181], v[168:169], 0, v[54:55]
	s_mov_b64 s[2:3], 0x40080
	v_ashrrev_i32_e32 v57, 31, v56
	v_lshl_add_u64 v[186:187], v[180:181], 0, s[2:3]
	s_mov_b64 s[2:3], 0x60080
	v_lshlrev_b64 v[56:57], 11, v[56:57]
	v_lshl_add_u64 v[188:189], v[180:181], 0, s[2:3]
	s_mov_b64 s[2:3], 0x40000
	v_lshl_add_u64 v[182:183], v[172:173], 0, v[56:57]
	s_mov_b64 s[4:5], 0x20000
	v_lshl_add_u64 v[194:195], v[180:181], 0, s[2:3]
	s_mov_b64 s[2:3], 0x60000
	v_mov_b32_e32 v50, 0
	s_mov_b32 s13, 0
	v_lshl_add_u64 v[184:185], v[180:181], 0, s[62:63]
	v_lshl_add_u64 v[190:191], v[182:183], 0, s[62:63]
	v_lshl_add_u64 v[192:193], v[180:181], 0, s[4:5]
	v_lshl_add_u64 v[196:197], v[180:181], 0, s[2:3]
	s_mov_b64 s[64:65], 0x20000
	v_lshl_add_u64 v[198:199], v[182:183], 0, s[4:5]
	v_mov_b32_e32 v51, v50
	v_mov_b32_e32 v52, v50
	v_mov_b32_e32 v53, v50
	v_mov_b32_e32 v54, v50
	v_mov_b32_e32 v55, v50
	v_mov_b32_e32 v56, v50
	v_mov_b32_e32 v57, v50
	v_mov_b32_e32 v82, v50
	v_mov_b32_e32 v83, v50
	v_mov_b32_e32 v84, v50
	v_mov_b32_e32 v85, v50
	v_mov_b32_e32 v86, v50
	v_mov_b32_e32 v87, v50
	v_mov_b32_e32 v88, v50
	v_mov_b32_e32 v89, v50
	v_mov_b32_e32 v58, v50
	v_mov_b32_e32 v59, v50
	v_mov_b32_e32 v60, v50
	v_mov_b32_e32 v61, v50
	v_mov_b32_e32 v62, v50
	v_mov_b32_e32 v63, v50
	v_mov_b32_e32 v64, v50
	v_mov_b32_e32 v65, v50
	v_mov_b32_e32 v90, v50
	v_mov_b32_e32 v91, v50
	v_mov_b32_e32 v92, v50
	v_mov_b32_e32 v93, v50
	v_mov_b32_e32 v94, v50
	v_mov_b32_e32 v95, v50
	v_mov_b32_e32 v96, v50
	v_mov_b32_e32 v97, v50
	v_mov_b32_e32 v66, v50
	v_mov_b32_e32 v67, v50
	v_mov_b32_e32 v68, v50
	v_mov_b32_e32 v69, v50
	v_mov_b32_e32 v70, v50
	v_mov_b32_e32 v71, v50
	v_mov_b32_e32 v72, v50
	v_mov_b32_e32 v73, v50
	v_mov_b32_e32 v98, v50
	v_mov_b32_e32 v99, v50
	v_mov_b32_e32 v100, v50
	v_mov_b32_e32 v101, v50
	v_mov_b32_e32 v102, v50
	v_mov_b32_e32 v103, v50
	v_mov_b32_e32 v104, v50
	v_mov_b32_e32 v105, v50
	v_mov_b32_e32 v74, v50
	v_mov_b32_e32 v75, v50
	v_mov_b32_e32 v76, v50
	v_mov_b32_e32 v77, v50
	v_mov_b32_e32 v78, v50
	v_mov_b32_e32 v79, v50
	v_mov_b32_e32 v80, v50
	v_mov_b32_e32 v81, v50
	v_mov_b32_e32 v106, v50
	v_mov_b32_e32 v107, v50
	v_mov_b32_e32 v108, v50
	v_mov_b32_e32 v109, v50
	v_mov_b32_e32 v110, v50
	v_mov_b32_e32 v111, v50
	v_mov_b32_e32 v112, v50
	v_mov_b32_e32 v113, v50
	s_branch .LBB0_1040
.LBB0_1040:
	s_waitcnt lgkmcnt(0)
	s_barrier
	ds_read_b128 v[114:117], v224
	ds_read_b128 v[118:121], v224 offset:2048
	ds_read_b128 v[122:125], v224 offset:4096
	ds_read_b128 v[126:129], v224 offset:6144
	ds_read_b128 v[130:133], v225
	ds_read_b128 v[134:137], v225 offset:2048
	ds_read_b128 v[138:141], v225 offset:4096
	ds_read_b128 v[142:145], v225 offset:6144
	s_waitcnt vmcnt(6)
	ds_write_b128 v222, v[2:5] offset:32768
	ds_write_b128 v222, v[6:9] offset:40960
	ds_write_b128 v222, v[10:13] offset:49152
	ds_write_b128 v222, v[14:17] offset:57344
	ds_write_b128 v228, v[18:21]
	ds_write_b128 v228, v[26:29] offset:8192
	s_cmp_gt_u32 s13, 12
	s_mov_b64 s[2:3], -1
	s_cbranch_scc0 .Lmydfe__1044
	s_andn2_b64 vcc, exec, s[0:1]
	s_cbranch_vccnz .Lmydfe__1043
	global_load_dwordx4 v[6:9], v[184:185], off
	global_load_dwordx4 v[10:13], v[186:187], off
	global_load_dwordx4 v[2:5], v[180:181], off offset:128
	global_load_dwordx4 v[18:21], v[182:183], off offset:128
	global_load_dwordx4 v[14:17], v[188:189], off
	global_load_dwordx4 v[26:29], v[190:191], off

.Lmydfe__1044:
	s_andn2_b64 vcc, exec, s[2:3]
	s_cbranch_vccnz .Lmydfe__1046
	v_lshl_add_u64 v[10:11], v[178:179], 0, v[174:175]
	v_add_co_u32_e32 v2, vcc, 0x2800000, v10
	v_lshl_add_u64 v[18:19], v[176:177], 0, v[174:175]
	v_addc_co_u32_e32 v3, vcc, 0, v11, vcc
	v_add_co_u32_e32 v6, vcc, 0x2820000, v10
	s_nop 1
	v_addc_co_u32_e32 v7, vcc, 0, v11, vcc
	v_add_co_u32_e32 v12, vcc, 0x2840000, v10
	global_load_dwordx4 v[2:5], v[2:3], off offset:384
	s_nop 0
	global_load_dwordx4 v[6:9], v[6:7], off offset:384
	v_addc_co_u32_e32 v13, vcc, 0, v11, vcc
	v_add_co_u32_e32 v14, vcc, 0x2860000, v10
	s_nop 1
	v_addc_co_u32_e32 v15, vcc, 0, v11, vcc
	v_add_co_u32_e32 v20, vcc, 0x400000, v18
	global_load_dwordx4 v[10:13], v[12:13], off offset:384
	s_nop 0
	global_load_dwordx4 v[14:17], v[14:15], off offset:384
	v_addc_co_u32_e32 v21, vcc, 0, v19, vcc
	v_add_co_u32_e32 v26, vcc, 0x420000, v18
	s_nop 1
	v_addc_co_u32_e32 v27, vcc, 0, v19, vcc
	global_load_dwordx4 v[18:21], v[20:21], off offset:384
	s_nop 0
	global_load_dwordx4 v[26:29], v[26:27], off offset:384
.Lmydfe__1046:
	s_waitcnt lgkmcnt(0)
	v_mfma_f32_16x16x32_bf16 v[110:113], v[114:117], v[130:133], v[110:113]
	ds_read_b128 v[146:149], v226
	v_mfma_f32_16x16x32_bf16 v[106:109], v[114:117], v[134:137], v[106:109]
	ds_read_b128 v[150:153], v226 offset:2048
	v_mfma_f32_16x16x32_bf16 v[78:81], v[114:117], v[138:141], v[78:81]
	ds_read_b128 v[154:157], v226 offset:4096
	v_mfma_f32_16x16x32_bf16 v[74:77], v[114:117], v[142:145], v[74:77]
	ds_read_b128 v[158:161], v226 offset:6144
	v_mfma_f32_16x16x32_bf16 v[102:105], v[118:121], v[130:133], v[102:105]
	ds_read_b128 v[162:165], v227
	v_mfma_f32_16x16x32_bf16 v[98:101], v[118:121], v[134:137], v[98:101]
	ds_read_b128 v[234:237], v227 offset:2048
	v_mfma_f32_16x16x32_bf16 v[70:73], v[118:121], v[138:141], v[70:73]
	ds_read_b128 v[238:241], v227 offset:4096
	v_mfma_f32_16x16x32_bf16 v[66:69], v[118:121], v[142:145], v[66:69]
	ds_read_b128 v[242:245], v227 offset:6144
	v_mfma_f32_16x16x32_bf16 v[94:97], v[122:125], v[130:133], v[94:97]
	v_mfma_f32_16x16x32_bf16 v[90:93], v[122:125], v[134:137], v[90:93]
	v_mfma_f32_16x16x32_bf16 v[62:65], v[122:125], v[138:141], v[62:65]
	v_mfma_f32_16x16x32_bf16 v[58:61], v[122:125], v[142:145], v[58:61]
	v_mfma_f32_16x16x32_bf16 v[86:89], v[126:129], v[130:133], v[86:89]
	v_mfma_f32_16x16x32_bf16 v[82:85], v[126:129], v[134:137], v[82:85]
	v_mfma_f32_16x16x32_bf16 v[54:57], v[126:129], v[138:141], v[54:57]
	v_mfma_f32_16x16x32_bf16 v[50:53], v[126:129], v[142:145], v[50:53]
	s_branch .Lmyd_odd
.Lmyd_even:
	s_waitcnt lgkmcnt(0)
	s_barrier
	ds_read_b128 v[114:117], v224
	ds_read_b128 v[118:121], v224 offset:2048
	ds_read_b128 v[122:125], v224 offset:4096
	ds_read_b128 v[126:129], v224 offset:6144
	ds_read_b128 v[130:133], v225
	ds_read_b128 v[134:137], v225 offset:2048
	ds_read_b128 v[138:141], v225 offset:4096
	ds_read_b128 v[142:145], v225 offset:6144
	s_cmp_gt_u32 s13, 12
	s_cbranch_scc0 .Lmyd_ew6
	s_and_b64 vcc, exec, s[0:1]
	s_cbranch_vccnz .Lmyd_ew6
	s_waitcnt vmcnt(0)
.Lmyd_ew6:
	s_waitcnt vmcnt(6)
	v_mfma_f32_16x16x32_bf16 v[110:113], v[146:149], v[162:165], v[110:113]
	ds_write_b128 v222, v[2:5] offset:32768
	v_mfma_f32_16x16x32_bf16 v[106:109], v[146:149], v[234:237], v[106:109]
	ds_write_b128 v222, v[6:9] offset:40960
	v_mfma_f32_16x16x32_bf16 v[78:81], v[146:149], v[238:241], v[78:81]
	ds_write_b128 v222, v[10:13] offset:49152
	v_mfma_f32_16x16x32_bf16 v[74:77], v[146:149], v[242:245], v[74:77]
	ds_write_b128 v222, v[14:17] offset:57344
	v_mfma_f32_16x16x32_bf16 v[102:105], v[150:153], v[162:165], v[102:105]
	ds_write_b128 v228, v[18:21]
	v_mfma_f32_16x16x32_bf16 v[98:101], v[150:153], v[234:237], v[98:101]
	ds_write_b128 v228, v[26:29] offset:8192
	v_mfma_f32_16x16x32_bf16 v[70:73], v[150:153], v[238:241], v[70:73]
	v_mfma_f32_16x16x32_bf16 v[66:69], v[150:153], v[242:245], v[66:69]
	s_cmp_gt_u32 s13, 12
	s_mov_b64 s[2:3], -1
	s_cbranch_scc0 .Lmydse__1044
	s_andn2_b64 vcc, exec, s[0:1]
	s_cbranch_vccnz .Lmydse__1043
	global_load_dwordx4 v[6:9], v[184:185], off
	global_load_dwordx4 v[10:13], v[186:187], off
	global_load_dwordx4 v[2:5], v[180:181], off offset:128
	global_load_dwordx4 v[18:21], v[182:183], off offset:128
	global_load_dwordx4 v[14:17], v[188:189], off
	global_load_dwordx4 v[26:29], v[190:191], off

.Lmydse__1046:
	v_mfma_f32_16x16x32_bf16 v[94:97], v[154:157], v[162:165], v[94:97]
	v_mfma_f32_16x16x32_bf16 v[90:93], v[154:157], v[234:237], v[90:93]
	v_mfma_f32_16x16x32_bf16 v[62:65], v[154:157], v[238:241], v[62:65]
	v_mfma_f32_16x16x32_bf16 v[58:61], v[154:157], v[242:245], v[58:61]
	v_mfma_f32_16x16x32_bf16 v[86:89], v[158:161], v[162:165], v[86:89]
	v_mfma_f32_16x16x32_bf16 v[82:85], v[158:161], v[234:237], v[82:85]
	v_mfma_f32_16x16x32_bf16 v[54:57], v[158:161], v[238:241], v[54:57]
	v_mfma_f32_16x16x32_bf16 v[50:53], v[158:161], v[242:245], v[50:53]
	s_waitcnt lgkmcnt(0)
	v_mfma_f32_16x16x32_bf16 v[110:113], v[114:117], v[130:133], v[110:113]
	ds_read_b128 v[146:149], v226
	v_mfma_f32_16x16x32_bf16 v[106:109], v[114:117], v[134:137], v[106:109]
	ds_read_b128 v[150:153], v226 offset:2048
	v_mfma_f32_16x16x32_bf16 v[78:81], v[114:117], v[138:141], v[78:81]
	ds_read_b128 v[154:157], v226 offset:4096
	v_mfma_f32_16x16x32_bf16 v[74:77], v[114:117], v[142:145], v[74:77]
	ds_read_b128 v[158:161], v226 offset:6144
	v_mfma_f32_16x16x32_bf16 v[102:105], v[118:121], v[130:133], v[102:105]
	ds_read_b128 v[162:165], v227
	v_mfma_f32_16x16x32_bf16 v[98:101], v[118:121], v[134:137], v[98:101]
	ds_read_b128 v[234:237], v227 offset:2048
	v_mfma_f32_16x16x32_bf16 v[70:73], v[118:121], v[138:141], v[70:73]
	ds_read_b128 v[238:241], v227 offset:4096
	v_mfma_f32_16x16x32_bf16 v[66:69], v[118:121], v[142:145], v[66:69]
	ds_read_b128 v[242:245], v227 offset:6144
	v_mfma_f32_16x16x32_bf16 v[94:97], v[122:125], v[130:133], v[94:97]
	v_mfma_f32_16x16x32_bf16 v[90:93], v[122:125], v[134:137], v[90:93]
	v_mfma_f32_16x16x32_bf16 v[62:65], v[122:125], v[138:141], v[62:65]
	v_mfma_f32_16x16x32_bf16 v[58:61], v[122:125], v[142:145], v[58:61]
	v_mfma_f32_16x16x32_bf16 v[86:89], v[126:129], v[130:133], v[86:89]
	v_mfma_f32_16x16x32_bf16 v[82:85], v[126:129], v[134:137], v[82:85]
	v_mfma_f32_16x16x32_bf16 v[54:57], v[126:129], v[138:141], v[54:57]
	v_mfma_f32_16x16x32_bf16 v[50:53], v[126:129], v[142:145], v[50:53]
.Lmyd_odd:
	s_waitcnt lgkmcnt(0)
	s_barrier
	ds_read_b128 v[114:117], v224 offset:32768
	ds_read_b128 v[118:121], v224 offset:34816
	ds_read_b128 v[122:125], v224 offset:36864
	ds_read_b128 v[126:129], v224 offset:38912
	ds_read_b128 v[130:133], v229
	ds_read_b128 v[134:137], v229 offset:2048
	ds_read_b128 v[138:141], v229 offset:4096
	ds_read_b128 v[142:145], v229 offset:6144
	s_cmp_gt_u32 s13, 13
	s_cselect_b64 s[2:3], -1, 0
	s_and_b64 vcc, exec, s[2:3]
	s_cbranch_vccnz .Lmyd_oddlast
	s_waitcnt vmcnt(6)
	v_mfma_f32_16x16x32_bf16 v[110:113], v[146:149], v[162:165], v[110:113]
	ds_write_b128 v222, v[38:41]
	v_mfma_f32_16x16x32_bf16 v[106:109], v[146:149], v[234:237], v[106:109]
	ds_write_b128 v222, v[46:49] offset:8192
	v_mfma_f32_16x16x32_bf16 v[78:81], v[146:149], v[238:241], v[78:81]
	ds_write_b128 v222, v[34:37] offset:16384
	v_mfma_f32_16x16x32_bf16 v[74:77], v[146:149], v[242:245], v[74:77]
	ds_write_b128 v222, v[42:45] offset:24576
	v_mfma_f32_16x16x32_bf16 v[102:105], v[150:153], v[162:165], v[102:105]
	ds_write_b128 v223, v[22:25]
	v_mfma_f32_16x16x32_bf16 v[98:101], v[150:153], v[234:237], v[98:101]
	ds_write_b128 v223, v[30:33] offset:8192
	v_mfma_f32_16x16x32_bf16 v[70:73], v[150:153], v[238:241], v[70:73]
	v_mfma_f32_16x16x32_bf16 v[66:69], v[150:153], v[242:245], v[66:69]
	s_cmp_gt_u32 s13, 11
	s_mov_b64 s[4:5], -1
	s_cbranch_scc0 .Lmydso__1051
	s_andn2_b64 vcc, exec, s[0:1]
	s_cbranch_vccnz .Lmydso__1050
	global_load_dwordx4 v[46:49], v[192:193], off
	global_load_dwordx4 v[34:37], v[194:195], off
	global_load_dwordx4 v[38:41], v[180:181], off
	global_load_dwordx4 v[22:25], v[182:183], off
	global_load_dwordx4 v[42:45], v[196:197], off
	global_load_dwordx4 v[30:33], v[198:199], off

.Lmydso__1051:
	s_andn2_b64 vcc, exec, s[4:5]
	s_cbranch_vccnz .Lmyd_ocont
	v_lshl_add_u64 v[22:23], v[178:179], 0, v[174:175]
	v_add_co_u32_e32 v30, vcc, 0x2800000, v22
	v_lshl_add_u64 v[24:25], v[176:177], 0, v[174:175]
	s_nop 0
	v_addc_co_u32_e32 v31, vcc, 0, v23, vcc
	v_add_co_u32_e32 v32, vcc, 0x2820000, v22
	s_nop 1
	v_addc_co_u32_e32 v33, vcc, 0, v23, vcc
	global_load_dwordx4 v[38:41], v[30:31], off offset:512
	global_load_dwordx4 v[46:49], v[32:33], off offset:512
	v_add_co_u32_e32 v30, vcc, 0x2840000, v22
	s_nop 1
	v_addc_co_u32_e32 v31, vcc, 0, v23, vcc
	v_add_co_u32_e32 v22, vcc, 0x2860000, v22
	s_nop 1
	v_addc_co_u32_e32 v23, vcc, 0, v23, vcc
	global_load_dwordx4 v[34:37], v[30:31], off offset:512
	global_load_dwordx4 v[42:45], v[22:23], off offset:512
	v_add_co_u32_e32 v22, vcc, 0x400000, v24
	s_nop 1
	v_addc_co_u32_e32 v23, vcc, 0, v25, vcc
	v_add_co_u32_e32 v30, vcc, 0x420000, v24
	s_nop 1
	v_addc_co_u32_e32 v31, vcc, 0, v25, vcc
	global_load_dwordx4 v[22:25], v[22:23], off offset:512
	s_nop 0
	global_load_dwordx4 v[30:33], v[30:31], off offset:512
.Lmyd_ocont:
	v_mfma_f32_16x16x32_bf16 v[94:97], v[154:157], v[162:165], v[94:97]
	v_mfma_f32_16x16x32_bf16 v[90:93], v[154:157], v[234:237], v[90:93]
	v_mfma_f32_16x16x32_bf16 v[62:65], v[154:157], v[238:241], v[62:65]
	v_mfma_f32_16x16x32_bf16 v[58:61], v[154:157], v[242:245], v[58:61]
	v_mfma_f32_16x16x32_bf16 v[86:89], v[158:161], v[162:165], v[86:89]
	v_mfma_f32_16x16x32_bf16 v[82:85], v[158:161], v[234:237], v[82:85]
	v_mfma_f32_16x16x32_bf16 v[54:57], v[158:161], v[238:241], v[54:57]
	v_mfma_f32_16x16x32_bf16 v[50:53], v[158:161], v[242:245], v[50:53]
	s_waitcnt lgkmcnt(0)
	v_mfma_f32_16x16x32_bf16 v[110:113], v[114:117], v[130:133], v[110:113]
	ds_read_b128 v[146:149], v226 offset:32768
	v_mfma_f32_16x16x32_bf16 v[106:109], v[114:117], v[134:137], v[106:109]
	ds_read_b128 v[150:153], v226 offset:34816
	v_mfma_f32_16x16x32_bf16 v[78:81], v[114:117], v[138:141], v[78:81]
	ds_read_b128 v[154:157], v226 offset:36864
	v_mfma_f32_16x16x32_bf16 v[74:77], v[114:117], v[142:145], v[74:77]
	ds_read_b128 v[158:161], v226 offset:38912
	v_mfma_f32_16x16x32_bf16 v[102:105], v[118:121], v[130:133], v[102:105]
	ds_read_b128 v[162:165], v230
	v_mfma_f32_16x16x32_bf16 v[98:101], v[118:121], v[134:137], v[98:101]
	ds_read_b128 v[234:237], v230 offset:2048
	v_mfma_f32_16x16x32_bf16 v[70:73], v[118:121], v[138:141], v[70:73]
	ds_read_b128 v[238:241], v230 offset:4096
	v_mfma_f32_16x16x32_bf16 v[66:69], v[118:121], v[142:145], v[66:69]
	ds_read_b128 v[242:245], v230 offset:6144
	v_mfma_f32_16x16x32_bf16 v[94:97], v[122:125], v[130:133], v[94:97]
	v_mfma_f32_16x16x32_bf16 v[90:93], v[122:125], v[134:137], v[90:93]
	v_mfma_f32_16x16x32_bf16 v[62:65], v[122:125], v[138:141], v[62:65]
	v_mfma_f32_16x16x32_bf16 v[58:61], v[122:125], v[142:145], v[58:61]
	v_mfma_f32_16x16x32_bf16 v[86:89], v[126:129], v[130:133], v[86:89]
	v_mfma_f32_16x16x32_bf16 v[82:85], v[126:129], v[134:137], v[82:85]
	v_mfma_f32_16x16x32_bf16 v[54:57], v[126:129], v[138:141], v[54:57]
	v_mfma_f32_16x16x32_bf16 v[50:53], v[126:129], v[142:145], v[50:53]
	s_add_i32 s13, s13, 2
	v_lshl_add_u64 v[176:177], v[176:177], 0, s[74:75]
	v_lshl_add_u64 v[178:179], v[178:179], 0, s[74:75]
	s_branch .Lmyd_even
.Lmyd_oddlast:
	v_mfma_f32_16x16x32_bf16 v[110:113], v[146:149], v[162:165], v[110:113]
	v_mfma_f32_16x16x32_bf16 v[106:109], v[146:149], v[234:237], v[106:109]
	v_mfma_f32_16x16x32_bf16 v[78:81], v[146:149], v[238:241], v[78:81]
	v_mfma_f32_16x16x32_bf16 v[74:77], v[146:149], v[242:245], v[74:77]
	v_mfma_f32_16x16x32_bf16 v[102:105], v[150:153], v[162:165], v[102:105]
	v_mfma_f32_16x16x32_bf16 v[98:101], v[150:153], v[234:237], v[98:101]
	v_mfma_f32_16x16x32_bf16 v[70:73], v[150:153], v[238:241], v[70:73]
	v_mfma_f32_16x16x32_bf16 v[66:69], v[150:153], v[242:245], v[66:69]
	v_mfma_f32_16x16x32_bf16 v[94:97], v[154:157], v[162:165], v[94:97]
	v_mfma_f32_16x16x32_bf16 v[90:93], v[154:157], v[234:237], v[90:93]
	v_mfma_f32_16x16x32_bf16 v[62:65], v[154:157], v[238:241], v[62:65]
	v_mfma_f32_16x16x32_bf16 v[58:61], v[154:157], v[242:245], v[58:61]
	v_mfma_f32_16x16x32_bf16 v[86:89], v[158:161], v[162:165], v[86:89]
	v_mfma_f32_16x16x32_bf16 v[82:85], v[158:161], v[234:237], v[82:85]
	v_mfma_f32_16x16x32_bf16 v[54:57], v[158:161], v[238:241], v[54:57]
	v_mfma_f32_16x16x32_bf16 v[50:53], v[158:161], v[242:245], v[50:53]
	s_waitcnt lgkmcnt(0)
	v_mfma_f32_16x16x32_bf16 v[110:113], v[114:117], v[130:133], v[110:113]
	ds_read_b128 v[146:149], v226 offset:32768
	v_mfma_f32_16x16x32_bf16 v[106:109], v[114:117], v[134:137], v[106:109]
	ds_read_b128 v[150:153], v226 offset:34816
	v_mfma_f32_16x16x32_bf16 v[78:81], v[114:117], v[138:141], v[78:81]
	ds_read_b128 v[154:157], v226 offset:36864
	v_mfma_f32_16x16x32_bf16 v[74:77], v[114:117], v[142:145], v[74:77]
	ds_read_b128 v[158:161], v226 offset:38912
	v_mfma_f32_16x16x32_bf16 v[102:105], v[118:121], v[130:133], v[102:105]
	ds_read_b128 v[162:165], v230
	v_mfma_f32_16x16x32_bf16 v[98:101], v[118:121], v[134:137], v[98:101]
	ds_read_b128 v[234:237], v230 offset:2048
	v_mfma_f32_16x16x32_bf16 v[70:73], v[118:121], v[138:141], v[70:73]
	ds_read_b128 v[238:241], v230 offset:4096
	v_mfma_f32_16x16x32_bf16 v[66:69], v[118:121], v[142:145], v[66:69]
	ds_read_b128 v[242:245], v230 offset:6144
	v_mfma_f32_16x16x32_bf16 v[94:97], v[122:125], v[130:133], v[94:97]
	v_mfma_f32_16x16x32_bf16 v[90:93], v[122:125], v[134:137], v[90:93]
	v_mfma_f32_16x16x32_bf16 v[62:65], v[122:125], v[138:141], v[62:65]
	v_mfma_f32_16x16x32_bf16 v[58:61], v[122:125], v[142:145], v[58:61]
	v_mfma_f32_16x16x32_bf16 v[86:89], v[126:129], v[130:133], v[86:89]
	v_mfma_f32_16x16x32_bf16 v[82:85], v[126:129], v[134:137], v[82:85]
	v_mfma_f32_16x16x32_bf16 v[54:57], v[126:129], v[138:141], v[54:57]
	v_mfma_f32_16x16x32_bf16 v[50:53], v[126:129], v[142:145], v[50:53]
	s_add_i32 s13, s13, 2
	v_lshl_add_u64 v[176:177], v[176:177], 0, s[74:75]
	v_lshl_add_u64 v[178:179], v[178:179], 0, s[74:75]
	s_waitcnt lgkmcnt(0)
	v_mfma_f32_16x16x32_bf16 v[110:113], v[146:149], v[162:165], v[110:113]
	v_mfma_f32_16x16x32_bf16 v[106:109], v[146:149], v[234:237], v[106:109]
	v_mfma_f32_16x16x32_bf16 v[78:81], v[146:149], v[238:241], v[78:81]
	v_mfma_f32_16x16x32_bf16 v[74:77], v[146:149], v[242:245], v[74:77]
	v_mfma_f32_16x16x32_bf16 v[102:105], v[150:153], v[162:165], v[102:105]
	v_mfma_f32_16x16x32_bf16 v[98:101], v[150:153], v[234:237], v[98:101]
	v_mfma_f32_16x16x32_bf16 v[70:73], v[150:153], v[238:241], v[70:73]
	v_mfma_f32_16x16x32_bf16 v[66:69], v[150:153], v[242:245], v[66:69]
	v_mfma_f32_16x16x32_bf16 v[94:97], v[154:157], v[162:165], v[94:97]
	v_mfma_f32_16x16x32_bf16 v[90:93], v[154:157], v[234:237], v[90:93]
	v_mfma_f32_16x16x32_bf16 v[62:65], v[154:157], v[238:241], v[62:65]
	v_mfma_f32_16x16x32_bf16 v[58:61], v[154:157], v[242:245], v[58:61]
	v_mfma_f32_16x16x32_bf16 v[86:89], v[158:161], v[162:165], v[86:89]
	v_mfma_f32_16x16x32_bf16 v[82:85], v[158:161], v[234:237], v[82:85]
	v_mfma_f32_16x16x32_bf16 v[54:57], v[158:161], v[238:241], v[54:57]
	v_mfma_f32_16x16x32_bf16 v[50:53], v[158:161], v[242:245], v[50:53]
	s_and_b64 vcc, exec, s[2:3]
	s_nop 7
	s_branch .LBB0_1053

.LBB0_1221:
	ds_read_b128 v[116:119], v175
	ds_read_b128 v[230:233], v175 offset:4096
	ds_read_b128 v[234:237], v176
	ds_read_b128 v[238:241], v176 offset:4096
	ds_read_b128 v[242:245], v177
	ds_read_b128 v[246:249], v177 offset:4096
	v_mov_b32_e32 v147, v146
	v_pk_mul_f32 v[94:95], v[146:147], v[94:95]
	v_pk_mul_f32 v[92:93], v[156:157], v[92:93]
	v_pk_mul_f32 v[98:99], v[146:147], v[98:99]
	v_pk_mul_f32 v[96:97], v[156:157], v[96:97]
	s_add_i32 s20, s20, -1
	s_cmp_eq_u32 s21, 64
	s_mov_b32 s9, s21
	s_waitcnt lgkmcnt(5)
	v_mfma_f32_16x16x32_bf16 v[92:95], v[116:119], v[112:115], v[92:95]
	s_waitcnt lgkmcnt(4)
	v_mfma_f32_16x16x32_bf16 v[96:99], v[230:233], v[112:115], v[96:99]
	ds_read_b128 v[116:119], v178
	ds_read_b128 v[230:233], v178 offset:4096
	s_waitcnt lgkmcnt(5)
	v_mfma_f32_16x16x32_bf16 v[92:95], v[234:237], v[108:111], v[92:95]
	s_waitcnt lgkmcnt(4)
	v_mfma_f32_16x16x32_bf16 v[96:99], v[238:241], v[108:111], v[96:99]
	s_waitcnt lgkmcnt(3)
	v_mfma_f32_16x16x32_bf16 v[92:95], v[242:245], v[104:107], v[92:95]
	s_waitcnt lgkmcnt(2)
	v_mfma_f32_16x16x32_bf16 v[96:99], v[246:249], v[104:107], v[96:99]
	s_waitcnt lgkmcnt(1)
	v_mfma_f32_16x16x32_bf16 v[92:95], v[116:119], v[100:103], v[92:95]
	s_waitcnt lgkmcnt(0)
	v_mfma_f32_16x16x32_bf16 v[96:99], v[230:233], v[100:103], v[96:99]
	s_cbranch_scc1 .LBB0_1217

.LBB0_1226:
	s_cmp_gt_u32 s13, 1
	s_cselect_b64 s[14:15], -1, 0
	s_and_b32 s12, s13, 1
	s_cmp_lt_u32 s13, 2
	s_mul_i32 s22, s12, 0x2100
	s_cbranch_scc1 .Lscan_nl
	s_waitcnt vmcnt(13)
	v_add_u32_e32 v0, v125, v163
	ds_write_b128 v194, v[44:47]
	ds_write_b128 v195, v[52:55]
	ds_write_b128 v196, v[56:59]
	ds_write_b128 v197, v[60:63]
	ds_write_b128 v198, v[48:51]
	ds_write_b128 v199, v[64:67]
	ds_write_b128 v201, v[84:87]
	ds_write_b128 v220, v[88:91]
	ds_write_b128 v0, v[80:83]
	v_add_u32_e32 v0, v125, v165
	ds_write_b128 v0, v[76:79] offset:1024
	v_add_u32_e32 v0, v125, v169
	ds_write_b128 v0, v[72:75] offset:2048
	v_add_u32_e32 v0, v125, v173
	ds_write_b128 v0, v[68:71] offset:3072
	s_and_saveexec_b64 s[10:11], s[2:3]
	ds_write_b128 v137, v[40:43]
	s_or_b64 exec, exec, s[10:11]
	v_and_b32_sdwa v3, v92, v204 dst_sel:DWORD dst_unused:UNUSED_PAD src0_sel:WORD_1 src1_sel:DWORD
	v_add3_u32 v100, v92, v3, s33
	v_and_b32_sdwa v3, v95, v204 dst_sel:DWORD dst_unused:UNUSED_PAD src0_sel:WORD_1 src1_sel:DWORD
	v_and_b32_sdwa v101, v93, v204 dst_sel:DWORD dst_unused:UNUSED_PAD src0_sel:WORD_1 src1_sel:DWORD
	v_and_b32_sdwa v2, v94, v204 dst_sel:DWORD dst_unused:UNUSED_PAD src0_sel:WORD_1 src1_sel:DWORD
	v_add3_u32 v3, v95, v3, s33
	v_add3_u32 v101, v93, v101, s33
	v_add3_u32 v2, v94, v2, s33
	v_and_b32_e32 v3, 0xffff0000, v3
	v_and_b32_e32 v101, 0xffff0000, v101
	v_or_b32_sdwa v3, v3, v2 dst_sel:DWORD dst_unused:UNUSED_PAD src0_sel:DWORD src1_sel:WORD_1
	v_or_b32_sdwa v2, v101, v100 dst_sel:DWORD dst_unused:UNUSED_PAD src0_sel:DWORD src1_sel:WORD_1
	v_and_b32_sdwa v101, v96, v204 dst_sel:DWORD dst_unused:UNUSED_PAD src0_sel:WORD_1 src1_sel:DWORD
	v_add3_u32 v102, v96, v101, s33
	v_and_b32_sdwa v101, v99, v204 dst_sel:DWORD dst_unused:UNUSED_PAD src0_sel:WORD_1 src1_sel:DWORD
	v_and_b32_sdwa v103, v97, v204 dst_sel:DWORD dst_unused:UNUSED_PAD src0_sel:WORD_1 src1_sel:DWORD
	v_and_b32_sdwa v100, v98, v204 dst_sel:DWORD dst_unused:UNUSED_PAD src0_sel:WORD_1 src1_sel:DWORD
	v_add3_u32 v101, v99, v101, s33
	v_add3_u32 v103, v97, v103, s33
	v_add3_u32 v100, v98, v100, s33
	v_and_b32_e32 v101, 0xffff0000, v101
	v_and_b32_e32 v103, 0xffff0000, v103
	v_add_u32_e32 v0, s22, v179
	v_or_b32_sdwa v101, v101, v100 dst_sel:DWORD dst_unused:UNUSED_PAD src0_sel:DWORD src1_sel:WORD_1
	v_or_b32_sdwa v100, v103, v102 dst_sel:DWORD dst_unused:UNUSED_PAD src0_sel:DWORD src1_sel:WORD_1
	ds_write2_b64 v0, v[2:3], v[100:101] offset1:4
.LBB0_1230:
	s_lshl_b32 s23, s12, 11
	s_and_saveexec_b64 s[10:11], s[0:1]
	s_cbranch_execz .LBB0_1232
	v_lshl_add_u32 v0, s23, 1, v135
	ds_write_b128 v0, v[20:23]

.Lscan_nl:
	s_waitcnt vmcnt(0)
	s_branch .LBB0_1230

.LBB0_1242:
	s_or_b64 exec, exec, s[16:17]
	v_lshl_add_u32 v0, s23, 1, v158
	v_lshl_add_u32 v2, v159, 1, v0
	s_waitcnt lgkmcnt(0)
	s_barrier
	v_lshl_add_u32 v3, v160, 1, v0
	ds_read_b128 v[112:115], v2
	ds_read_b128 v[108:111], v3
	v_lshl_add_u32 v2, v161, 1, v0
	v_lshl_add_u32 v0, v162, 1, v0
	ds_read_b128 v[104:107], v2
	ds_read_b128 v[100:103], v0
	s_andn2_b64 vcc, exec, s[14:15]
	s_cbranch_vccnz .LBB0_1248
	s_setprio 1
	v_add_u32_e32 v0, s22, v181
	v_add_u32_e32 v2, v180, v163
	v_add_u32_e32 v3, v180, v165
	ds_read_b128 v[238:241], v2
	ds_read_b128 v[242:245], v0
	ds_read_b128 v[246:249], v3
	ds_read_b128 v[116:119], v0 offset:64
	v_add_u32_e32 v2, v180, v169
	v_add_u32_e32 v3, v180, v173
	s_waitcnt lgkmcnt(2)
	v_mfma_f32_16x16x32_bf16 v[234:237], v[238:241], v[242:245], 0
	ds_read_b128 v[238:241], v2
	ds_read_b128 v[242:245], v0 offset:128
	s_waitcnt lgkmcnt(2)
	v_mfma_f32_16x16x32_bf16 v[230:233], v[246:249], v[116:119], 0
	ds_read_b128 v[246:249], v3
	ds_read_b128 v[116:119], v0 offset:192
	s_waitcnt lgkmcnt(2)
	v_mfma_f32_16x16x32_bf16 v[234:237], v[238:241], v[242:245], v[234:237]
	ds_read_b128 v[238:241], v221
	ds_read_b128 v[242:245], v0 offset:256
	s_waitcnt lgkmcnt(2)
	v_mfma_f32_16x16x32_bf16 v[230:233], v[246:249], v[116:119], v[230:233]
	ds_read_b128 v[246:249], v222
	ds_read_b128 v[116:119], v0 offset:320
	s_waitcnt lgkmcnt(2)
	v_mfma_f32_16x16x32_bf16 v[234:237], v[238:241], v[242:245], v[234:237]
	ds_read_b128 v[238:241], v223
	ds_read_b128 v[242:245], v0 offset:384
	s_waitcnt lgkmcnt(2)
	v_mfma_f32_16x16x32_bf16 v[230:233], v[246:249], v[116:119], v[230:233]
	ds_read_b128 v[246:249], v224
	ds_read_b128 v[116:119], v0 offset:448
	s_waitcnt lgkmcnt(2)
	v_mfma_f32_16x16x32_bf16 v[234:237], v[238:241], v[242:245], v[234:237]
	ds_read_b128 v[238:241], v182
	ds_read_b128 v[242:245], v183
	s_waitcnt lgkmcnt(2)
	v_mfma_f32_16x16x32_bf16 v[230:233], v[246:249], v[116:119], v[230:233]
	ds_read_b128 v[246:249], v184
	s_waitcnt lgkmcnt(2)
	v_mfma_f32_16x16x32_bf16 v[116:119], v[238:241], v[112:115], 0
	ds_read_b128 v[238:241], v185
	s_waitcnt lgkmcnt(2)
	v_mfma_f32_16x16x32_bf16 v[116:119], v[242:245], v[108:111], v[116:119]
	s_waitcnt lgkmcnt(1)
	v_mfma_f32_16x16x32_bf16 v[116:119], v[246:249], v[104:107], v[116:119]
	s_waitcnt lgkmcnt(0)
	v_mfma_f32_16x16x32_bf16 v[116:119], v[238:241], v[100:103], v[116:119]
	s_setprio 0
	v_add_f32_e32 v0, v234, v230
	s_nop 5
	v_fma_f32 v3, v226, v0, v116
	v_add_f32_e32 v0, v235, v231
	v_fma_f32 v2, v227, v0, v117
	v_add_f32_e32 v0, v236, v232
	v_add_f32_e32 v116, v237, v233
	v_fma_f32 v0, v228, v0, v118
	v_fmac_f32_e32 v119, v229, v116
	v_mul_f32_e32 v116, v3, v3
	v_mul_f32_e32 v118, v2, v2
	v_mul_f32_e32 v141, v0, v0
	v_mul_f32_e32 v230, v119, v119
	v_mov_b32_dpp v116, v116 quad_perm:[1,0,3,2] row_mask:0xf bank_mask:0xf bound_ctrl:1
	v_mov_b32_dpp v118, v118 quad_perm:[1,0,3,2] row_mask:0xf bank_mask:0xf bound_ctrl:1
	v_mov_b32_dpp v141, v141 quad_perm:[1,0,3,2] row_mask:0xf bank_mask:0xf bound_ctrl:1
	v_mov_b32_dpp v230, v230 quad_perm:[1,0,3,2] row_mask:0xf bank_mask:0xf bound_ctrl:1
	v_fmac_f32_e32 v116, v3, v3
	v_fmac_f32_e32 v118, v2, v2
	v_fmac_f32_e32 v141, v0, v0
	v_fmac_f32_e32 v230, v119, v119
	v_add_f32_dpp v116, v116, v116 quad_perm:[2,3,0,1] row_mask:0xf bank_mask:0xf bound_ctrl:1
	v_add_f32_dpp v118, v118, v118 quad_perm:[2,3,0,1] row_mask:0xf bank_mask:0xf bound_ctrl:1
	v_add_f32_dpp v141, v141, v141 quad_perm:[2,3,0,1] row_mask:0xf bank_mask:0xf bound_ctrl:1
	v_add_f32_dpp v230, v230, v230 quad_perm:[2,3,0,1] row_mask:0xf bank_mask:0xf bound_ctrl:1
	v_add_f32_dpp v116, v116, v116 row_half_mirror row_mask:0xf bank_mask:0xf bound_ctrl:1
	v_add_f32_dpp v118, v118, v118 row_half_mirror row_mask:0xf bank_mask:0xf bound_ctrl:1
	v_add_f32_dpp v141, v141, v141 row_half_mirror row_mask:0xf bank_mask:0xf bound_ctrl:1
	v_add_f32_dpp v230, v230, v230 row_half_mirror row_mask:0xf bank_mask:0xf bound_ctrl:1
	v_mov_b32_dpp v117, v116 row_mirror row_mask:0xf bank_mask:0xf bound_ctrl:1
	v_mov_b32_dpp v139, v118 row_mirror row_mask:0xf bank_mask:0xf bound_ctrl:1
	v_mov_b32_dpp v147, v141 row_mirror row_mask:0xf bank_mask:0xf bound_ctrl:1
	v_mov_b32_dpp v231, v230 row_mirror row_mask:0xf bank_mask:0xf bound_ctrl:1
	s_and_saveexec_b64 s[14:15], s[4:5]
	s_cbranch_execz .LBB0_1245
	s_ashr_i32 s9, s8, 31
	s_lshl_b64 s[16:17], s[8:9], 9
	v_lshl_add_u64 v[232:233], v[154:155], 0, s[16:17]
	v_add_f32_e32 v116, v116, v117
	v_add_f32_e32 v230, v230, v231
	v_add_f32_e32 v141, v141, v147
	v_add_f32_e32 v118, v118, v139
	global_store_dword v[232:233], v116, off
	global_store_dword v[232:233], v118, off offset:512
	global_store_dword v[232:233], v141, off offset:1024
	global_store_dword v[232:233], v230, off offset:1536
.LBB0_1245:
	s_or_b64 exec, exec, s[14:15]
	ds_read_u16 v116, v225
	ds_read_u16 v117, v225 offset:32
	ds_read_u16 v118, v225 offset:64
	ds_read_u16 v141, v225 offset:96
	s_waitcnt lgkmcnt(3)
	v_lshlrev_b32_e32 v116, 16, v116
	v_mul_f32_e32 v3, v3, v116
	v_bfe_u32 v116, v3, 16, 1
	v_add3_u32 v3, v3, v116, s33
	ds_write_b16_d16_hi v225, v3
	s_waitcnt lgkmcnt(3)
	v_lshlrev_b32_e32 v3, 16, v117
	v_mul_f32_e32 v2, v2, v3
	v_bfe_u32 v3, v2, 16, 1
	v_add3_u32 v2, v2, v3, s33
	ds_write_b16_d16_hi v225, v2 offset:32
	s_waitcnt lgkmcnt(3)
	v_lshlrev_b32_e32 v2, 16, v118
	v_mul_f32_e32 v0, v0, v2
	v_bfe_u32 v2, v0, 16, 1
	v_add3_u32 v0, v0, v2, s33
	ds_write_b16_d16_hi v225, v0 offset:64
	s_waitcnt lgkmcnt(3)
	v_lshlrev_b32_e32 v0, 16, v141
	v_mul_f32_e32 v0, v119, v0
	v_bfe_u32 v2, v0, 16, 1
	v_add3_u32 v0, v0, v2, s33
	ds_write_b16_d16_hi v225, v0 offset:96
	s_and_saveexec_b64 s[14:15], s[2:3]
	s_cbranch_execz .LBB0_1247
	ds_read_b128 v[116:119], v137
	s_ashr_i32 s9, s8, 31
	s_lshl_b64 s[8:9], s[8:9], 12
	v_lshl_add_u64 v[2:3], v[152:153], 0, s[8:9]
	s_waitcnt lgkmcnt(0)
	global_store_dwordx4 v[2:3], v[116:119], off
.LBB0_1247:
	s_or_b64 exec, exec, s[14:15]
	s_andn2_b64 vcc, exec, s[12:13]
	s_cbranch_vccnz .Lscan_w0
	s_waitcnt vmcnt(18)
	s_branch .Lscan_kw
.LBB0_1248:
	s_andn2_b64 vcc, exec, s[12:13]
.Lscan_w0:
	s_waitcnt vmcnt(0)
.Lscan_kw:
	ds_write_b128 v164, v[4:7]
	ds_write_b128 v168, v[8:11] offset:1024
	ds_write_b128 v172, v[12:15] offset:2048
	ds_write_b128 v174, v[16:19] offset:3072
	ds_write_b128 v164, v[24:27] offset:4096
	ds_write_b128 v168, v[28:31] offset:5120
	ds_write_b128 v172, v[32:35] offset:6144
	ds_write_b128 v174, v[36:39] offset:7168
	s_cbranch_vccnz .LBB0_1221
	s_ashr_i32 s11, s10, 31
	v_lshl_add_u64 v[2:3], s[10:11], 1, v[142:143]
	v_add_co_u32_e32 v8, vcc, 0x10000, v2
	s_nop 1
	v_addc_co_u32_e32 v9, vcc, 0, v3, vcc
	v_add_co_u32_e32 v12, vcc, 0x21000, v2
	global_load_dwordx4 v[4:7], v[2:3], off
	s_nop 0
	global_load_dwordx4 v[8:11], v[8:9], off offset:2048
	v_addc_co_u32_e32 v13, vcc, 0, v3, vcc
	v_add_co_u32_e32 v16, vcc, 0x31000, v2
	s_nop 1
	v_addc_co_u32_e32 v17, vcc, 0, v3, vcc
	v_add_co_u32_e32 v24, vcc, 0x42000, v2
	global_load_dwordx4 v[12:15], v[12:13], off
	s_nop 0
	global_load_dwordx4 v[16:19], v[16:17], off offset:2048
	v_addc_co_u32_e32 v25, vcc, 0, v3, vcc
	v_add_co_u32_e32 v28, vcc, 0x52000, v2
	s_nop 1
	v_addc_co_u32_e32 v29, vcc, 0, v3, vcc
	v_add_co_u32_e32 v32, vcc, 0x63000, v2
	global_load_dwordx4 v[24:27], v[24:25], off
	s_nop 0
	global_load_dwordx4 v[28:31], v[28:29], off offset:2048
	v_addc_co_u32_e32 v33, vcc, 0, v3, vcc
	v_add_co_u32_e32 v2, vcc, 0x73000, v2
	s_nop 1
	v_addc_co_u32_e32 v3, vcc, 0, v3, vcc
	global_load_dwordx4 v[32:35], v[32:33], off
	s_nop 0
	global_load_dwordx4 v[36:39], v[2:3], off offset:2048
	s_branch .LBB0_1221

.LBB0_1364:
	s_waitcnt lgkmcnt(0)
	s_barrier
	ds_read_b128 v[114:117], v224
	ds_read_b128 v[118:121], v224 offset:2048
	ds_read_b128 v[122:125], v224 offset:4096
	ds_read_b128 v[126:129], v224 offset:6144
	ds_read_b128 v[130:133], v225
	ds_read_b128 v[134:137], v225 offset:2048
	ds_read_b128 v[138:141], v225 offset:4096
	ds_read_b128 v[142:145], v225 offset:6144
	s_waitcnt vmcnt(6)
	ds_write_b128 v222, v[6:9] offset:32768
	ds_write_b128 v222, v[10:13] offset:40960
	ds_write_b128 v222, v[18:21] offset:49152
	ds_write_b128 v222, v[22:25] offset:57344
	ds_write_b128 v228, v[26:29]
	ds_write_b128 v228, v[34:37] offset:8192
	s_cmp_gt_u32 s13, 28
	s_mov_b64 s[4:5], -1
	s_cbranch_scc0 .Lmyefe__1368
	s_andn2_b64 vcc, exec, s[2:3]
	s_cbranch_vccnz .Lmyefe__1367
	global_load_dwordx4 v[10:13], v[186:187], off
	global_load_dwordx4 v[18:21], v[188:189], off
	global_load_dwordx4 v[6:9], v[182:183], off offset:128
	global_load_dwordx4 v[26:29], v[184:185], off offset:128
	global_load_dwordx4 v[22:25], v[190:191], off
	global_load_dwordx4 v[34:37], v[192:193], off

.Lmyefe__1368:
	s_andn2_b64 vcc, exec, s[4:5]
	s_cbranch_vccnz .Lmyefe__1370
	v_lshl_add_u64 v[18:19], v[180:181], 0, v[176:177]
	v_add_co_u32_e32 v6, vcc, 0xab00000, v18
	v_lshl_add_u64 v[26:27], v[178:179], 0, v[176:177]
	v_addc_co_u32_e32 v7, vcc, 0, v19, vcc
	v_add_co_u32_e32 v10, vcc, 0xab40000, v18
	s_nop 1
	v_addc_co_u32_e32 v11, vcc, 0, v19, vcc
	v_add_co_u32_e32 v20, vcc, 0xab80000, v18
	global_load_dwordx4 v[6:9], v[6:7], off offset:384
	s_nop 0
	global_load_dwordx4 v[10:13], v[10:11], off offset:384
	v_addc_co_u32_e32 v21, vcc, 0, v19, vcc
	v_add_co_u32_e32 v22, vcc, 0xabc0000, v18
	s_nop 1
	v_addc_co_u32_e32 v23, vcc, 0, v19, vcc
	v_add_co_u32_e32 v28, vcc, 0x1400000, v26
	global_load_dwordx4 v[18:21], v[20:21], off offset:384
	s_nop 0
	global_load_dwordx4 v[22:25], v[22:23], off offset:384
	v_addc_co_u32_e32 v29, vcc, 0, v27, vcc
	v_add_co_u32_e32 v34, vcc, 0x1440000, v26
	s_nop 1
	v_addc_co_u32_e32 v35, vcc, 0, v27, vcc
	global_load_dwordx4 v[26:29], v[28:29], off offset:384
	s_nop 0
	global_load_dwordx4 v[34:37], v[34:35], off offset:384
.Lmyefe__1370:
	s_waitcnt lgkmcnt(0)
	v_mfma_f32_16x16x32_bf16 v[110:113], v[114:117], v[130:133], v[110:113]
	ds_read_b128 v[146:149], v226
	v_mfma_f32_16x16x32_bf16 v[106:109], v[114:117], v[134:137], v[106:109]
	ds_read_b128 v[150:153], v226 offset:2048
	v_mfma_f32_16x16x32_bf16 v[102:105], v[114:117], v[138:141], v[102:105]
	ds_read_b128 v[154:157], v226 offset:4096
	v_mfma_f32_16x16x32_bf16 v[98:101], v[114:117], v[142:145], v[98:101]
	ds_read_b128 v[158:161], v226 offset:6144
	v_mfma_f32_16x16x32_bf16 v[94:97], v[118:121], v[130:133], v[94:97]
	ds_read_b128 v[162:165], v227
	v_mfma_f32_16x16x32_bf16 v[90:93], v[118:121], v[134:137], v[90:93]
	ds_read_b128 v[166:169], v227 offset:2048
	v_mfma_f32_16x16x32_bf16 v[86:89], v[118:121], v[138:141], v[86:89]
	ds_read_b128 v[234:237], v227 offset:4096
	v_mfma_f32_16x16x32_bf16 v[82:85], v[118:121], v[142:145], v[82:85]
	ds_read_b128 v[238:241], v227 offset:6144
	v_mfma_f32_16x16x32_bf16 v[78:81], v[122:125], v[130:133], v[78:81]
	v_mfma_f32_16x16x32_bf16 v[74:77], v[122:125], v[134:137], v[74:77]
	v_mfma_f32_16x16x32_bf16 v[70:73], v[122:125], v[138:141], v[70:73]
	v_mfma_f32_16x16x32_bf16 v[66:69], v[122:125], v[142:145], v[66:69]
	v_mfma_f32_16x16x32_bf16 v[62:65], v[126:129], v[130:133], v[62:65]
	v_mfma_f32_16x16x32_bf16 v[58:61], v[126:129], v[134:137], v[58:61]
	v_mfma_f32_16x16x32_bf16 v[54:57], v[126:129], v[138:141], v[54:57]
	v_mfma_f32_16x16x32_bf16 v[50:53], v[126:129], v[142:145], v[50:53]
	s_branch .Lmye_odd
.Lmye_even:
	s_waitcnt lgkmcnt(0)
	s_barrier
	ds_read_b128 v[114:117], v224
	ds_read_b128 v[118:121], v224 offset:2048
	ds_read_b128 v[122:125], v224 offset:4096
	ds_read_b128 v[126:129], v224 offset:6144
	ds_read_b128 v[130:133], v225
	ds_read_b128 v[134:137], v225 offset:2048
	ds_read_b128 v[138:141], v225 offset:4096
	ds_read_b128 v[142:145], v225 offset:6144
	s_cmp_gt_u32 s13, 28
	s_cbranch_scc0 .Lmye_ew6
	s_and_b64 vcc, exec, s[2:3]
	s_cbranch_vccnz .Lmye_ew6
	s_waitcnt vmcnt(0)
.Lmye_ew6:
	s_waitcnt vmcnt(6)
	v_mfma_f32_16x16x32_bf16 v[110:113], v[146:149], v[162:165], v[110:113]
	ds_write_b128 v222, v[6:9] offset:32768
	v_mfma_f32_16x16x32_bf16 v[106:109], v[146:149], v[166:169], v[106:109]
	ds_write_b128 v222, v[10:13] offset:40960
	v_mfma_f32_16x16x32_bf16 v[102:105], v[146:149], v[234:237], v[102:105]
	ds_write_b128 v222, v[18:21] offset:49152
	v_mfma_f32_16x16x32_bf16 v[98:101], v[146:149], v[238:241], v[98:101]
	ds_write_b128 v222, v[22:25] offset:57344
	v_mfma_f32_16x16x32_bf16 v[94:97], v[150:153], v[162:165], v[94:97]
	ds_write_b128 v228, v[26:29]
	v_mfma_f32_16x16x32_bf16 v[90:93], v[150:153], v[166:169], v[90:93]
	ds_write_b128 v228, v[34:37] offset:8192
	v_mfma_f32_16x16x32_bf16 v[86:89], v[150:153], v[234:237], v[86:89]
	v_mfma_f32_16x16x32_bf16 v[82:85], v[150:153], v[238:241], v[82:85]
	s_cmp_gt_u32 s13, 28
	s_mov_b64 s[4:5], -1
	s_cbranch_scc0 .Lmyese__1368
	s_andn2_b64 vcc, exec, s[2:3]
	s_cbranch_vccnz .Lmyese__1367
	global_load_dwordx4 v[10:13], v[186:187], off
	global_load_dwordx4 v[18:21], v[188:189], off
	global_load_dwordx4 v[6:9], v[182:183], off offset:128
	global_load_dwordx4 v[26:29], v[184:185], off offset:128
	global_load_dwordx4 v[22:25], v[190:191], off
	global_load_dwordx4 v[34:37], v[192:193], off

.Lmyese__1370:
	v_mfma_f32_16x16x32_bf16 v[78:81], v[154:157], v[162:165], v[78:81]
	v_mfma_f32_16x16x32_bf16 v[74:77], v[154:157], v[166:169], v[74:77]
	v_mfma_f32_16x16x32_bf16 v[70:73], v[154:157], v[234:237], v[70:73]
	v_mfma_f32_16x16x32_bf16 v[66:69], v[154:157], v[238:241], v[66:69]
	v_mfma_f32_16x16x32_bf16 v[62:65], v[158:161], v[162:165], v[62:65]
	v_mfma_f32_16x16x32_bf16 v[58:61], v[158:161], v[166:169], v[58:61]
	v_mfma_f32_16x16x32_bf16 v[54:57], v[158:161], v[234:237], v[54:57]
	v_mfma_f32_16x16x32_bf16 v[50:53], v[158:161], v[238:241], v[50:53]
	s_waitcnt lgkmcnt(0)
	v_mfma_f32_16x16x32_bf16 v[110:113], v[114:117], v[130:133], v[110:113]
	ds_read_b128 v[146:149], v226
	v_mfma_f32_16x16x32_bf16 v[106:109], v[114:117], v[134:137], v[106:109]
	ds_read_b128 v[150:153], v226 offset:2048
	v_mfma_f32_16x16x32_bf16 v[102:105], v[114:117], v[138:141], v[102:105]
	ds_read_b128 v[154:157], v226 offset:4096
	v_mfma_f32_16x16x32_bf16 v[98:101], v[114:117], v[142:145], v[98:101]
	ds_read_b128 v[158:161], v226 offset:6144
	v_mfma_f32_16x16x32_bf16 v[94:97], v[118:121], v[130:133], v[94:97]
	ds_read_b128 v[162:165], v227
	v_mfma_f32_16x16x32_bf16 v[90:93], v[118:121], v[134:137], v[90:93]
	ds_read_b128 v[166:169], v227 offset:2048
	v_mfma_f32_16x16x32_bf16 v[86:89], v[118:121], v[138:141], v[86:89]
	ds_read_b128 v[234:237], v227 offset:4096
	v_mfma_f32_16x16x32_bf16 v[82:85], v[118:121], v[142:145], v[82:85]
	ds_read_b128 v[238:241], v227 offset:6144
	v_mfma_f32_16x16x32_bf16 v[78:81], v[122:125], v[130:133], v[78:81]
	v_mfma_f32_16x16x32_bf16 v[74:77], v[122:125], v[134:137], v[74:77]
	v_mfma_f32_16x16x32_bf16 v[70:73], v[122:125], v[138:141], v[70:73]
	v_mfma_f32_16x16x32_bf16 v[66:69], v[122:125], v[142:145], v[66:69]
	v_mfma_f32_16x16x32_bf16 v[62:65], v[126:129], v[130:133], v[62:65]
	v_mfma_f32_16x16x32_bf16 v[58:61], v[126:129], v[134:137], v[58:61]
	v_mfma_f32_16x16x32_bf16 v[54:57], v[126:129], v[138:141], v[54:57]
	v_mfma_f32_16x16x32_bf16 v[50:53], v[126:129], v[142:145], v[50:53]
.Lmye_odd:
	s_waitcnt lgkmcnt(0)
	s_barrier
	ds_read_b128 v[114:117], v224 offset:32768
	ds_read_b128 v[118:121], v224 offset:34816
	ds_read_b128 v[122:125], v224 offset:36864
	ds_read_b128 v[126:129], v224 offset:38912
	ds_read_b128 v[130:133], v229
	ds_read_b128 v[134:137], v229 offset:2048
	ds_read_b128 v[138:141], v229 offset:4096
	ds_read_b128 v[142:145], v229 offset:6144
	s_cmp_gt_u32 s13, 29
	s_cselect_b64 s[4:5], -1, 0
	s_and_b64 vcc, exec, s[4:5]
	s_cbranch_vccnz .Lmye_oddlast
	s_waitcnt vmcnt(6)
	v_mfma_f32_16x16x32_bf16 v[110:113], v[146:149], v[162:165], v[110:113]
	ds_write_b128 v222, v[2:5]
	v_mfma_f32_16x16x32_bf16 v[106:109], v[146:149], v[166:169], v[106:109]
	ds_write_b128 v222, v[14:17] offset:8192
	v_mfma_f32_16x16x32_bf16 v[102:105], v[146:149], v[234:237], v[102:105]
	ds_write_b128 v222, v[30:33] offset:16384
	v_mfma_f32_16x16x32_bf16 v[98:101], v[146:149], v[238:241], v[98:101]
	ds_write_b128 v222, v[38:41] offset:24576
	v_mfma_f32_16x16x32_bf16 v[94:97], v[150:153], v[162:165], v[94:97]
	ds_write_b128 v223, v[42:45]
	v_mfma_f32_16x16x32_bf16 v[90:93], v[150:153], v[166:169], v[90:93]
	ds_write_b128 v223, v[46:49] offset:8192
	v_mfma_f32_16x16x32_bf16 v[86:89], v[150:153], v[234:237], v[86:89]
	v_mfma_f32_16x16x32_bf16 v[82:85], v[150:153], v[238:241], v[82:85]
	s_cmp_gt_u32 s13, 27
	s_mov_b64 s[6:7], -1
	s_cbranch_scc0 .Lmyeso__1375
	s_andn2_b64 vcc, exec, s[2:3]
	s_cbranch_vccnz .Lmyeso__1374
	global_load_dwordx4 v[14:17], v[194:195], off
	global_load_dwordx4 v[30:33], v[196:197], off
	global_load_dwordx4 v[2:5], v[182:183], off
	global_load_dwordx4 v[42:45], v[184:185], off
	global_load_dwordx4 v[38:41], v[198:199], off
	global_load_dwordx4 v[46:49], v[200:201], off

.Lmyeso__1375:
	s_andn2_b64 vcc, exec, s[6:7]
	s_cbranch_vccnz .Lmye_ocont
	v_lshl_add_u64 v[30:31], v[180:181], 0, v[176:177]
	v_add_co_u32_e32 v2, vcc, 0xab00000, v30
	v_lshl_add_u64 v[42:43], v[178:179], 0, v[176:177]
	v_addc_co_u32_e32 v3, vcc, 0, v31, vcc
	v_add_co_u32_e32 v14, vcc, 0xab40000, v30
	s_nop 1
	v_addc_co_u32_e32 v15, vcc, 0, v31, vcc
	v_add_co_u32_e32 v32, vcc, 0xab80000, v30
	global_load_dwordx4 v[2:5], v[2:3], off offset:512
	s_nop 0
	global_load_dwordx4 v[14:17], v[14:15], off offset:512
	v_addc_co_u32_e32 v33, vcc, 0, v31, vcc
	v_add_co_u32_e32 v38, vcc, 0xabc0000, v30
	s_nop 1
	v_addc_co_u32_e32 v39, vcc, 0, v31, vcc
	v_add_co_u32_e32 v44, vcc, 0x1400000, v42
	global_load_dwordx4 v[30:33], v[32:33], off offset:512
	s_nop 0
	global_load_dwordx4 v[38:41], v[38:39], off offset:512
	v_addc_co_u32_e32 v45, vcc, 0, v43, vcc
	v_add_co_u32_e32 v46, vcc, 0x1440000, v42
	s_nop 1
	v_addc_co_u32_e32 v47, vcc, 0, v43, vcc
	global_load_dwordx4 v[42:45], v[44:45], off offset:512
	s_nop 0
	global_load_dwordx4 v[46:49], v[46:47], off offset:512
.Lmye_ocont:
	v_mfma_f32_16x16x32_bf16 v[78:81], v[154:157], v[162:165], v[78:81]
	v_mfma_f32_16x16x32_bf16 v[74:77], v[154:157], v[166:169], v[74:77]
	v_mfma_f32_16x16x32_bf16 v[70:73], v[154:157], v[234:237], v[70:73]
	v_mfma_f32_16x16x32_bf16 v[66:69], v[154:157], v[238:241], v[66:69]
	v_mfma_f32_16x16x32_bf16 v[62:65], v[158:161], v[162:165], v[62:65]
	v_mfma_f32_16x16x32_bf16 v[58:61], v[158:161], v[166:169], v[58:61]
	v_mfma_f32_16x16x32_bf16 v[54:57], v[158:161], v[234:237], v[54:57]
	v_mfma_f32_16x16x32_bf16 v[50:53], v[158:161], v[238:241], v[50:53]
	s_waitcnt lgkmcnt(0)
	v_mfma_f32_16x16x32_bf16 v[110:113], v[114:117], v[130:133], v[110:113]
	ds_read_b128 v[146:149], v226 offset:32768
	v_mfma_f32_16x16x32_bf16 v[106:109], v[114:117], v[134:137], v[106:109]
	ds_read_b128 v[150:153], v226 offset:34816
	v_mfma_f32_16x16x32_bf16 v[102:105], v[114:117], v[138:141], v[102:105]
	ds_read_b128 v[154:157], v226 offset:36864
	v_mfma_f32_16x16x32_bf16 v[98:101], v[114:117], v[142:145], v[98:101]
	ds_read_b128 v[158:161], v226 offset:38912
	v_mfma_f32_16x16x32_bf16 v[94:97], v[118:121], v[130:133], v[94:97]
	ds_read_b128 v[162:165], v230
	v_mfma_f32_16x16x32_bf16 v[90:93], v[118:121], v[134:137], v[90:93]
	ds_read_b128 v[166:169], v230 offset:2048
	v_mfma_f32_16x16x32_bf16 v[86:89], v[118:121], v[138:141], v[86:89]
	ds_read_b128 v[234:237], v230 offset:4096
	v_mfma_f32_16x16x32_bf16 v[82:85], v[118:121], v[142:145], v[82:85]
	ds_read_b128 v[238:241], v230 offset:6144
	v_mfma_f32_16x16x32_bf16 v[78:81], v[122:125], v[130:133], v[78:81]
	v_mfma_f32_16x16x32_bf16 v[74:77], v[122:125], v[134:137], v[74:77]
	v_mfma_f32_16x16x32_bf16 v[70:73], v[122:125], v[138:141], v[70:73]
	v_mfma_f32_16x16x32_bf16 v[66:69], v[122:125], v[142:145], v[66:69]
	v_mfma_f32_16x16x32_bf16 v[62:65], v[126:129], v[130:133], v[62:65]
	v_mfma_f32_16x16x32_bf16 v[58:61], v[126:129], v[134:137], v[58:61]
	v_mfma_f32_16x16x32_bf16 v[54:57], v[126:129], v[138:141], v[54:57]
	v_mfma_f32_16x16x32_bf16 v[50:53], v[126:129], v[142:145], v[50:53]
	s_add_i32 s13, s13, 2
	v_lshl_add_u64 v[178:179], v[178:179], 0, s[74:75]
	v_lshl_add_u64 v[180:181], v[180:181], 0, s[74:75]
	s_branch .Lmye_even
.Lmye_oddlast:
	v_mfma_f32_16x16x32_bf16 v[110:113], v[146:149], v[162:165], v[110:113]
	v_mfma_f32_16x16x32_bf16 v[106:109], v[146:149], v[166:169], v[106:109]
	v_mfma_f32_16x16x32_bf16 v[102:105], v[146:149], v[234:237], v[102:105]
	v_mfma_f32_16x16x32_bf16 v[98:101], v[146:149], v[238:241], v[98:101]
	v_mfma_f32_16x16x32_bf16 v[94:97], v[150:153], v[162:165], v[94:97]
	v_mfma_f32_16x16x32_bf16 v[90:93], v[150:153], v[166:169], v[90:93]
	v_mfma_f32_16x16x32_bf16 v[86:89], v[150:153], v[234:237], v[86:89]
	v_mfma_f32_16x16x32_bf16 v[82:85], v[150:153], v[238:241], v[82:85]
	v_mfma_f32_16x16x32_bf16 v[78:81], v[154:157], v[162:165], v[78:81]
	v_mfma_f32_16x16x32_bf16 v[74:77], v[154:157], v[166:169], v[74:77]
	v_mfma_f32_16x16x32_bf16 v[70:73], v[154:157], v[234:237], v[70:73]
	v_mfma_f32_16x16x32_bf16 v[66:69], v[154:157], v[238:241], v[66:69]
	v_mfma_f32_16x16x32_bf16 v[62:65], v[158:161], v[162:165], v[62:65]
	v_mfma_f32_16x16x32_bf16 v[58:61], v[158:161], v[166:169], v[58:61]
	v_mfma_f32_16x16x32_bf16 v[54:57], v[158:161], v[234:237], v[54:57]
	v_mfma_f32_16x16x32_bf16 v[50:53], v[158:161], v[238:241], v[50:53]
	s_waitcnt lgkmcnt(0)
	v_mfma_f32_16x16x32_bf16 v[110:113], v[114:117], v[130:133], v[110:113]
	ds_read_b128 v[146:149], v226 offset:32768
	v_mfma_f32_16x16x32_bf16 v[106:109], v[114:117], v[134:137], v[106:109]
	ds_read_b128 v[150:153], v226 offset:34816
	v_mfma_f32_16x16x32_bf16 v[102:105], v[114:117], v[138:141], v[102:105]
	ds_read_b128 v[154:157], v226 offset:36864
	v_mfma_f32_16x16x32_bf16 v[98:101], v[114:117], v[142:145], v[98:101]
	ds_read_b128 v[158:161], v226 offset:38912
	v_mfma_f32_16x16x32_bf16 v[94:97], v[118:121], v[130:133], v[94:97]
	ds_read_b128 v[162:165], v230
	v_mfma_f32_16x16x32_bf16 v[90:93], v[118:121], v[134:137], v[90:93]
	ds_read_b128 v[166:169], v230 offset:2048
	v_mfma_f32_16x16x32_bf16 v[86:89], v[118:121], v[138:141], v[86:89]
	ds_read_b128 v[234:237], v230 offset:4096
	v_mfma_f32_16x16x32_bf16 v[82:85], v[118:121], v[142:145], v[82:85]
	ds_read_b128 v[238:241], v230 offset:6144
	v_mfma_f32_16x16x32_bf16 v[78:81], v[122:125], v[130:133], v[78:81]
	v_mfma_f32_16x16x32_bf16 v[74:77], v[122:125], v[134:137], v[74:77]
	v_mfma_f32_16x16x32_bf16 v[70:73], v[122:125], v[138:141], v[70:73]
	v_mfma_f32_16x16x32_bf16 v[66:69], v[122:125], v[142:145], v[66:69]
	v_mfma_f32_16x16x32_bf16 v[62:65], v[126:129], v[130:133], v[62:65]
	v_mfma_f32_16x16x32_bf16 v[58:61], v[126:129], v[134:137], v[58:61]
	v_mfma_f32_16x16x32_bf16 v[54:57], v[126:129], v[138:141], v[54:57]
	v_mfma_f32_16x16x32_bf16 v[50:53], v[126:129], v[142:145], v[50:53]
	s_add_i32 s13, s13, 2
	v_lshl_add_u64 v[178:179], v[178:179], 0, s[74:75]
	v_lshl_add_u64 v[180:181], v[180:181], 0, s[74:75]
	s_waitcnt lgkmcnt(0)
	v_mfma_f32_16x16x32_bf16 v[110:113], v[146:149], v[162:165], v[110:113]
	v_mfma_f32_16x16x32_bf16 v[106:109], v[146:149], v[166:169], v[106:109]
	v_mfma_f32_16x16x32_bf16 v[102:105], v[146:149], v[234:237], v[102:105]
	v_mfma_f32_16x16x32_bf16 v[98:101], v[146:149], v[238:241], v[98:101]
	v_mfma_f32_16x16x32_bf16 v[94:97], v[150:153], v[162:165], v[94:97]
	v_mfma_f32_16x16x32_bf16 v[90:93], v[150:153], v[166:169], v[90:93]
	v_mfma_f32_16x16x32_bf16 v[86:89], v[150:153], v[234:237], v[86:89]
	v_mfma_f32_16x16x32_bf16 v[82:85], v[150:153], v[238:241], v[82:85]
	v_mfma_f32_16x16x32_bf16 v[78:81], v[154:157], v[162:165], v[78:81]
	v_mfma_f32_16x16x32_bf16 v[74:77], v[154:157], v[166:169], v[74:77]
	v_mfma_f32_16x16x32_bf16 v[70:73], v[154:157], v[234:237], v[70:73]
	v_mfma_f32_16x16x32_bf16 v[66:69], v[154:157], v[238:241], v[66:69]
	v_mfma_f32_16x16x32_bf16 v[62:65], v[158:161], v[162:165], v[62:65]
	v_mfma_f32_16x16x32_bf16 v[58:61], v[158:161], v[166:169], v[58:61]
	v_mfma_f32_16x16x32_bf16 v[54:57], v[158:161], v[234:237], v[54:57]
	v_mfma_f32_16x16x32_bf16 v[50:53], v[158:161], v[238:241], v[50:53]
	s_and_b64 vcc, exec, s[4:5]
	s_nop 7
	s_branch .LBB0_1359

.LBB0_1485:
	s_or_b64 exec, exec, s[0:1]
	v_readlane_b32 s0, v252, 21
	s_waitcnt lgkmcnt(0)
	v_mov_b32_e32 v0, v170
	s_cmpk_gt_u32 s0, 0x7ff
	s_barrier
	v_readlane_b32 s1, v252, 22
	s_cbranch_scc1 .LBB0_1505
	v_lshlrev_b32_e32 v2, 4, v0
	v_readlane_b32 s0, v252, 13
	v_and_b32_e32 v174, 0x70, v2
	v_mov_b32_e32 v175, 0
	v_readlane_b32 s1, v252, 14
	v_lshl_add_u64 v[2:3], s[76:77], 0, v[174:175]
	v_and_b32_e32 v4, 15, v0
	v_lshl_add_u64 v[176:177], s[0:1], 0, v[174:175]
	s_mov_b64 s[0:1], 0x1800000
	v_lshl_add_u64 v[178:179], v[2:3], 0, s[0:1]
	v_lshrrev_b32_e32 v2, 4, v0
	v_xor_b32_e32 v2, v2, v0
	v_ashrrev_i32_e32 v171, 3, v0
	v_bfe_u32 v5, v0, 6, 1
	v_ashrrev_i32_e32 v6, 7, v0
	v_lshlrev_b32_e32 v2, 4, v2
	v_lshlrev_b32_e32 v4, 7, v4
	v_lshlrev_b32_e32 v3, 7, v171
	v_and_b32_e32 v2, 0x70, v2
	v_readlane_b32 s0, v252, 29
	v_lshl_or_b32 v7, v6, 13, v4
	v_lshl_or_b32 v4, v5, 13, v4
	v_readlane_b32 s2, v252, 16
	v_bfe_u32 v1, v0, 4, 2
	v_and_b32_e32 v40, 3, v171
	v_lshlrev_b32_e32 v40, 4, v40
	v_lshrrev_b32_e32 v41, 2, v171
	v_add_u32_e32 v40, v40, v41
	v_lshrrev_b32_e32 v41, 1, v40
	v_xor_b32_e32 v41, v41, v0
	v_and_b32_e32 v41, 7, v41
	v_lshlrev_b32_e32 v41, 4, v41
	v_lshl_add_u32 v40, v40, 7, v41
	v_add_u32_e32 v214, s0, v40
	v_add_u32_e32 v8, s0, v4
	v_bfe_u32 v9, v0, 1, 3
	v_readlane_b32 s0, v252, 30
	v_add3_u32 v173, 16, v3, v2
	v_xor_b32_e32 v10, v1, v9
	v_bitop3_b32 v1, v1, v9, 4 bitop3:0x36
	v_and_b32_e32 v40, 3, v171
	v_lshlrev_b32_e32 v40, 4, v40
	v_lshrrev_b32_e32 v41, 2, v171
	v_add_u32_e32 v40, v40, v41
	v_lshrrev_b32_e32 v41, 1, v40
	v_xor_b32_e32 v41, v41, v0
	v_and_b32_e32 v41, 7, v41
	v_lshlrev_b32_e32 v41, 4, v41
	v_lshl_add_u32 v40, v40, 7, v41
	v_add_u32_e32 v219, s0, v40
	v_add_u32_e32 v2, s0, v4
	s_lshl_b32 s0, s2, 15
	v_readlane_b32 s1, v253, 24
	v_and_b32_e32 v169, 63, v0
	v_add_u32_e32 v7, 16, v7
	v_lshlrev_b32_e32 v9, 4, v10
	v_lshlrev_b32_e32 v1, 4, v1
	v_and_b32_e32 v0, 7, v0
	s_add_i32 s15, s0, s1
	s_lshl_b32 s0, s2, 11
	s_lshl_b32 s1, s62, 3
	s_lshl_b32 s14, s2, 8
	v_add_u32_e32 v215, v7, v9
	v_add_u32_e32 v216, v8, v9
	v_add_u32_e32 v217, v7, v1
	v_add_u32_e32 v218, v8, v1
	v_add_u32_e32 v220, v2, v9
	v_add_u32_e32 v221, v2, v1
	v_lshlrev_b32_e32 v222, 6, v6
	v_lshlrev_b32_e32 v223, 6, v5
	v_lshlrev_b32_e32 v180, 4, v0
	v_mov_b32_e32 v181, v175
	s_add_i32 s16, s0, s1
	s_lshl_b32 s17, s51, 3
	s_mov_b64 s[8:9], 0
	s_mov_b64 s[0:1], 0x20080
	s_mov_b64 s[2:3], 0x20000
	s_mov_b64 s[4:5], 0x100
	s_movk_i32 s18, 0x7fff
	s_mov_b32 s19, s62
	s_branch .LBB0_1488
.LBB0_1487:
	v_and_b32_e32 v112, 15, v169
	v_lshrrev_b32_e32 v113, 4, v169
	v_add3_u32 v114, s20, v222, v112
	v_or_b32_e32 v115, s21, v223
	v_lshl_add_u32 v115, v113, 4, v115
	v_lshlrev_b32_e32 v114, 13, v114
	v_lshl_add_u32 v114, v115, 1, v114
	v_readlane_b32 s8, v251, 56
	v_readlane_b32 s9, v251, 57
	v_max_f32_e32 v108, 0, v108
	v_max_f32_e32 v104, 0, v104
	v_max_f32_e32 v100, 0, v100
	v_max_f32_e32 v96, 0, v96
	v_mul_f32_e32 v108, v108, v108
	v_mul_f32_e32 v104, v104, v104
	v_mul_f32_e32 v100, v100, v100
	v_mul_f32_e32 v96, v96, v96
	v_cvt_pk_bf16_f32 v120, v108, v104
	v_cvt_pk_bf16_f32 v121, v100, v96
	v_max_f32_e32 v109, 0, v109
	v_max_f32_e32 v105, 0, v105
	v_max_f32_e32 v101, 0, v101
	v_max_f32_e32 v97, 0, v97
	v_mul_f32_e32 v109, v109, v109
	v_mul_f32_e32 v105, v105, v105
	v_mul_f32_e32 v101, v101, v101
	v_mul_f32_e32 v97, v97, v97
	v_cvt_pk_bf16_f32 v122, v109, v105
	v_cvt_pk_bf16_f32 v123, v101, v97
	v_max_f32_e32 v110, 0, v110
	v_max_f32_e32 v106, 0, v106
	v_max_f32_e32 v102, 0, v102
	v_max_f32_e32 v98, 0, v98
	v_mul_f32_e32 v110, v110, v110
	v_mul_f32_e32 v106, v106, v106
	v_mul_f32_e32 v102, v102, v102
	v_mul_f32_e32 v98, v98, v98
	v_cvt_pk_bf16_f32 v124, v110, v106
	v_cvt_pk_bf16_f32 v125, v102, v98
	v_max_f32_e32 v111, 0, v111
	v_max_f32_e32 v107, 0, v107
	v_max_f32_e32 v103, 0, v103
	v_max_f32_e32 v99, 0, v99
	v_mul_f32_e32 v111, v111, v111
	v_mul_f32_e32 v107, v107, v107
	v_mul_f32_e32 v103, v103, v103
	v_mul_f32_e32 v99, v99, v99
	v_cvt_pk_bf16_f32 v126, v111, v107
	v_cvt_pk_bf16_f32 v127, v103, v99
	global_store_dwordx4 v114, v[120:123], s[8:9]
	global_store_dwordx4 v114, v[124:127], s[8:9] offset:16
	v_add_u32_e32 v114, 0x20000, v114
	v_max_f32_e32 v92, 0, v92
	v_max_f32_e32 v88, 0, v88
	v_max_f32_e32 v84, 0, v84
	v_max_f32_e32 v80, 0, v80
	v_mul_f32_e32 v92, v92, v92
	v_mul_f32_e32 v88, v88, v88
	v_mul_f32_e32 v84, v84, v84
	v_mul_f32_e32 v80, v80, v80
	v_cvt_pk_bf16_f32 v120, v92, v88
	v_cvt_pk_bf16_f32 v121, v84, v80
	v_max_f32_e32 v93, 0, v93
	v_max_f32_e32 v89, 0, v89
	v_max_f32_e32 v85, 0, v85
	v_max_f32_e32 v81, 0, v81
	v_mul_f32_e32 v93, v93, v93
	v_mul_f32_e32 v89, v89, v89
	v_mul_f32_e32 v85, v85, v85
	v_mul_f32_e32 v81, v81, v81
	v_cvt_pk_bf16_f32 v122, v93, v89
	v_cvt_pk_bf16_f32 v123, v85, v81
	v_max_f32_e32 v94, 0, v94
	v_max_f32_e32 v90, 0, v90
	v_max_f32_e32 v86, 0, v86
	v_max_f32_e32 v82, 0, v82
	v_mul_f32_e32 v94, v94, v94
	v_mul_f32_e32 v90, v90, v90
	v_mul_f32_e32 v86, v86, v86
	v_mul_f32_e32 v82, v82, v82
	v_cvt_pk_bf16_f32 v124, v94, v90
	v_cvt_pk_bf16_f32 v125, v86, v82
	v_max_f32_e32 v95, 0, v95
	v_max_f32_e32 v91, 0, v91
	v_max_f32_e32 v87, 0, v87
	v_max_f32_e32 v83, 0, v83
	v_mul_f32_e32 v95, v95, v95
	v_mul_f32_e32 v91, v91, v91
	v_mul_f32_e32 v87, v87, v87
	v_mul_f32_e32 v83, v83, v83
	v_cvt_pk_bf16_f32 v126, v95, v91
	v_cvt_pk_bf16_f32 v127, v87, v83
	global_store_dwordx4 v114, v[120:123], s[8:9]
	global_store_dwordx4 v114, v[124:127], s[8:9] offset:16
	v_add_u32_e32 v114, 0x20000, v114
	v_max_f32_e32 v76, 0, v76
	v_max_f32_e32 v72, 0, v72
	v_max_f32_e32 v68, 0, v68
	v_max_f32_e32 v64, 0, v64
	v_mul_f32_e32 v76, v76, v76
	v_mul_f32_e32 v72, v72, v72
	v_mul_f32_e32 v68, v68, v68
	v_mul_f32_e32 v64, v64, v64
	v_cvt_pk_bf16_f32 v120, v76, v72
	v_cvt_pk_bf16_f32 v121, v68, v64
	v_max_f32_e32 v77, 0, v77
	v_max_f32_e32 v73, 0, v73
	v_max_f32_e32 v69, 0, v69
	v_max_f32_e32 v65, 0, v65
	v_mul_f32_e32 v77, v77, v77
	v_mul_f32_e32 v73, v73, v73
	v_mul_f32_e32 v69, v69, v69
	v_mul_f32_e32 v65, v65, v65
	v_cvt_pk_bf16_f32 v122, v77, v73
	v_cvt_pk_bf16_f32 v123, v69, v65
	v_max_f32_e32 v78, 0, v78
	v_max_f32_e32 v74, 0, v74
	v_max_f32_e32 v70, 0, v70
	v_max_f32_e32 v66, 0, v66
	v_mul_f32_e32 v78, v78, v78
	v_mul_f32_e32 v74, v74, v74
	v_mul_f32_e32 v70, v70, v70
	v_mul_f32_e32 v66, v66, v66
	v_cvt_pk_bf16_f32 v124, v78, v74
	v_cvt_pk_bf16_f32 v125, v70, v66
	v_max_f32_e32 v79, 0, v79
	v_max_f32_e32 v75, 0, v75
	v_max_f32_e32 v71, 0, v71
	v_max_f32_e32 v67, 0, v67
	v_mul_f32_e32 v79, v79, v79
	v_mul_f32_e32 v75, v75, v75
	v_mul_f32_e32 v71, v71, v71
	v_mul_f32_e32 v67, v67, v67
	v_cvt_pk_bf16_f32 v126, v79, v75
	v_cvt_pk_bf16_f32 v127, v71, v67
	global_store_dwordx4 v114, v[120:123], s[8:9]
	global_store_dwordx4 v114, v[124:127], s[8:9] offset:16
	v_add_u32_e32 v114, 0x20000, v114
	v_max_f32_e32 v60, 0, v60
	v_max_f32_e32 v56, 0, v56
	v_max_f32_e32 v52, 0, v52
	v_max_f32_e32 v48, 0, v48
	v_mul_f32_e32 v60, v60, v60
	v_mul_f32_e32 v56, v56, v56
	v_mul_f32_e32 v52, v52, v52
	v_mul_f32_e32 v48, v48, v48
	v_cvt_pk_bf16_f32 v120, v60, v56
	v_cvt_pk_bf16_f32 v121, v52, v48
	v_max_f32_e32 v61, 0, v61
	v_max_f32_e32 v57, 0, v57
	v_max_f32_e32 v53, 0, v53
	v_max_f32_e32 v49, 0, v49
	v_mul_f32_e32 v61, v61, v61
	v_mul_f32_e32 v57, v57, v57
	v_mul_f32_e32 v53, v53, v53
	v_mul_f32_e32 v49, v49, v49
	v_cvt_pk_bf16_f32 v122, v61, v57
	v_cvt_pk_bf16_f32 v123, v53, v49
	v_max_f32_e32 v62, 0, v62
	v_max_f32_e32 v58, 0, v58
	v_max_f32_e32 v54, 0, v54
	v_max_f32_e32 v50, 0, v50
	v_mul_f32_e32 v62, v62, v62
	v_mul_f32_e32 v58, v58, v58
	v_mul_f32_e32 v54, v54, v54
	v_mul_f32_e32 v50, v50, v50
	v_cvt_pk_bf16_f32 v124, v62, v58
	v_cvt_pk_bf16_f32 v125, v54, v50
	v_max_f32_e32 v63, 0, v63
	v_max_f32_e32 v59, 0, v59
	v_max_f32_e32 v55, 0, v55
	v_max_f32_e32 v51, 0, v51
	v_mul_f32_e32 v63, v63, v63
	v_mul_f32_e32 v59, v59, v59
	v_mul_f32_e32 v55, v55, v55
	v_mul_f32_e32 v51, v51, v51
	v_cvt_pk_bf16_f32 v126, v63, v59
	v_cvt_pk_bf16_f32 v127, v55, v51
	global_store_dwordx4 v114, v[120:123], s[8:9]
	global_store_dwordx4 v114, v[124:127], s[8:9] offset:16
	s_add_i32 s15, s15, s36
	s_add_i32 s16, s16, s17
	s_mov_b64 s[8:9], -1
	s_and_b64 vcc, exec, s[6:7]
	s_cbranch_vccnz .LBB0_1505
.LBB0_1488:
	s_add_i32 s6, s19, s14
	s_mov_b32 s100, s6
	s_lshr_b32 s98, s100, 7
	s_lshl_b32 s98, s98, 10
	s_and_b32 s99, s100, 3
	s_lshl_b32 s99, s99, 8
	s_or_b32 s20, s98, s99
	s_lshl_b32 s98, s100, 5
	s_and_b32 s21, s98, 0xf80
	v_add_u32_e32 v48, s20, v171
	v_add_u32_e32 v50, s21, v171
	v_ashrrev_i32_e32 v49, 31, v48
	v_ashrrev_i32_e32 v51, 31, v50
	v_lshlrev_b64 v[48:49], 11, v[48:49]
	v_lshlrev_b64 v[50:51], 11, v[50:51]
	v_lshl_add_u64 v[48:49], v[176:177], 0, v[48:49]
	v_lshl_add_u64 v[50:51], v[178:179], 0, v[50:51]
	s_and_b64 vcc, exec, s[8:9]
	s_cbranch_vccnz .LBB0_1490
	s_waitcnt vmcnt(62)
	v_add_co_u32_e32 v4, vcc, 0x20000, v48
	s_nop 1
	v_addc_co_u32_e32 v5, vcc, 0, v49, vcc
	v_add_co_u32_e32 v8, vcc, 0x40000, v48
	s_nop 1
	v_addc_co_u32_e32 v9, vcc, 0, v49, vcc
	v_add_co_u32_e32 v12, vcc, 0x60000, v48
	s_nop 1
	v_addc_co_u32_e32 v13, vcc, 0, v49, vcc
	s_waitcnt vmcnt(0)
	v_add_co_u32_e32 v24, vcc, 0x20000, v50
	s_nop 1
	v_addc_co_u32_e32 v25, vcc, 0, v51, vcc
	global_load_dwordx4 v[36:39], v[48:49], off
	global_load_dwordx4 v[0:3], v[48:49], off offset:128
	global_load_dwordx4 v[44:47], v[4:5], off
	s_nop 0
	global_load_dwordx4 v[4:7], v[4:5], off offset:128
	s_nop 0
	global_load_dwordx4 v[32:35], v[8:9], off
	s_nop 0
	global_load_dwordx4 v[8:11], v[8:9], off offset:128
	s_nop 0
	global_load_dwordx4 v[40:43], v[12:13], off
	s_nop 0
	global_load_dwordx4 v[12:15], v[12:13], off offset:128
	s_nop 0
	global_load_dwordx4 v[20:23], v[50:51], off
	global_load_dwordx4 v[16:19], v[50:51], off offset:128
	global_load_dwordx4 v[28:31], v[24:25], off
	s_nop 0
	global_load_dwordx4 v[24:27], v[24:25], off offset:128
.LBB0_1490:
	s_mov_b32 s6, s21
	v_add_u32_e32 v52, s6, v171
	v_ashrrev_i32_e32 v53, 31, v52
	s_mov_b32 s6, s20
	s_add_i32 s19, s19, s51
	v_lshlrev_b64 v[52:53], 11, v[52:53]
	s_cmpk_gt_u32 s19, 0xff
	v_lshl_add_u64 v[182:183], s[76:77], 0, v[52:53]
	v_add_u32_e32 v52, s6, v171
	s_cselect_b64 s[6:7], -1, 0
	s_add_i32 s12, s19, s14
	s_cmpk_lt_u32 s19, 0x100
	s_cselect_b64 s[8:9], -1, 0
	s_and_b64 s[10:11], s[8:9], exec
	s_cselect_b32 s10, s12, 0
	s_mov_b32 s100, s10
	s_lshr_b32 s98, s100, 7
	s_lshl_b32 s98, s98, 10
	s_and_b32 s99, s100, 3
	s_lshl_b32 s99, s99, 8
	s_or_b32 s11, s98, s99
	s_lshl_b32 s98, s100, 5
	s_and_b32 s10, s98, 0xf80
	v_add_u32_e32 v54, s10, v171
	s_mov_b32 s10, 0x20000
	s_barrier
	s_waitcnt vmcnt(0)
	ds_write_b128 v173, v[36:39]
	ds_write_b128 v173, v[44:47] offset:8192
	ds_write_b128 v173, v[32:35] offset:16384
	ds_write_b128 v173, v[40:43] offset:24576
	ds_write_b128 v214, v[20:23]
	ds_write_b128 v214, v[28:31] offset:8192
	v_add_co_u32_e32 v20, vcc, s10, v50
	v_ashrrev_i32_e32 v53, 31, v52
	s_nop 0
	v_addc_co_u32_e32 v21, vcc, 0, v51, vcc
	v_add_co_u32_e32 v32, vcc, 0x60000, v48
	global_load_dwordx4 v[28:31], v[20:21], off offset:256
	s_nop 0
	global_load_dwordx4 v[20:23], v[50:51], off offset:256
	v_addc_co_u32_e32 v33, vcc, 0, v49, vcc
	global_load_dwordx4 v[40:43], v[32:33], off offset:256
	v_add_co_u32_e32 v32, vcc, 0x40000, v48
	v_lshlrev_b64 v[52:53], 11, v[52:53]
	s_nop 0
	v_addc_co_u32_e32 v33, vcc, 0, v49, vcc
	v_add_co_u32_e32 v36, vcc, 0x20000, v48
	global_load_dwordx4 v[32:35], v[32:33], off offset:256
	s_nop 0
	v_addc_co_u32_e32 v37, vcc, 0, v49, vcc
	global_load_dwordx4 v[44:47], v[36:37], off offset:256
	s_nop 0
	global_load_dwordx4 v[36:39], v[48:49], off offset:256
	v_lshl_add_u64 v[184:185], s[76:77], 0, v[52:53]
	v_add_u32_e32 v52, s11, v171
	v_ashrrev_i32_e32 v53, 31, v52
	v_lshlrev_b64 v[52:53], 11, v[52:53]
	v_lshl_add_u64 v[186:187], v[176:177], 0, v[52:53]
	s_mov_b64 s[10:11], 0x40080
	v_ashrrev_i32_e32 v55, 31, v54
	v_lshl_add_u64 v[192:193], v[186:187], 0, s[10:11]
	s_mov_b64 s[10:11], 0x60080
	v_lshlrev_b64 v[54:55], 11, v[54:55]
	v_lshl_add_u64 v[194:195], v[186:187], 0, s[10:11]
	s_mov_b64 s[10:11], 0x40000
	v_lshl_add_u64 v[188:189], v[178:179], 0, v[54:55]
	v_lshl_add_u64 v[200:201], v[186:187], 0, s[10:11]
	s_mov_b64 s[10:11], 0x60000
	v_mov_b32_e32 v48, 0
	s_mov_b32 s22, 0
	v_lshl_add_u64 v[190:191], v[186:187], 0, s[0:1]
	v_lshl_add_u64 v[196:197], v[188:189], 0, s[0:1]
	v_lshl_add_u64 v[198:199], v[186:187], 0, s[2:3]
	v_lshl_add_u64 v[202:203], v[186:187], 0, s[10:11]
	v_lshl_add_u64 v[204:205], v[188:189], 0, s[2:3]
	v_mov_b32_e32 v49, v48
	v_mov_b32_e32 v50, v48
	v_mov_b32_e32 v51, v48
	v_mov_b32_e32 v52, v48
	v_mov_b32_e32 v53, v48
	v_mov_b32_e32 v54, v48
	v_mov_b32_e32 v55, v48
	v_mov_b32_e32 v56, v48
	v_mov_b32_e32 v57, v48
	v_mov_b32_e32 v58, v48
	v_mov_b32_e32 v59, v48
	v_mov_b32_e32 v60, v48
	v_mov_b32_e32 v61, v48
	v_mov_b32_e32 v62, v48
	v_mov_b32_e32 v63, v48
	v_mov_b32_e32 v64, v48
	v_mov_b32_e32 v65, v48
	v_mov_b32_e32 v66, v48
	v_mov_b32_e32 v67, v48
	v_mov_b32_e32 v68, v48
	v_mov_b32_e32 v69, v48
	v_mov_b32_e32 v70, v48
	v_mov_b32_e32 v71, v48
	v_mov_b32_e32 v72, v48
	v_mov_b32_e32 v73, v48
	v_mov_b32_e32 v74, v48
	v_mov_b32_e32 v75, v48
	v_mov_b32_e32 v76, v48
	v_mov_b32_e32 v77, v48
	v_mov_b32_e32 v78, v48
	v_mov_b32_e32 v79, v48
	v_mov_b32_e32 v80, v48
	v_mov_b32_e32 v81, v48
	v_mov_b32_e32 v82, v48
	v_mov_b32_e32 v83, v48
	v_mov_b32_e32 v84, v48
	v_mov_b32_e32 v85, v48
	v_mov_b32_e32 v86, v48
	v_mov_b32_e32 v87, v48
	v_mov_b32_e32 v88, v48
	v_mov_b32_e32 v89, v48
	v_mov_b32_e32 v90, v48
	v_mov_b32_e32 v91, v48
	v_mov_b32_e32 v92, v48
	v_mov_b32_e32 v93, v48
	v_mov_b32_e32 v94, v48
	v_mov_b32_e32 v95, v48
	v_mov_b32_e32 v96, v48
	v_mov_b32_e32 v97, v48
	v_mov_b32_e32 v98, v48
	v_mov_b32_e32 v99, v48
	v_mov_b32_e32 v100, v48
	v_mov_b32_e32 v101, v48
	v_mov_b32_e32 v102, v48
	v_mov_b32_e32 v103, v48
	v_mov_b32_e32 v104, v48
	v_mov_b32_e32 v105, v48
	v_mov_b32_e32 v106, v48
	v_mov_b32_e32 v107, v48
	v_mov_b32_e32 v108, v48
	v_mov_b32_e32 v109, v48
	v_mov_b32_e32 v110, v48
	v_mov_b32_e32 v111, v48
	s_branch .LBB0_1492
.LBB0_1492:
	s_waitcnt lgkmcnt(0)
	s_barrier
	ds_read_b128 v[112:115], v215
	ds_read_b128 v[116:119], v215 offset:2048
	ds_read_b128 v[120:123], v215 offset:4096
	ds_read_b128 v[124:127], v215 offset:6144
	ds_read_b128 v[128:131], v216
	ds_read_b128 v[132:135], v216 offset:2048
	ds_read_b128 v[136:139], v216 offset:4096
	ds_read_b128 v[140:143], v216 offset:6144
	s_waitcnt vmcnt(6)
	ds_write_b128 v173, v[0:3] offset:32768
	ds_write_b128 v173, v[4:7] offset:40960
	ds_write_b128 v173, v[8:11] offset:49152
	ds_write_b128 v173, v[12:15] offset:57344
	ds_write_b128 v219, v[16:19]
	ds_write_b128 v219, v[24:27] offset:8192
	s_cmp_gt_u32 s22, 12
	s_mov_b64 s[10:11], -1
	s_cbranch_scc0 .Lmyffe__1496
	s_andn2_b64 vcc, exec, s[8:9]
	s_cbranch_vccnz .Lmyffe__1495
	global_load_dwordx4 v[4:7], v[190:191], off
	global_load_dwordx4 v[8:11], v[192:193], off
	global_load_dwordx4 v[0:3], v[186:187], off offset:128
	global_load_dwordx4 v[16:19], v[188:189], off offset:128
	global_load_dwordx4 v[12:15], v[194:195], off
	global_load_dwordx4 v[24:27], v[196:197], off

.Lmyffe__1496:
	s_andn2_b64 vcc, exec, s[10:11]
	s_cbranch_vccnz .Lmyffe__1498
	v_lshl_add_u64 v[8:9], v[184:185], 0, v[180:181]
	v_add_co_u32_e32 v0, vcc, 0x2800000, v8
	v_lshl_add_u64 v[16:17], v[182:183], 0, v[180:181]
	v_addc_co_u32_e32 v1, vcc, 0, v9, vcc
	v_add_co_u32_e32 v4, vcc, 0x2820000, v8
	s_nop 1
	v_addc_co_u32_e32 v5, vcc, 0, v9, vcc
	v_add_co_u32_e32 v10, vcc, 0x2840000, v8
	global_load_dwordx4 v[0:3], v[0:1], off offset:384
	s_nop 0
	global_load_dwordx4 v[4:7], v[4:5], off offset:384
	v_addc_co_u32_e32 v11, vcc, 0, v9, vcc
	v_add_co_u32_e32 v12, vcc, 0x2860000, v8
	s_nop 1
	v_addc_co_u32_e32 v13, vcc, 0, v9, vcc
	v_add_co_u32_e32 v18, vcc, 0x1800000, v16
	global_load_dwordx4 v[8:11], v[10:11], off offset:384
	s_nop 0
	global_load_dwordx4 v[12:15], v[12:13], off offset:384
	v_addc_co_u32_e32 v19, vcc, 0, v17, vcc
	v_add_co_u32_e32 v24, vcc, 0x1820000, v16
	s_nop 1
	v_addc_co_u32_e32 v25, vcc, 0, v17, vcc
	global_load_dwordx4 v[16:19], v[18:19], off offset:384
	s_nop 0
	global_load_dwordx4 v[24:27], v[24:25], off offset:384
.Lmyffe__1498:
	s_waitcnt lgkmcnt(0)
	v_mfma_f32_16x16x32_bf16 v[108:111], v[128:131], v[112:115], v[108:111]
	ds_read_b128 v[144:147], v217
	v_mfma_f32_16x16x32_bf16 v[104:107], v[132:135], v[112:115], v[104:107]
	ds_read_b128 v[148:151], v217 offset:2048
	v_mfma_f32_16x16x32_bf16 v[100:103], v[136:139], v[112:115], v[100:103]
	ds_read_b128 v[152:155], v217 offset:4096
	v_mfma_f32_16x16x32_bf16 v[96:99], v[140:143], v[112:115], v[96:99]
	ds_read_b128 v[156:159], v217 offset:6144
	v_mfma_f32_16x16x32_bf16 v[92:95], v[128:131], v[116:119], v[92:95]
	ds_read_b128 v[160:163], v218
	v_mfma_f32_16x16x32_bf16 v[88:91], v[132:135], v[116:119], v[88:91]
	ds_read_b128 v[164:167], v218 offset:2048
	v_mfma_f32_16x16x32_bf16 v[84:87], v[136:139], v[116:119], v[84:87]
	ds_read_b128 v[224:227], v218 offset:4096
	v_mfma_f32_16x16x32_bf16 v[80:83], v[140:143], v[116:119], v[80:83]
	ds_read_b128 v[228:231], v218 offset:6144
	v_mfma_f32_16x16x32_bf16 v[76:79], v[128:131], v[120:123], v[76:79]
	v_mfma_f32_16x16x32_bf16 v[72:75], v[132:135], v[120:123], v[72:75]
	v_mfma_f32_16x16x32_bf16 v[68:71], v[136:139], v[120:123], v[68:71]
	v_mfma_f32_16x16x32_bf16 v[64:67], v[140:143], v[120:123], v[64:67]
	v_mfma_f32_16x16x32_bf16 v[60:63], v[128:131], v[124:127], v[60:63]
	v_mfma_f32_16x16x32_bf16 v[56:59], v[132:135], v[124:127], v[56:59]
	v_mfma_f32_16x16x32_bf16 v[52:55], v[136:139], v[124:127], v[52:55]
	v_mfma_f32_16x16x32_bf16 v[48:51], v[140:143], v[124:127], v[48:51]
	s_branch .Lmyf_odd
.Lmyf_even:
	s_waitcnt lgkmcnt(0)
	s_barrier
	ds_read_b128 v[112:115], v215
	ds_read_b128 v[116:119], v215 offset:2048
	ds_read_b128 v[120:123], v215 offset:4096
	ds_read_b128 v[124:127], v215 offset:6144
	ds_read_b128 v[128:131], v216
	ds_read_b128 v[132:135], v216 offset:2048
	ds_read_b128 v[136:139], v216 offset:4096
	ds_read_b128 v[140:143], v216 offset:6144
	s_cmp_gt_u32 s22, 12
	s_cbranch_scc0 .Lmyf_ew6
	s_and_b64 vcc, exec, s[8:9]
	s_cbranch_vccnz .Lmyf_ew6
	s_waitcnt vmcnt(0)
.Lmyf_ew6:
	s_waitcnt vmcnt(6)
	v_mfma_f32_16x16x32_bf16 v[108:111], v[160:163], v[144:147], v[108:111]
	ds_write_b128 v173, v[0:3] offset:32768
	v_mfma_f32_16x16x32_bf16 v[104:107], v[164:167], v[144:147], v[104:107]
	ds_write_b128 v173, v[4:7] offset:40960
	v_mfma_f32_16x16x32_bf16 v[100:103], v[224:227], v[144:147], v[100:103]
	ds_write_b128 v173, v[8:11] offset:49152
	v_mfma_f32_16x16x32_bf16 v[96:99], v[228:231], v[144:147], v[96:99]
	ds_write_b128 v173, v[12:15] offset:57344
	v_mfma_f32_16x16x32_bf16 v[92:95], v[160:163], v[148:151], v[92:95]
	ds_write_b128 v219, v[16:19]
	v_mfma_f32_16x16x32_bf16 v[88:91], v[164:167], v[148:151], v[88:91]
	ds_write_b128 v219, v[24:27] offset:8192
	v_mfma_f32_16x16x32_bf16 v[84:87], v[224:227], v[148:151], v[84:87]
	v_mfma_f32_16x16x32_bf16 v[80:83], v[228:231], v[148:151], v[80:83]
	s_cmp_gt_u32 s22, 12
	s_mov_b64 s[10:11], -1
	s_cbranch_scc0 .Lmyfse__1496
	s_andn2_b64 vcc, exec, s[8:9]
	s_cbranch_vccnz .Lmyfse__1495
	global_load_dwordx4 v[4:7], v[190:191], off
	global_load_dwordx4 v[8:11], v[192:193], off
	global_load_dwordx4 v[0:3], v[186:187], off offset:128
	global_load_dwordx4 v[16:19], v[188:189], off offset:128
	global_load_dwordx4 v[12:15], v[194:195], off
	global_load_dwordx4 v[24:27], v[196:197], off

.Lmyfse__1498:
	v_mfma_f32_16x16x32_bf16 v[76:79], v[160:163], v[152:155], v[76:79]
	v_mfma_f32_16x16x32_bf16 v[72:75], v[164:167], v[152:155], v[72:75]
	v_mfma_f32_16x16x32_bf16 v[68:71], v[224:227], v[152:155], v[68:71]
	v_mfma_f32_16x16x32_bf16 v[64:67], v[228:231], v[152:155], v[64:67]
	v_mfma_f32_16x16x32_bf16 v[60:63], v[160:163], v[156:159], v[60:63]
	v_mfma_f32_16x16x32_bf16 v[56:59], v[164:167], v[156:159], v[56:59]
	v_mfma_f32_16x16x32_bf16 v[52:55], v[224:227], v[156:159], v[52:55]
	v_mfma_f32_16x16x32_bf16 v[48:51], v[228:231], v[156:159], v[48:51]
	s_waitcnt lgkmcnt(0)
	v_mfma_f32_16x16x32_bf16 v[108:111], v[128:131], v[112:115], v[108:111]
	ds_read_b128 v[144:147], v217
	v_mfma_f32_16x16x32_bf16 v[104:107], v[132:135], v[112:115], v[104:107]
	ds_read_b128 v[148:151], v217 offset:2048
	v_mfma_f32_16x16x32_bf16 v[100:103], v[136:139], v[112:115], v[100:103]
	ds_read_b128 v[152:155], v217 offset:4096
	v_mfma_f32_16x16x32_bf16 v[96:99], v[140:143], v[112:115], v[96:99]
	ds_read_b128 v[156:159], v217 offset:6144
	v_mfma_f32_16x16x32_bf16 v[92:95], v[128:131], v[116:119], v[92:95]
	ds_read_b128 v[160:163], v218
	v_mfma_f32_16x16x32_bf16 v[88:91], v[132:135], v[116:119], v[88:91]
	ds_read_b128 v[164:167], v218 offset:2048
	v_mfma_f32_16x16x32_bf16 v[84:87], v[136:139], v[116:119], v[84:87]
	ds_read_b128 v[224:227], v218 offset:4096
	v_mfma_f32_16x16x32_bf16 v[80:83], v[140:143], v[116:119], v[80:83]
	ds_read_b128 v[228:231], v218 offset:6144
	v_mfma_f32_16x16x32_bf16 v[76:79], v[128:131], v[120:123], v[76:79]
	v_mfma_f32_16x16x32_bf16 v[72:75], v[132:135], v[120:123], v[72:75]
	v_mfma_f32_16x16x32_bf16 v[68:71], v[136:139], v[120:123], v[68:71]
	v_mfma_f32_16x16x32_bf16 v[64:67], v[140:143], v[120:123], v[64:67]
	v_mfma_f32_16x16x32_bf16 v[60:63], v[128:131], v[124:127], v[60:63]
	v_mfma_f32_16x16x32_bf16 v[56:59], v[132:135], v[124:127], v[56:59]
	v_mfma_f32_16x16x32_bf16 v[52:55], v[136:139], v[124:127], v[52:55]
	v_mfma_f32_16x16x32_bf16 v[48:51], v[140:143], v[124:127], v[48:51]
.Lmyf_odd:
	s_waitcnt lgkmcnt(0)
	s_barrier
	ds_read_b128 v[112:115], v215 offset:32768
	ds_read_b128 v[116:119], v215 offset:34816
	ds_read_b128 v[120:123], v215 offset:36864
	ds_read_b128 v[124:127], v215 offset:38912
	ds_read_b128 v[128:131], v220
	ds_read_b128 v[132:135], v220 offset:2048
	ds_read_b128 v[136:139], v220 offset:4096
	ds_read_b128 v[140:143], v220 offset:6144
	s_cmp_gt_u32 s22, 13
	s_cselect_b64 s[10:11], -1, 0
	s_and_b64 vcc, exec, s[10:11]
	s_cbranch_vccnz .Lmyf_oddlast
	s_waitcnt vmcnt(6)
	v_mfma_f32_16x16x32_bf16 v[108:111], v[160:163], v[144:147], v[108:111]
	ds_write_b128 v173, v[36:39]
	v_mfma_f32_16x16x32_bf16 v[104:107], v[164:167], v[144:147], v[104:107]
	ds_write_b128 v173, v[44:47] offset:8192
	v_mfma_f32_16x16x32_bf16 v[100:103], v[224:227], v[144:147], v[100:103]
	ds_write_b128 v173, v[32:35] offset:16384
	v_mfma_f32_16x16x32_bf16 v[96:99], v[228:231], v[144:147], v[96:99]
	ds_write_b128 v173, v[40:43] offset:24576
	v_mfma_f32_16x16x32_bf16 v[92:95], v[160:163], v[148:151], v[92:95]
	ds_write_b128 v214, v[20:23]
	v_mfma_f32_16x16x32_bf16 v[88:91], v[164:167], v[148:151], v[88:91]
	ds_write_b128 v214, v[28:31] offset:8192
	v_mfma_f32_16x16x32_bf16 v[84:87], v[224:227], v[148:151], v[84:87]
	v_mfma_f32_16x16x32_bf16 v[80:83], v[228:231], v[148:151], v[80:83]
	s_cmp_gt_u32 s22, 11
	s_mov_b64 s[12:13], -1
	s_cbranch_scc0 .Lmyfso__1503
	s_andn2_b64 vcc, exec, s[8:9]
	s_cbranch_vccnz .Lmyfso__1502
	global_load_dwordx4 v[44:47], v[198:199], off
	global_load_dwordx4 v[32:35], v[200:201], off
	global_load_dwordx4 v[36:39], v[186:187], off
	global_load_dwordx4 v[20:23], v[188:189], off
	global_load_dwordx4 v[40:43], v[202:203], off
	global_load_dwordx4 v[28:31], v[204:205], off

.Lmyfso__1503:
	s_andn2_b64 vcc, exec, s[12:13]
	s_cbranch_vccnz .Lmyf_ocont
	v_lshl_add_u64 v[20:21], v[184:185], 0, v[180:181]
	v_add_co_u32_e32 v28, vcc, 0x2800000, v20
	v_lshl_add_u64 v[22:23], v[182:183], 0, v[180:181]
	s_nop 0
	v_addc_co_u32_e32 v29, vcc, 0, v21, vcc
	v_add_co_u32_e32 v30, vcc, 0x2820000, v20
	s_nop 1
	v_addc_co_u32_e32 v31, vcc, 0, v21, vcc
	global_load_dwordx4 v[36:39], v[28:29], off offset:512
	global_load_dwordx4 v[44:47], v[30:31], off offset:512
	v_add_co_u32_e32 v28, vcc, 0x2840000, v20
	s_nop 1
	v_addc_co_u32_e32 v29, vcc, 0, v21, vcc
	v_add_co_u32_e32 v20, vcc, 0x2860000, v20
	s_nop 1
	v_addc_co_u32_e32 v21, vcc, 0, v21, vcc
	global_load_dwordx4 v[32:35], v[28:29], off offset:512
	global_load_dwordx4 v[40:43], v[20:21], off offset:512
	v_add_co_u32_e32 v20, vcc, 0x1800000, v22
	s_nop 1
	v_addc_co_u32_e32 v21, vcc, 0, v23, vcc
	v_add_co_u32_e32 v28, vcc, 0x1820000, v22
	s_nop 1
	v_addc_co_u32_e32 v29, vcc, 0, v23, vcc
	global_load_dwordx4 v[20:23], v[20:21], off offset:512
	s_nop 0
	global_load_dwordx4 v[28:31], v[28:29], off offset:512
.Lmyf_ocont:
	v_mfma_f32_16x16x32_bf16 v[76:79], v[160:163], v[152:155], v[76:79]
	v_mfma_f32_16x16x32_bf16 v[72:75], v[164:167], v[152:155], v[72:75]
	v_mfma_f32_16x16x32_bf16 v[68:71], v[224:227], v[152:155], v[68:71]
	v_mfma_f32_16x16x32_bf16 v[64:67], v[228:231], v[152:155], v[64:67]
	v_mfma_f32_16x16x32_bf16 v[60:63], v[160:163], v[156:159], v[60:63]
	v_mfma_f32_16x16x32_bf16 v[56:59], v[164:167], v[156:159], v[56:59]
	v_mfma_f32_16x16x32_bf16 v[52:55], v[224:227], v[156:159], v[52:55]
	v_mfma_f32_16x16x32_bf16 v[48:51], v[228:231], v[156:159], v[48:51]
	s_waitcnt lgkmcnt(0)
	v_mfma_f32_16x16x32_bf16 v[108:111], v[128:131], v[112:115], v[108:111]
	ds_read_b128 v[144:147], v217 offset:32768
	v_mfma_f32_16x16x32_bf16 v[104:107], v[132:135], v[112:115], v[104:107]
	ds_read_b128 v[148:151], v217 offset:34816
	v_mfma_f32_16x16x32_bf16 v[100:103], v[136:139], v[112:115], v[100:103]
	ds_read_b128 v[152:155], v217 offset:36864
	v_mfma_f32_16x16x32_bf16 v[96:99], v[140:143], v[112:115], v[96:99]
	ds_read_b128 v[156:159], v217 offset:38912
	v_mfma_f32_16x16x32_bf16 v[92:95], v[128:131], v[116:119], v[92:95]
	ds_read_b128 v[160:163], v221
	v_mfma_f32_16x16x32_bf16 v[88:91], v[132:135], v[116:119], v[88:91]
	ds_read_b128 v[164:167], v221 offset:2048
	v_mfma_f32_16x16x32_bf16 v[84:87], v[136:139], v[116:119], v[84:87]
	ds_read_b128 v[224:227], v221 offset:4096
	v_mfma_f32_16x16x32_bf16 v[80:83], v[140:143], v[116:119], v[80:83]
	ds_read_b128 v[228:231], v221 offset:6144
	v_mfma_f32_16x16x32_bf16 v[76:79], v[128:131], v[120:123], v[76:79]
	v_mfma_f32_16x16x32_bf16 v[72:75], v[132:135], v[120:123], v[72:75]
	v_mfma_f32_16x16x32_bf16 v[68:71], v[136:139], v[120:123], v[68:71]
	v_mfma_f32_16x16x32_bf16 v[64:67], v[140:143], v[120:123], v[64:67]
	v_mfma_f32_16x16x32_bf16 v[60:63], v[128:131], v[124:127], v[60:63]
	v_mfma_f32_16x16x32_bf16 v[56:59], v[132:135], v[124:127], v[56:59]
	v_mfma_f32_16x16x32_bf16 v[52:55], v[136:139], v[124:127], v[52:55]
	v_mfma_f32_16x16x32_bf16 v[48:51], v[140:143], v[124:127], v[48:51]
	s_add_i32 s22, s22, 2
	v_lshl_add_u64 v[182:183], v[182:183], 0, s[4:5]
	v_lshl_add_u64 v[184:185], v[184:185], 0, s[4:5]
	s_branch .Lmyf_even
.Lmyf_oddlast:
	v_mfma_f32_16x16x32_bf16 v[108:111], v[160:163], v[144:147], v[108:111]
	v_mfma_f32_16x16x32_bf16 v[104:107], v[164:167], v[144:147], v[104:107]
	v_mfma_f32_16x16x32_bf16 v[100:103], v[224:227], v[144:147], v[100:103]
	v_mfma_f32_16x16x32_bf16 v[96:99], v[228:231], v[144:147], v[96:99]
	v_mfma_f32_16x16x32_bf16 v[92:95], v[160:163], v[148:151], v[92:95]
	v_mfma_f32_16x16x32_bf16 v[88:91], v[164:167], v[148:151], v[88:91]
	v_mfma_f32_16x16x32_bf16 v[84:87], v[224:227], v[148:151], v[84:87]
	v_mfma_f32_16x16x32_bf16 v[80:83], v[228:231], v[148:151], v[80:83]
	v_mfma_f32_16x16x32_bf16 v[76:79], v[160:163], v[152:155], v[76:79]
	v_mfma_f32_16x16x32_bf16 v[72:75], v[164:167], v[152:155], v[72:75]
	v_mfma_f32_16x16x32_bf16 v[68:71], v[224:227], v[152:155], v[68:71]
	v_mfma_f32_16x16x32_bf16 v[64:67], v[228:231], v[152:155], v[64:67]
	v_mfma_f32_16x16x32_bf16 v[60:63], v[160:163], v[156:159], v[60:63]
	v_mfma_f32_16x16x32_bf16 v[56:59], v[164:167], v[156:159], v[56:59]
	v_mfma_f32_16x16x32_bf16 v[52:55], v[224:227], v[156:159], v[52:55]
	v_mfma_f32_16x16x32_bf16 v[48:51], v[228:231], v[156:159], v[48:51]
	s_waitcnt lgkmcnt(0)
	v_mfma_f32_16x16x32_bf16 v[108:111], v[128:131], v[112:115], v[108:111]
	ds_read_b128 v[144:147], v217 offset:32768
	v_mfma_f32_16x16x32_bf16 v[104:107], v[132:135], v[112:115], v[104:107]
	ds_read_b128 v[148:151], v217 offset:34816
	v_mfma_f32_16x16x32_bf16 v[100:103], v[136:139], v[112:115], v[100:103]
	ds_read_b128 v[152:155], v217 offset:36864
	v_mfma_f32_16x16x32_bf16 v[96:99], v[140:143], v[112:115], v[96:99]
	ds_read_b128 v[156:159], v217 offset:38912
	v_mfma_f32_16x16x32_bf16 v[92:95], v[128:131], v[116:119], v[92:95]
	ds_read_b128 v[160:163], v221
	v_mfma_f32_16x16x32_bf16 v[88:91], v[132:135], v[116:119], v[88:91]
	ds_read_b128 v[164:167], v221 offset:2048
	v_mfma_f32_16x16x32_bf16 v[84:87], v[136:139], v[116:119], v[84:87]
	ds_read_b128 v[224:227], v221 offset:4096
	v_mfma_f32_16x16x32_bf16 v[80:83], v[140:143], v[116:119], v[80:83]
	ds_read_b128 v[228:231], v221 offset:6144
	v_mfma_f32_16x16x32_bf16 v[76:79], v[128:131], v[120:123], v[76:79]
	v_mfma_f32_16x16x32_bf16 v[72:75], v[132:135], v[120:123], v[72:75]
	v_mfma_f32_16x16x32_bf16 v[68:71], v[136:139], v[120:123], v[68:71]
	v_mfma_f32_16x16x32_bf16 v[64:67], v[140:143], v[120:123], v[64:67]
	v_mfma_f32_16x16x32_bf16 v[60:63], v[128:131], v[124:127], v[60:63]
	v_mfma_f32_16x16x32_bf16 v[56:59], v[132:135], v[124:127], v[56:59]
	v_mfma_f32_16x16x32_bf16 v[52:55], v[136:139], v[124:127], v[52:55]
	v_mfma_f32_16x16x32_bf16 v[48:51], v[140:143], v[124:127], v[48:51]
	s_add_i32 s22, s22, 2
	v_lshl_add_u64 v[182:183], v[182:183], 0, s[4:5]
	v_lshl_add_u64 v[184:185], v[184:185], 0, s[4:5]
	s_waitcnt lgkmcnt(0)
	v_mfma_f32_16x16x32_bf16 v[108:111], v[160:163], v[144:147], v[108:111]
	v_mfma_f32_16x16x32_bf16 v[104:107], v[164:167], v[144:147], v[104:107]
	v_mfma_f32_16x16x32_bf16 v[100:103], v[224:227], v[144:147], v[100:103]
	v_mfma_f32_16x16x32_bf16 v[96:99], v[228:231], v[144:147], v[96:99]
	v_mfma_f32_16x16x32_bf16 v[92:95], v[160:163], v[148:151], v[92:95]
	v_mfma_f32_16x16x32_bf16 v[88:91], v[164:167], v[148:151], v[88:91]
	v_mfma_f32_16x16x32_bf16 v[84:87], v[224:227], v[148:151], v[84:87]
	v_mfma_f32_16x16x32_bf16 v[80:83], v[228:231], v[148:151], v[80:83]
	v_mfma_f32_16x16x32_bf16 v[76:79], v[160:163], v[152:155], v[76:79]
	v_mfma_f32_16x16x32_bf16 v[72:75], v[164:167], v[152:155], v[72:75]
	v_mfma_f32_16x16x32_bf16 v[68:71], v[224:227], v[152:155], v[68:71]
	v_mfma_f32_16x16x32_bf16 v[64:67], v[228:231], v[152:155], v[64:67]
	v_mfma_f32_16x16x32_bf16 v[60:63], v[160:163], v[156:159], v[60:63]
	v_mfma_f32_16x16x32_bf16 v[56:59], v[164:167], v[156:159], v[56:59]
	v_mfma_f32_16x16x32_bf16 v[52:55], v[224:227], v[156:159], v[52:55]
	v_mfma_f32_16x16x32_bf16 v[48:51], v[228:231], v[156:159], v[48:51]
	s_and_b64 vcc, exec, s[10:11]
	s_nop 7
	s_branch .LBB0_1487

.LBB0_1564:
	s_waitcnt lgkmcnt(0)
	s_barrier
	ds_read_b128 v[112:115], v214
	ds_read_b128 v[116:119], v214 offset:2048
	ds_read_b128 v[120:123], v214 offset:4096
	ds_read_b128 v[124:127], v214 offset:6144
	ds_read_b128 v[128:131], v215
	ds_read_b128 v[132:135], v215 offset:2048
	ds_read_b128 v[136:139], v215 offset:4096
	ds_read_b128 v[140:143], v215 offset:6144
	s_waitcnt vmcnt(6)
	ds_write_b128 v204, v[4:7] offset:32768
	ds_write_b128 v204, v[8:11] offset:40960
	ds_write_b128 v204, v[16:19] offset:49152
	ds_write_b128 v204, v[20:23] offset:57344
	ds_write_b128 v218, v[24:27]
	ds_write_b128 v218, v[32:35] offset:8192
	s_cmp_gt_u32 s19, 60
	s_mov_b64 s[10:11], -1
	s_cbranch_scc0 .Lmygfe__1568
	s_andn2_b64 vcc, exec, s[8:9]
	s_cbranch_vccnz .Lmygfe__1567
	global_load_dwordx4 v[8:11], v[188:189], off
	global_load_dwordx4 v[16:19], v[190:191], off
	global_load_dwordx4 v[4:7], v[184:185], off offset:128
	global_load_dwordx4 v[24:27], v[186:187], off offset:128
	global_load_dwordx4 v[20:23], v[192:193], off
	global_load_dwordx4 v[32:35], v[194:195], off

.Lmygfe__1568:
	s_andn2_b64 vcc, exec, s[10:11]
	s_cbranch_vccnz .Lmygfe__1570
	v_lshl_add_u64 v[16:17], v[182:183], 0, v[170:171]
	v_add_co_u32_e32 v4, vcc, 0x4900000, v16
	v_lshl_add_u64 v[24:25], v[180:181], 0, v[170:171]
	v_addc_co_u32_e32 v5, vcc, 0, v17, vcc
	v_add_co_u32_e32 v8, vcc, 0x4980000, v16
	s_nop 1
	v_addc_co_u32_e32 v9, vcc, 0, v17, vcc
	v_add_co_u32_e32 v18, vcc, 0x4a00000, v16
	global_load_dwordx4 v[4:7], v[4:5], off offset:384
	s_nop 0
	global_load_dwordx4 v[8:11], v[8:9], off offset:384
	v_addc_co_u32_e32 v19, vcc, 0, v17, vcc
	v_add_co_u32_e32 v20, vcc, 0x4a80000, v16
	s_nop 1
	v_addc_co_u32_e32 v21, vcc, 0, v17, vcc
	v_add_co_u32_e32 v26, vcc, 0x2000000, v24
	global_load_dwordx4 v[16:19], v[18:19], off offset:384
	s_nop 0
	global_load_dwordx4 v[20:23], v[20:21], off offset:384
	v_addc_co_u32_e32 v27, vcc, 0, v25, vcc
	v_add_co_u32_e32 v32, vcc, 0x2080000, v24
	s_nop 1
	v_addc_co_u32_e32 v33, vcc, 0, v25, vcc
	global_load_dwordx4 v[24:27], v[26:27], off offset:384
	s_nop 0
	global_load_dwordx4 v[32:35], v[32:33], off offset:384
.Lmygfe__1570:
	s_waitcnt lgkmcnt(0)
	v_mfma_f32_16x16x32_bf16 v[108:111], v[112:115], v[128:131], v[108:111]
	ds_read_b128 v[144:147], v216
	v_mfma_f32_16x16x32_bf16 v[104:107], v[112:115], v[132:135], v[104:107]
	ds_read_b128 v[148:151], v216 offset:2048
	v_mfma_f32_16x16x32_bf16 v[100:103], v[112:115], v[136:139], v[100:103]
	ds_read_b128 v[152:155], v216 offset:4096
	v_mfma_f32_16x16x32_bf16 v[96:99], v[112:115], v[140:143], v[96:99]
	ds_read_b128 v[156:159], v216 offset:6144
	v_mfma_f32_16x16x32_bf16 v[92:95], v[116:119], v[128:131], v[92:95]
	ds_read_b128 v[160:163], v217
	v_mfma_f32_16x16x32_bf16 v[88:91], v[116:119], v[132:135], v[88:91]
	ds_read_b128 v[164:167], v217 offset:2048
	v_mfma_f32_16x16x32_bf16 v[84:87], v[116:119], v[136:139], v[84:87]
	ds_read_b128 v[224:227], v217 offset:4096
	v_mfma_f32_16x16x32_bf16 v[80:83], v[116:119], v[140:143], v[80:83]
	ds_read_b128 v[228:231], v217 offset:6144
	v_mfma_f32_16x16x32_bf16 v[76:79], v[120:123], v[128:131], v[76:79]
	v_mfma_f32_16x16x32_bf16 v[72:75], v[120:123], v[132:135], v[72:75]
	v_mfma_f32_16x16x32_bf16 v[68:71], v[120:123], v[136:139], v[68:71]
	v_mfma_f32_16x16x32_bf16 v[64:67], v[120:123], v[140:143], v[64:67]
	v_mfma_f32_16x16x32_bf16 v[60:63], v[124:127], v[128:131], v[60:63]
	v_mfma_f32_16x16x32_bf16 v[56:59], v[124:127], v[132:135], v[56:59]
	v_mfma_f32_16x16x32_bf16 v[52:55], v[124:127], v[136:139], v[52:55]
	v_mfma_f32_16x16x32_bf16 v[48:51], v[124:127], v[140:143], v[48:51]
	s_branch .Lmyg_odd
.Lmyg_even:
	s_waitcnt lgkmcnt(0)
	s_barrier
	ds_read_b128 v[112:115], v214
	ds_read_b128 v[116:119], v214 offset:2048
	ds_read_b128 v[120:123], v214 offset:4096
	ds_read_b128 v[124:127], v214 offset:6144
	ds_read_b128 v[128:131], v215
	ds_read_b128 v[132:135], v215 offset:2048
	ds_read_b128 v[136:139], v215 offset:4096
	ds_read_b128 v[140:143], v215 offset:6144
	s_cmp_gt_u32 s19, 60
	s_cbranch_scc0 .Lmyg_ew6
	s_and_b64 vcc, exec, s[8:9]
	s_cbranch_vccnz .Lmyg_ew6
	s_waitcnt vmcnt(0)
.Lmyg_ew6:
	s_waitcnt vmcnt(6)
	v_mfma_f32_16x16x32_bf16 v[108:111], v[144:147], v[160:163], v[108:111]
	ds_write_b128 v204, v[4:7] offset:32768
	v_mfma_f32_16x16x32_bf16 v[104:107], v[144:147], v[164:167], v[104:107]
	ds_write_b128 v204, v[8:11] offset:40960
	v_mfma_f32_16x16x32_bf16 v[100:103], v[144:147], v[224:227], v[100:103]
	ds_write_b128 v204, v[16:19] offset:49152
	v_mfma_f32_16x16x32_bf16 v[96:99], v[144:147], v[228:231], v[96:99]
	ds_write_b128 v204, v[20:23] offset:57344
	v_mfma_f32_16x16x32_bf16 v[92:95], v[148:151], v[160:163], v[92:95]
	ds_write_b128 v218, v[24:27]
	v_mfma_f32_16x16x32_bf16 v[88:91], v[148:151], v[164:167], v[88:91]
	ds_write_b128 v218, v[32:35] offset:8192
	v_mfma_f32_16x16x32_bf16 v[84:87], v[148:151], v[224:227], v[84:87]
	v_mfma_f32_16x16x32_bf16 v[80:83], v[148:151], v[228:231], v[80:83]
	s_cmp_gt_u32 s19, 60
	s_mov_b64 s[10:11], -1
	s_cbranch_scc0 .Lmygse__1568
	s_andn2_b64 vcc, exec, s[8:9]
	s_cbranch_vccnz .Lmygse__1567
	global_load_dwordx4 v[8:11], v[188:189], off
	global_load_dwordx4 v[16:19], v[190:191], off
	global_load_dwordx4 v[4:7], v[184:185], off offset:128
	global_load_dwordx4 v[24:27], v[186:187], off offset:128
	global_load_dwordx4 v[20:23], v[192:193], off
	global_load_dwordx4 v[32:35], v[194:195], off

.Lmygse__1570:
	v_mfma_f32_16x16x32_bf16 v[76:79], v[152:155], v[160:163], v[76:79]
	v_mfma_f32_16x16x32_bf16 v[72:75], v[152:155], v[164:167], v[72:75]
	v_mfma_f32_16x16x32_bf16 v[68:71], v[152:155], v[224:227], v[68:71]
	v_mfma_f32_16x16x32_bf16 v[64:67], v[152:155], v[228:231], v[64:67]
	v_mfma_f32_16x16x32_bf16 v[60:63], v[156:159], v[160:163], v[60:63]
	v_mfma_f32_16x16x32_bf16 v[56:59], v[156:159], v[164:167], v[56:59]
	v_mfma_f32_16x16x32_bf16 v[52:55], v[156:159], v[224:227], v[52:55]
	v_mfma_f32_16x16x32_bf16 v[48:51], v[156:159], v[228:231], v[48:51]
	s_waitcnt lgkmcnt(0)
	v_mfma_f32_16x16x32_bf16 v[108:111], v[112:115], v[128:131], v[108:111]
	ds_read_b128 v[144:147], v216
	v_mfma_f32_16x16x32_bf16 v[104:107], v[112:115], v[132:135], v[104:107]
	ds_read_b128 v[148:151], v216 offset:2048
	v_mfma_f32_16x16x32_bf16 v[100:103], v[112:115], v[136:139], v[100:103]
	ds_read_b128 v[152:155], v216 offset:4096
	v_mfma_f32_16x16x32_bf16 v[96:99], v[112:115], v[140:143], v[96:99]
	ds_read_b128 v[156:159], v216 offset:6144
	v_mfma_f32_16x16x32_bf16 v[92:95], v[116:119], v[128:131], v[92:95]
	ds_read_b128 v[160:163], v217
	v_mfma_f32_16x16x32_bf16 v[88:91], v[116:119], v[132:135], v[88:91]
	ds_read_b128 v[164:167], v217 offset:2048
	v_mfma_f32_16x16x32_bf16 v[84:87], v[116:119], v[136:139], v[84:87]
	ds_read_b128 v[224:227], v217 offset:4096
	v_mfma_f32_16x16x32_bf16 v[80:83], v[116:119], v[140:143], v[80:83]
	ds_read_b128 v[228:231], v217 offset:6144
	v_mfma_f32_16x16x32_bf16 v[76:79], v[120:123], v[128:131], v[76:79]
	v_mfma_f32_16x16x32_bf16 v[72:75], v[120:123], v[132:135], v[72:75]
	v_mfma_f32_16x16x32_bf16 v[68:71], v[120:123], v[136:139], v[68:71]
	v_mfma_f32_16x16x32_bf16 v[64:67], v[120:123], v[140:143], v[64:67]
	v_mfma_f32_16x16x32_bf16 v[60:63], v[124:127], v[128:131], v[60:63]
	v_mfma_f32_16x16x32_bf16 v[56:59], v[124:127], v[132:135], v[56:59]
	v_mfma_f32_16x16x32_bf16 v[52:55], v[124:127], v[136:139], v[52:55]
	v_mfma_f32_16x16x32_bf16 v[48:51], v[124:127], v[140:143], v[48:51]
.Lmyg_odd:
	s_waitcnt lgkmcnt(0)
	s_barrier
	ds_read_b128 v[112:115], v214 offset:32768
	ds_read_b128 v[116:119], v214 offset:34816
	ds_read_b128 v[120:123], v214 offset:36864
	ds_read_b128 v[124:127], v214 offset:38912
	ds_read_b128 v[128:131], v219
	ds_read_b128 v[132:135], v219 offset:2048
	ds_read_b128 v[136:139], v219 offset:4096
	ds_read_b128 v[140:143], v219 offset:6144
	s_cmp_gt_u32 s19, 61
	s_cselect_b64 s[10:11], -1, 0
	s_and_b64 vcc, exec, s[10:11]
	s_cbranch_vccnz .Lmyg_oddlast
	s_waitcnt vmcnt(6)
	v_mfma_f32_16x16x32_bf16 v[108:111], v[144:147], v[160:163], v[108:111]
	ds_write_b128 v204, v[0:3]
	v_mfma_f32_16x16x32_bf16 v[104:107], v[144:147], v[164:167], v[104:107]
	ds_write_b128 v204, v[12:15] offset:8192
	v_mfma_f32_16x16x32_bf16 v[100:103], v[144:147], v[224:227], v[100:103]
	ds_write_b128 v204, v[28:31] offset:16384
	v_mfma_f32_16x16x32_bf16 v[96:99], v[144:147], v[228:231], v[96:99]
	ds_write_b128 v204, v[36:39] offset:24576
	v_mfma_f32_16x16x32_bf16 v[92:95], v[148:151], v[160:163], v[92:95]
	ds_write_b128 v205, v[40:43]
	v_mfma_f32_16x16x32_bf16 v[88:91], v[148:151], v[164:167], v[88:91]
	ds_write_b128 v205, v[44:47] offset:8192
	v_mfma_f32_16x16x32_bf16 v[84:87], v[148:151], v[224:227], v[84:87]
	v_mfma_f32_16x16x32_bf16 v[80:83], v[148:151], v[228:231], v[80:83]
	s_cmp_gt_u32 s19, 59
	s_mov_b64 s[12:13], -1
	s_cbranch_scc0 .Lmygso__1575
	s_andn2_b64 vcc, exec, s[8:9]
	s_cbranch_vccnz .Lmygso__1574
	global_load_dwordx4 v[12:15], v[196:197], off
	global_load_dwordx4 v[28:31], v[198:199], off
	global_load_dwordx4 v[0:3], v[184:185], off
	global_load_dwordx4 v[40:43], v[186:187], off
	global_load_dwordx4 v[36:39], v[200:201], off
	global_load_dwordx4 v[44:47], v[202:203], off

.Lmygso__1575:
	s_andn2_b64 vcc, exec, s[12:13]
	s_cbranch_vccnz .Lmyg_ocont
	v_lshl_add_u64 v[28:29], v[182:183], 0, v[170:171]
	v_add_co_u32_e32 v0, vcc, 0x4900000, v28
	v_lshl_add_u64 v[40:41], v[180:181], 0, v[170:171]
	v_addc_co_u32_e32 v1, vcc, 0, v29, vcc
	v_add_co_u32_e32 v12, vcc, 0x4980000, v28
	s_nop 1
	v_addc_co_u32_e32 v13, vcc, 0, v29, vcc
	v_add_co_u32_e32 v30, vcc, 0x4a00000, v28
	global_load_dwordx4 v[0:3], v[0:1], off offset:512
	s_nop 0
	global_load_dwordx4 v[12:15], v[12:13], off offset:512
	v_addc_co_u32_e32 v31, vcc, 0, v29, vcc
	v_add_co_u32_e32 v36, vcc, 0x4a80000, v28
	s_nop 1
	v_addc_co_u32_e32 v37, vcc, 0, v29, vcc
	v_add_co_u32_e32 v42, vcc, 0x2000000, v40
	global_load_dwordx4 v[28:31], v[30:31], off offset:512
	s_nop 0
	global_load_dwordx4 v[36:39], v[36:37], off offset:512
	v_addc_co_u32_e32 v43, vcc, 0, v41, vcc
	v_add_co_u32_e32 v44, vcc, 0x2080000, v40
	s_nop 1
	v_addc_co_u32_e32 v45, vcc, 0, v41, vcc
	global_load_dwordx4 v[40:43], v[42:43], off offset:512
	s_nop 0
	global_load_dwordx4 v[44:47], v[44:45], off offset:512
.Lmyg_ocont:
	v_mfma_f32_16x16x32_bf16 v[76:79], v[152:155], v[160:163], v[76:79]
	v_mfma_f32_16x16x32_bf16 v[72:75], v[152:155], v[164:167], v[72:75]
	v_mfma_f32_16x16x32_bf16 v[68:71], v[152:155], v[224:227], v[68:71]
	v_mfma_f32_16x16x32_bf16 v[64:67], v[152:155], v[228:231], v[64:67]
	v_mfma_f32_16x16x32_bf16 v[60:63], v[156:159], v[160:163], v[60:63]
	v_mfma_f32_16x16x32_bf16 v[56:59], v[156:159], v[164:167], v[56:59]
	v_mfma_f32_16x16x32_bf16 v[52:55], v[156:159], v[224:227], v[52:55]
	v_mfma_f32_16x16x32_bf16 v[48:51], v[156:159], v[228:231], v[48:51]
	s_waitcnt lgkmcnt(0)
	v_mfma_f32_16x16x32_bf16 v[108:111], v[112:115], v[128:131], v[108:111]
	ds_read_b128 v[144:147], v216 offset:32768
	v_mfma_f32_16x16x32_bf16 v[104:107], v[112:115], v[132:135], v[104:107]
	ds_read_b128 v[148:151], v216 offset:34816
	v_mfma_f32_16x16x32_bf16 v[100:103], v[112:115], v[136:139], v[100:103]
	ds_read_b128 v[152:155], v216 offset:36864
	v_mfma_f32_16x16x32_bf16 v[96:99], v[112:115], v[140:143], v[96:99]
	ds_read_b128 v[156:159], v216 offset:38912
	v_mfma_f32_16x16x32_bf16 v[92:95], v[116:119], v[128:131], v[92:95]
	ds_read_b128 v[160:163], v220
	v_mfma_f32_16x16x32_bf16 v[88:91], v[116:119], v[132:135], v[88:91]
	ds_read_b128 v[164:167], v220 offset:2048
	v_mfma_f32_16x16x32_bf16 v[84:87], v[116:119], v[136:139], v[84:87]
	ds_read_b128 v[224:227], v220 offset:4096
	v_mfma_f32_16x16x32_bf16 v[80:83], v[116:119], v[140:143], v[80:83]
	ds_read_b128 v[228:231], v220 offset:6144
	v_mfma_f32_16x16x32_bf16 v[76:79], v[120:123], v[128:131], v[76:79]
	v_mfma_f32_16x16x32_bf16 v[72:75], v[120:123], v[132:135], v[72:75]
	v_mfma_f32_16x16x32_bf16 v[68:71], v[120:123], v[136:139], v[68:71]
	v_mfma_f32_16x16x32_bf16 v[64:67], v[120:123], v[140:143], v[64:67]
	v_mfma_f32_16x16x32_bf16 v[60:63], v[124:127], v[128:131], v[60:63]
	v_mfma_f32_16x16x32_bf16 v[56:59], v[124:127], v[132:135], v[56:59]
	v_mfma_f32_16x16x32_bf16 v[52:55], v[124:127], v[136:139], v[52:55]
	v_mfma_f32_16x16x32_bf16 v[48:51], v[124:127], v[140:143], v[48:51]
	s_add_i32 s19, s19, 2
	v_lshl_add_u64 v[180:181], v[180:181], 0, s[4:5]
	v_lshl_add_u64 v[182:183], v[182:183], 0, s[4:5]
	s_branch .Lmyg_even
.Lmyg_oddlast:
	v_mfma_f32_16x16x32_bf16 v[108:111], v[144:147], v[160:163], v[108:111]
	v_mfma_f32_16x16x32_bf16 v[104:107], v[144:147], v[164:167], v[104:107]
	v_mfma_f32_16x16x32_bf16 v[100:103], v[144:147], v[224:227], v[100:103]
	v_mfma_f32_16x16x32_bf16 v[96:99], v[144:147], v[228:231], v[96:99]
	v_mfma_f32_16x16x32_bf16 v[92:95], v[148:151], v[160:163], v[92:95]
	v_mfma_f32_16x16x32_bf16 v[88:91], v[148:151], v[164:167], v[88:91]
	v_mfma_f32_16x16x32_bf16 v[84:87], v[148:151], v[224:227], v[84:87]
	v_mfma_f32_16x16x32_bf16 v[80:83], v[148:151], v[228:231], v[80:83]
	v_mfma_f32_16x16x32_bf16 v[76:79], v[152:155], v[160:163], v[76:79]
	v_mfma_f32_16x16x32_bf16 v[72:75], v[152:155], v[164:167], v[72:75]
	v_mfma_f32_16x16x32_bf16 v[68:71], v[152:155], v[224:227], v[68:71]
	v_mfma_f32_16x16x32_bf16 v[64:67], v[152:155], v[228:231], v[64:67]
	v_mfma_f32_16x16x32_bf16 v[60:63], v[156:159], v[160:163], v[60:63]
	v_mfma_f32_16x16x32_bf16 v[56:59], v[156:159], v[164:167], v[56:59]
	v_mfma_f32_16x16x32_bf16 v[52:55], v[156:159], v[224:227], v[52:55]
	v_mfma_f32_16x16x32_bf16 v[48:51], v[156:159], v[228:231], v[48:51]
	s_waitcnt lgkmcnt(0)
	v_mfma_f32_16x16x32_bf16 v[108:111], v[112:115], v[128:131], v[108:111]
	ds_read_b128 v[144:147], v216 offset:32768
	v_mfma_f32_16x16x32_bf16 v[104:107], v[112:115], v[132:135], v[104:107]
	ds_read_b128 v[148:151], v216 offset:34816
	v_mfma_f32_16x16x32_bf16 v[100:103], v[112:115], v[136:139], v[100:103]
	ds_read_b128 v[152:155], v216 offset:36864
	v_mfma_f32_16x16x32_bf16 v[96:99], v[112:115], v[140:143], v[96:99]
	ds_read_b128 v[156:159], v216 offset:38912
	v_mfma_f32_16x16x32_bf16 v[92:95], v[116:119], v[128:131], v[92:95]
	ds_read_b128 v[160:163], v220
	v_mfma_f32_16x16x32_bf16 v[88:91], v[116:119], v[132:135], v[88:91]
	ds_read_b128 v[164:167], v220 offset:2048
	v_mfma_f32_16x16x32_bf16 v[84:87], v[116:119], v[136:139], v[84:87]
	ds_read_b128 v[224:227], v220 offset:4096
	v_mfma_f32_16x16x32_bf16 v[80:83], v[116:119], v[140:143], v[80:83]
	ds_read_b128 v[228:231], v220 offset:6144
	v_mfma_f32_16x16x32_bf16 v[76:79], v[120:123], v[128:131], v[76:79]
	v_mfma_f32_16x16x32_bf16 v[72:75], v[120:123], v[132:135], v[72:75]
	v_mfma_f32_16x16x32_bf16 v[68:71], v[120:123], v[136:139], v[68:71]
	v_mfma_f32_16x16x32_bf16 v[64:67], v[120:123], v[140:143], v[64:67]
	v_mfma_f32_16x16x32_bf16 v[60:63], v[124:127], v[128:131], v[60:63]
	v_mfma_f32_16x16x32_bf16 v[56:59], v[124:127], v[132:135], v[56:59]
	v_mfma_f32_16x16x32_bf16 v[52:55], v[124:127], v[136:139], v[52:55]
	v_mfma_f32_16x16x32_bf16 v[48:51], v[124:127], v[140:143], v[48:51]
	s_add_i32 s19, s19, 2
	v_lshl_add_u64 v[180:181], v[180:181], 0, s[4:5]
	v_lshl_add_u64 v[182:183], v[182:183], 0, s[4:5]
	s_waitcnt lgkmcnt(0)
	v_mfma_f32_16x16x32_bf16 v[108:111], v[144:147], v[160:163], v[108:111]
	v_mfma_f32_16x16x32_bf16 v[104:107], v[144:147], v[164:167], v[104:107]
	v_mfma_f32_16x16x32_bf16 v[100:103], v[144:147], v[224:227], v[100:103]
	v_mfma_f32_16x16x32_bf16 v[96:99], v[144:147], v[228:231], v[96:99]
	v_mfma_f32_16x16x32_bf16 v[92:95], v[148:151], v[160:163], v[92:95]
	v_mfma_f32_16x16x32_bf16 v[88:91], v[148:151], v[164:167], v[88:91]
	v_mfma_f32_16x16x32_bf16 v[84:87], v[148:151], v[224:227], v[84:87]
	v_mfma_f32_16x16x32_bf16 v[80:83], v[148:151], v[228:231], v[80:83]
	v_mfma_f32_16x16x32_bf16 v[76:79], v[152:155], v[160:163], v[76:79]
	v_mfma_f32_16x16x32_bf16 v[72:75], v[152:155], v[164:167], v[72:75]
	v_mfma_f32_16x16x32_bf16 v[68:71], v[152:155], v[224:227], v[68:71]
	v_mfma_f32_16x16x32_bf16 v[64:67], v[152:155], v[228:231], v[64:67]
	v_mfma_f32_16x16x32_bf16 v[60:63], v[156:159], v[160:163], v[60:63]
	v_mfma_f32_16x16x32_bf16 v[56:59], v[156:159], v[164:167], v[56:59]
	v_mfma_f32_16x16x32_bf16 v[52:55], v[156:159], v[224:227], v[52:55]
	v_mfma_f32_16x16x32_bf16 v[48:51], v[156:159], v[228:231], v[48:51]
	s_and_b64 vcc, exec, s[10:11]
	s_nop 7
	s_branch .LBB0_1559

	.amdhsa_kernel _Z14fwd_megakernel6Params
		.amdhsa_group_segment_fixed_size 16
		.amdhsa_private_segment_fixed_size 0
		.amdhsa_kernarg_size 488
		.amdhsa_user_sgpr_count 2
		.amdhsa_user_sgpr_dispatch_ptr 0
		.amdhsa_user_sgpr_queue_ptr 0
		.amdhsa_user_sgpr_kernarg_segment_ptr 1
		.amdhsa_user_sgpr_dispatch_id 0
		.amdhsa_user_sgpr_kernarg_preload_length 0
		.amdhsa_user_sgpr_kernarg_preload_offset 0
		.amdhsa_user_sgpr_private_segment_size 0
		.amdhsa_uses_dynamic_stack 0
		.amdhsa_enable_private_segment 0
		.amdhsa_system_sgpr_workgroup_id_x 1
		.amdhsa_system_sgpr_workgroup_id_y 0
		.amdhsa_system_sgpr_workgroup_id_z 0
		.amdhsa_system_sgpr_workgroup_info 0
		.amdhsa_system_vgpr_workitem_id 2
		.amdhsa_next_free_vgpr 256
		.amdhsa_next_free_sgpr 101
		.amdhsa_accum_offset 256
		.amdhsa_reserve_vcc 1
		.amdhsa_float_round_mode_32 0
		.amdhsa_float_round_mode_16_64 0
		.amdhsa_float_denorm_mode_32 3
		.amdhsa_float_denorm_mode_16_64 3
		.amdhsa_dx10_clamp 1
		.amdhsa_ieee_mode 1
		.amdhsa_fp16_overflow 0
		.amdhsa_tg_split 0
		.amdhsa_exception_fp_ieee_invalid_op 0
		.amdhsa_exception_fp_denorm_src 0
		.amdhsa_exception_fp_ieee_div_zero 0
		.amdhsa_exception_fp_ieee_overflow 0
		.amdhsa_exception_fp_ieee_underflow 0
		.amdhsa_exception_fp_ieee_inexact 0
		.amdhsa_exception_int_div_zero 0
	.end_amdhsa_kernel

amdhsa.kernels:
  - .agpr_count:     0
    .args:
      - .offset:         0
        .size:           232
        .value_kind:     by_value
      - .offset:         232
        .size:           4
        .value_kind:     hidden_block_count_x
      - .offset:         236
        .size:           4
        .value_kind:     hidden_block_count_y
      - .offset:         240
        .size:           4
        .value_kind:     hidden_block_count_z
      - .offset:         244
        .size:           2
        .value_kind:     hidden_group_size_x
      - .offset:         246
        .size:           2
        .value_kind:     hidden_group_size_y
      - .offset:         248
        .size:           2
        .value_kind:     hidden_group_size_z
      - .offset:         250
        .size:           2
        .value_kind:     hidden_remainder_x
      - .offset:         252
        .size:           2
        .value_kind:     hidden_remainder_y
      - .offset:         254
        .size:           2
        .value_kind:     hidden_remainder_z
      - .offset:         272
        .size:           8
        .value_kind:     hidden_global_offset_x
      - .offset:         280
        .size:           8
        .value_kind:     hidden_global_offset_y
      - .offset:         288
        .size:           8
        .value_kind:     hidden_global_offset_z
      - .offset:         296
        .size:           2
        .value_kind:     hidden_grid_dims
      - .offset:         320
        .size:           8
        .value_kind:     hidden_multigrid_sync_arg
      - .offset:         352
        .size:           4
        .value_kind:     hidden_dynamic_lds_size
    .group_segment_fixed_size: 16
    .kernarg_segment_align: 8
    .kernarg_segment_size: 488
    .language:       OpenCL C
    .language_version:
      - 2
      - 0
    .max_flat_workgroup_size: 512
    .name:           _Z14fwd_megakernel6Params
    .private_segment_fixed_size: 0
    .sgpr_count:     107
    .sgpr_spill_count: 278
    .symbol:         _Z14fwd_megakernel6Params.kd
    .uniform_work_group_size: 1
    .uses_dynamic_stack: false
    .vgpr_count:     256
    .vgpr_spill_count: 0
    .wavefront_size: 64
